# attention: K/V LDS-DMA prefetch loads spread between the MFMA groups of the current chunk instead of one burst after the barrier
# speedup vs baseline: 1.0000x; 1.0000x over previous
.LBB0_868:
.LBB0_869:
	s_add_i32 s0, 0, 0x23f94
	s_waitcnt vmcnt(0)
	v_mov_b32_e32 v0, s0
	v_mbcnt_lo_u32_b32 v58, -1, 0
	v_mbcnt_hi_u32_b32 v58, -1, v58
	ds_read_b32 v0, v0
	v_lshlrev_b32_e32 v71, 4, v58
	v_and_b32_e32 v59, 15, v58
	s_mov_b32 s1, 0
	v_ashrrev_i32_e32 v70, 4, v58
	s_waitcnt lgkmcnt(0)
	v_readfirstlane_b32 s0, v0
	s_and_b32 s4, s0, 7
	s_mul_i32 s5, s4, 0x1400000
	s_add_u32 s5, s94, s5
	s_addc_u32 s6, s95, 0
	s_lshl_b32 s4, s4, 22
	s_sub_u32 s4, 0, s4
	s_subb_u32 s7, 0, 0
	s_add_u32 s4, s5, s4
	s_addc_u32 s5, s6, s7
	s_lshl_b32 s8, s88, 10
	v_add_u32_e32 v0, s8, v71
	v_ashrrev_i32_e32 v1, 31, v0
	v_lshrrev_b32_e32 v1, 22, v1
	v_add_u32_e32 v1, v0, v1
	v_ashrrev_i32_e32 v1, 10, v1
	v_mul_i32_i24_e32 v2, 0x400, v1
	v_sub_u32_e32 v2, v0, v2
	v_lshrrev_b32_e32 v3, 4, v2
	v_bitop3_b32 v2, v3, v2, 32 bitop3:0x6c
	v_ashrrev_i32_e32 v4, 31, v2
	v_lshrrev_b32_e32 v4, 26, v4
	v_lshlrev_b32_e32 v3, 3, v1
	v_add_u32_e32 v4, v2, v4
	v_and_b32_e32 v3, -16, v3
	v_ashrrev_i32_e32 v5, 6, v4
	v_add_u32_e32 v104, v5, v3
	v_and_b32_e32 v3, 0xc0, v4
	v_lshlrev_b32_e32 v1, 5, v1
	v_sub_u32_e32 v2, v2, v3
	v_mov_b32_e32 v3, 1
	v_and_b32_e32 v1, 32, v1
	v_ashrrev_i16_sdwa v2, v3, sext(v2) dst_sel:DWORD dst_unused:UNUSED_PAD src0_sel:DWORD src1_sel:BYTE_0
	v_add_u32_sdwa v1, v1, sext(v2) dst_sel:DWORD dst_unused:UNUSED_PAD src0_sel:DWORD src1_sel:WORD_0
	v_lshlrev_b32_e32 v2, 10, v104
	v_add_u32_e32 v0, 0x2000, v0
	v_lshl_add_u32 v62, v1, 1, v2
	v_ashrrev_i32_e32 v1, 31, v0
	v_lshrrev_b32_e32 v1, 22, v1
	v_add_u32_e32 v1, v0, v1
	v_ashrrev_i32_e32 v1, 10, v1
	v_mul_i32_i24_e32 v2, 0x400, v1
	v_sub_u32_e32 v0, v0, v2
	v_lshrrev_b32_e32 v2, 4, v0
	s_lshl_b32 s6, s0, 3
	v_bitop3_b32 v0, v2, v0, 32 bitop3:0x6c
	s_and_b32 s6, s6, 56
	s_ashr_i32 s7, s0, 5
	v_ashrrev_i32_e32 v4, 31, v0
	s_add_i32 s9, s6, s7
	v_lshrrev_b32_e32 v4, 26, v4
	s_ashr_i32 s12, s9, 5
	v_lshlrev_b32_e32 v2, 3, v1
	v_add_u32_e32 v4, v0, v4
	s_bfe_u32 s0, s0, 0x20003
	s_lshl_b32 s6, s12, 2
	v_and_b32_e32 v2, -16, v2
	v_ashrrev_i32_e32 v5, 6, v4
	s_or_b32 s6, s6, s0
	v_add_u32_e32 v108, v5, v2
	v_and_b32_e32 v2, 0xffc0, v4
	s_ashr_i32 s7, s6, 31
	v_sub_u32_e32 v0, v0, v2
	s_lshl_b64 s[6:7], s[6:7], 18
	v_lshrrev_b16_e32 v2, 7, v0
	s_add_u32 s10, s94, s6
	v_and_b32_e32 v2, 1, v2
	s_addc_u32 s11, s95, s7
	v_lshlrev_b32_e32 v1, 5, v1
	v_add_u16_e32 v0, v0, v2
	s_add_u32 s6, s10, 0x11400000
	v_and_b32_e32 v1, 32, v1
	v_ashrrev_i16_sdwa v0, v3, sext(v0) dst_sel:DWORD dst_unused:UNUSED_PAD src0_sel:DWORD src1_sel:BYTE_0
	s_addc_u32 s7, s11, 0
	s_lshl_b32 s9, s9, 7
	v_add_u32_sdwa v0, v1, sext(v0) dst_sel:DWORD dst_unused:UNUSED_PAD src0_sel:DWORD src1_sel:WORD_0
	v_lshlrev_b32_e32 v1, 10, v108
	s_lshl_b32 s12, s12, 12
	s_and_b32 s9, s9, 0xf80
	v_lshl_add_u32 v64, v0, 1, v1
	v_lshl_or_b32 v1, s88, 4, v59
	s_or_b32 s9, s12, s9
	v_add_u32_e32 v2, s9, v1
	v_ashrrev_i32_e32 v3, 31, v2
	v_lshlrev_b64 v[2:3], 12, v[2:3]
	s_lshl_b32 s0, s0, 10
	v_lshl_add_u64 v[2:3], s[4:5], 0, v[2:3]
	v_lshlrev_b32_e32 v0, 3, v70
	v_lshl_add_u64 v[2:3], v[2:3], 0, s[0:1]
	s_mov_b64 s[0:1], 0x13000000
	v_ashrrev_i32_e32 v1, 31, v0
	v_lshl_add_u64 v[60:61], v[2:3], 0, s[0:1]
	v_lshl_add_u64 v[0:1], v[0:1], 1, v[60:61]
	s_mov_b64 s[0:1], 0xc00000
	v_lshl_add_u64 v[2:3], v[0:1], 0, s[0:1]
	s_mov_b32 s0, 0xc00000
	v_add_co_u32_e32 v0, vcc, s0, v0
	s_add_i32 s22, s8, 0
	s_nop 0
	v_addc_co_u32_e32 v1, vcc, 0, v1, vcc
	v_mov_b32_e32 v63, 0
	s_mov_b32 m0, s22
	s_add_i32 s21, s22, 0x2000
	global_load_dwordx4 v[72:75], v[2:3], off offset:64
	global_load_dwordx4 v[52:55], v[2:3], off offset:128
	global_load_dwordx4 v[48:51], v[2:3], off offset:192
	global_load_dwordx4 v[44:47], v[2:3], off offset:256
	global_load_dwordx4 v[40:43], v[2:3], off offset:320
	global_load_dwordx4 v[36:39], v[2:3], off offset:384
	global_load_dwordx4 v[32:35], v[2:3], off offset:448
	global_load_dwordx4 v[28:31], v[2:3], off offset:512
	global_load_dwordx4 v[24:27], v[2:3], off offset:576
	global_load_dwordx4 v[20:23], v[2:3], off offset:640
	global_load_dwordx4 v[16:19], v[2:3], off offset:704
	global_load_dwordx4 v[12:15], v[2:3], off offset:768
	global_load_dwordx4 v[8:11], v[2:3], off offset:832
	global_load_dwordx4 v[4:7], v[2:3], off offset:896
	global_load_dwordx4 v[76:79], v[0:1], off
	s_nop 0
	global_load_dwordx4 v[0:3], v[2:3], off offset:960
	v_mov_b32_e32 v65, v63
	global_load_lds_dwordx4 v62, s[6:7]
	v_mov_b32_e32 v240, v62
	s_mov_b32 m0, s21
	v_lshl_add_u64 v[66:67], s[6:7], 0, v[62:63]
	v_lshl_add_u64 v[68:69], s[6:7], 0, v[64:65]
	global_load_lds_dwordx4 v64, s[6:7]
	s_add_i32 s20, s22, 0x4000
	s_mov_b64 s[6:7], 0x80
	s_add_i32 s23, s22, 0x6000
	v_lshl_add_u64 v[56:57], v[66:67], 0, s[6:7]
	s_mov_b32 m0, s20
	s_add_u32 s0, s10, 0x11420000
	global_load_lds_dwordx4 v[56:57], off
	v_lshl_add_u64 v[56:57], v[68:69], 0, s[6:7]
	s_mov_b32 m0, s23
	s_addc_u32 s1, s11, 0
	s_add_i32 s24, s22, 0x8000
	global_load_lds_dwordx4 v[56:57], off
	s_mov_b32 m0, s24
	s_add_i32 s25, s22, 0xa000
	global_load_lds_dwordx4 v62, s[0:1]
	s_mov_b32 m0, s25
	s_mov_b64 s[4:5], 0x180
	global_load_lds_dwordx4 v64, s[0:1]
	s_add_u32 s0, s10, 0x11420080
	s_addc_u32 s1, s11, 0
	s_add_i32 s26, s22, 0xc000
	s_mov_b32 m0, s26
	s_add_i32 s27, s22, 0xe000
	global_load_lds_dwordx4 v62, s[0:1]
	s_mov_b32 m0, s27
	s_add_u32 s8, s10, 0x11c00000
	global_load_lds_dwordx4 v64, s[0:1]
	s_addc_u32 s9, s11, 0
	s_add_i32 s19, s22, 0x10000
	s_mov_b64 s[0:1], 0x100
	v_lshl_add_u64 v[56:57], v[66:67], 0, s[0:1]
	s_mov_b32 m0, s19
	s_add_i32 s13, s22, 0x12000
	s_waitcnt vmcnt(0)
	s_waitcnt vmcnt(0) lgkmcnt(0)
	s_barrier
	global_load_lds_dwordx4 v[56:57], off
	v_lshl_add_u64 v[56:57], v[68:69], 0, s[0:1]
	s_mov_b32 m0, s13
	s_add_i32 s12, s22, 0x14000
	s_add_i32 s14, s22, 0x16000
	global_load_lds_dwordx4 v[56:57], off
	v_lshl_add_u64 v[56:57], v[66:67], 0, s[4:5]
	s_mov_b32 m0, s12
	s_add_u32 s28, s10, 0x11420100
	global_load_lds_dwordx4 v[56:57], off
	v_lshl_add_u64 v[56:57], v[68:69], 0, s[4:5]
	s_mov_b32 m0, s14
	s_addc_u32 s29, s11, 0
	s_add_i32 s15, s22, 0x18000
	global_load_lds_dwordx4 v[56:57], off
	s_mov_b32 m0, s15
	s_add_i32 s16, s22, 0x1a000
	global_load_lds_dwordx4 v62, s[28:29]
	s_mov_b32 m0, s16
	v_and_b32_e32 v57, 48, v58
	global_load_lds_dwordx4 v64, s[28:29]
	s_add_u32 s28, s10, 0x11420180
	s_addc_u32 s29, s11, 0
	s_add_i32 s17, s22, 0x1c000
	s_mov_b32 m0, s17
	s_add_i32 s18, s22, 0x1e000
	global_load_lds_dwordx4 v62, s[28:29]
	s_mov_b32 m0, s18
	v_lshlrev_b32_e32 v58, 2, v58
	global_load_lds_dwordx4 v64, s[28:29]
	v_lshlrev_b32_e32 v56, 6, v59
	v_and_b32_e32 v58, 32, v58
	v_bitop3_b32 v56, v56, v58, v57 bitop3:0x36
	v_and_b32_e32 v57, 0xfffffc00, v71
	v_add3_u32 v65, 0, v56, v57
	v_mov_b32_e32 v71, v65
	ds_read_b128 v[56:59], v71
	ds_read_b128 v[80:83], v71 offset:2048
	s_waitcnt lgkmcnt(0)
	v_mfma_f32_16x16x32_bf16 v[84:87], v[56:59], v[76:79], 0
	ds_read_b128 v[56:59], v71 offset:4096
	ds_read_b128 v[88:91], v71 offset:6144
	ds_read_b128 v[96:99], v71 offset:8192
	ds_read_b128 v[100:103], v71 offset:10240
	s_waitcnt lgkmcnt(0)
	v_mfma_f32_16x16x32_bf16 v[92:95], v[56:59], v[76:79], 0
	v_lshlrev_b32_e32 v56, 9, v104
	ds_read_b128 v[104:107], v71 offset:12288
	v_lshlrev_b32_e32 v57, 9, v108
	ds_read_b128 v[108:111], v71 offset:14336
	ds_read_b128 v[112:115], v71 offset:32768
	ds_read_b128 v[116:119], v71 offset:34816
	ds_read_b128 v[120:123], v71 offset:36864
	ds_read_b128 v[124:127], v71 offset:38912
	ds_read_b128 v[128:131], v71 offset:40960
	ds_read_b128 v[132:135], v71 offset:43008
	ds_read_b128 v[136:139], v71 offset:45056
	ds_read_b128 v[140:143], v71 offset:47104
	v_mfma_f32_16x16x32_bf16 v[80:83], v[80:83], v[76:79], 0
	v_sub_u32_e32 v56, v62, v56
	v_mov_b32_e32 v241, v56
	v_sub_u32_e32 v58, v64, v57
	v_mfma_f32_16x16x32_bf16 v[88:91], v[88:91], v[76:79], 0
	v_mfma_f32_16x16x32_bf16 v[96:99], v[96:99], v[76:79], 0
	v_mfma_f32_16x16x32_bf16 v[100:103], v[100:103], v[76:79], 0
	s_waitcnt lgkmcnt(0)
	v_mfma_f32_16x16x32_bf16 v[104:107], v[104:107], v[76:79], 0
	v_mfma_f32_16x16x32_bf16 v[108:111], v[108:111], v[76:79], 0
	ds_read_b128 v[144:147], v71 offset:15360
	ds_read_b128 v[148:151], v71 offset:13312
	ds_read_b128 v[152:155], v71 offset:11264
	ds_read_b128 v[156:159], v71 offset:9216
	ds_read_b128 v[160:163], v71 offset:7168
	ds_read_b128 v[164:167], v71 offset:5120
	ds_read_b128 v[168:171], v71 offset:3072
	ds_read_b128 v[172:175], v71 offset:1024
	v_mfma_f32_16x16x32_bf16 v[112:115], v[112:115], v[76:79], 0
	v_mfma_f32_16x16x32_bf16 v[116:119], v[116:119], v[76:79], 0
	v_mfma_f32_16x16x32_bf16 v[120:123], v[120:123], v[76:79], 0
	v_mfma_f32_16x16x32_bf16 v[124:127], v[124:127], v[76:79], 0
	v_mfma_f32_16x16x32_bf16 v[128:131], v[128:131], v[76:79], 0
	v_mfma_f32_16x16x32_bf16 v[132:135], v[132:135], v[76:79], 0
	v_mfma_f32_16x16x32_bf16 v[136:139], v[136:139], v[76:79], 0
	v_mfma_f32_16x16x32_bf16 v[76:79], v[140:143], v[76:79], 0
	s_waitcnt lgkmcnt(0)
	v_mfma_f32_16x16x32_bf16 v[84:87], v[172:175], v[72:75], v[84:87]
	v_mfma_f32_16x16x32_bf16 v[80:83], v[168:171], v[72:75], v[80:83]
	v_mfma_f32_16x16x32_bf16 v[92:95], v[164:167], v[72:75], v[92:95]
	v_mfma_f32_16x16x32_bf16 v[88:91], v[160:163], v[72:75], v[88:91]
	v_mfma_f32_16x16x32_bf16 v[96:99], v[156:159], v[72:75], v[96:99]
	v_mfma_f32_16x16x32_bf16 v[100:103], v[152:155], v[72:75], v[100:103]
	ds_read_b128 v[140:143], v71 offset:33792
	ds_read_b128 v[152:155], v71 offset:35840
	ds_read_b128 v[156:159], v71 offset:37888
	ds_read_b128 v[160:163], v71 offset:39936
	v_mfma_f32_16x16x32_bf16 v[104:107], v[148:151], v[72:75], v[104:107]
	ds_read_b128 v[148:151], v71 offset:41984
	ds_read_b128 v[164:167], v71 offset:44032
	ds_read_b128 v[168:171], v71 offset:46080
	ds_read_b128 v[172:175], v71 offset:48128
	v_mfma_f32_16x16x32_bf16 v[108:111], v[144:147], v[72:75], v[108:111]
	s_waitcnt lgkmcnt(0)
	v_mfma_f32_16x16x32_bf16 v[112:115], v[140:143], v[72:75], v[112:115]
	v_mfma_f32_16x16x32_bf16 v[116:119], v[152:155], v[72:75], v[116:119]
	v_mfma_f32_16x16x32_bf16 v[120:123], v[156:159], v[72:75], v[120:123]
	v_mfma_f32_16x16x32_bf16 v[124:127], v[160:163], v[72:75], v[124:127]
	v_mfma_f32_16x16x32_bf16 v[128:131], v[148:151], v[72:75], v[128:131]
	ds_read_b128 v[140:143], v71 offset:30720
	ds_read_b128 v[144:147], v71 offset:28672
	ds_read_b128 v[148:151], v71 offset:26624
	ds_read_b128 v[152:155], v71 offset:24576
	v_mfma_f32_16x16x32_bf16 v[132:135], v[164:167], v[72:75], v[132:135]
	v_mfma_f32_16x16x32_bf16 v[136:139], v[168:171], v[72:75], v[136:139]
	ds_read_b128 v[156:159], v71 offset:22528
	ds_read_b128 v[160:163], v71 offset:20480
	ds_read_b128 v[164:167], v71 offset:18432
	ds_read_b128 v[168:171], v71 offset:16384
	v_mfma_f32_16x16x32_bf16 v[72:75], v[172:175], v[72:75], v[76:79]
	s_waitcnt lgkmcnt(0)
	v_mfma_f32_16x16x32_bf16 v[76:79], v[168:171], v[52:55], v[84:87]
	v_mfma_f32_16x16x32_bf16 v[80:83], v[164:167], v[52:55], v[80:83]
	v_mfma_f32_16x16x32_bf16 v[84:87], v[160:163], v[52:55], v[92:95]
	v_mfma_f32_16x16x32_bf16 v[88:91], v[156:159], v[52:55], v[88:91]
	v_mfma_f32_16x16x32_bf16 v[92:95], v[152:155], v[52:55], v[96:99]
	v_mfma_f32_16x16x32_bf16 v[96:99], v[148:151], v[52:55], v[100:103]
	s_nop 2
	ds_read_b128 v[100:103], v71 offset:49152
	ds_read_b128 v[148:151], v71 offset:51200
	ds_read_b128 v[152:155], v71 offset:53248
	ds_read_b128 v[156:159], v71 offset:55296
	v_mfma_f32_16x16x32_bf16 v[104:107], v[144:147], v[52:55], v[104:107]
	ds_read_b128 v[144:147], v71 offset:57344
	ds_read_b128 v[160:163], v71 offset:59392
	ds_read_b128 v[164:167], v71 offset:61440
	ds_read_b128 v[168:171], v71 offset:63488
	v_mfma_f32_16x16x32_bf16 v[108:111], v[140:143], v[52:55], v[108:111]
	s_waitcnt lgkmcnt(0)
	v_mfma_f32_16x16x32_bf16 v[100:103], v[100:103], v[52:55], v[112:115]
	v_mfma_f32_16x16x32_bf16 v[112:115], v[148:151], v[52:55], v[116:119]
	v_mfma_f32_16x16x32_bf16 v[116:119], v[152:155], v[52:55], v[120:123]
	v_mfma_f32_16x16x32_bf16 v[120:123], v[156:159], v[52:55], v[124:127]
	v_mfma_f32_16x16x32_bf16 v[124:127], v[144:147], v[52:55], v[128:131]
	v_mfma_f32_16x16x32_bf16 v[128:131], v[160:163], v[52:55], v[132:135]
	s_nop 2
	ds_read_b128 v[132:135], v71 offset:31744
	ds_read_b128 v[140:143], v71 offset:29696
	ds_read_b128 v[144:147], v71 offset:27648
	ds_read_b128 v[148:151], v71 offset:25600
	v_mfma_f32_16x16x32_bf16 v[136:139], v[164:167], v[52:55], v[136:139]
	ds_read_b128 v[152:155], v71 offset:23552
	ds_read_b128 v[156:159], v71 offset:21504
	ds_read_b128 v[160:163], v71 offset:19456
	ds_read_b128 v[164:167], v71 offset:17408
	v_mfma_f32_16x16x32_bf16 v[52:55], v[168:171], v[52:55], v[72:75]
	s_waitcnt lgkmcnt(0)
	v_mfma_f32_16x16x32_bf16 v[72:75], v[164:167], v[48:51], v[76:79]
	v_mfma_f32_16x16x32_bf16 v[76:79], v[160:163], v[48:51], v[80:83]
	v_mfma_f32_16x16x32_bf16 v[80:83], v[156:159], v[48:51], v[84:87]
	v_mfma_f32_16x16x32_bf16 v[84:87], v[152:155], v[48:51], v[88:91]
	v_mfma_f32_16x16x32_bf16 v[88:91], v[148:151], v[48:51], v[92:95]
	v_mfma_f32_16x16x32_bf16 v[92:95], v[144:147], v[48:51], v[96:99]
	s_nop 2
	ds_read_b128 v[96:99], v71 offset:50176
	ds_read_b128 v[144:147], v71 offset:52224
	ds_read_b128 v[148:151], v71 offset:54272
	ds_read_b128 v[152:155], v71 offset:56320
	v_mfma_f32_16x16x32_bf16 v[104:107], v[140:143], v[48:51], v[104:107]
	ds_read_b128 v[140:143], v71 offset:58368
	ds_read_b128 v[156:159], v71 offset:60416
	ds_read_b128 v[160:163], v71 offset:62464
	ds_read_b128 v[164:167], v71 offset:64512
	v_mfma_f32_16x16x32_bf16 v[108:111], v[132:135], v[48:51], v[108:111]
	s_waitcnt lgkmcnt(0)
	v_mfma_f32_16x16x32_bf16 v[96:99], v[96:99], v[48:51], v[100:103]
	v_mfma_f32_16x16x32_bf16 v[100:103], v[144:147], v[48:51], v[112:115]
	v_mfma_f32_16x16x32_bf16 v[112:115], v[148:151], v[48:51], v[116:119]
	v_mfma_f32_16x16x32_bf16 v[116:119], v[152:155], v[48:51], v[120:123]
	v_mfma_f32_16x16x32_bf16 v[120:123], v[140:143], v[48:51], v[124:127]
	v_mfma_f32_16x16x32_bf16 v[124:127], v[156:159], v[48:51], v[128:131]
	v_mfma_f32_16x16x32_bf16 v[128:131], v[160:163], v[48:51], v[136:139]
	v_mfma_f32_16x16x32_bf16 v[50:53], v[164:167], v[48:51], v[52:55]
	s_waitcnt vmcnt(0)
	s_waitcnt vmcnt(0)
	s_barrier
	v_add_u32_e32 v48, 0x10000, v65
	v_mov_b32_e32 v49, v48
	ds_read_b128 v[132:135], v49
	ds_read_b128 v[136:139], v49 offset:2048
	s_waitcnt lgkmcnt(0)
	v_mfma_f32_16x16x32_bf16 v[72:75], v[132:135], v[44:47], v[72:75]
	ds_read_b128 v[132:135], v49 offset:4096
	v_mfma_f32_16x16x32_bf16 v[76:79], v[136:139], v[44:47], v[76:79]
	ds_read_b128 v[136:139], v49 offset:6144
	s_waitcnt lgkmcnt(0)
	v_mfma_f32_16x16x32_bf16 v[80:83], v[132:135], v[44:47], v[80:83]
	ds_read_b128 v[132:135], v49 offset:8192
	v_mfma_f32_16x16x32_bf16 v[84:87], v[136:139], v[44:47], v[84:87]
	ds_read_b128 v[136:139], v49 offset:10240
	s_waitcnt lgkmcnt(0)
	v_mfma_f32_16x16x32_bf16 v[88:91], v[132:135], v[44:47], v[88:91]
	ds_read_b128 v[132:135], v49 offset:12288
	ds_read_b128 v[140:143], v49 offset:14336
	v_mfma_f32_16x16x32_bf16 v[92:95], v[136:139], v[44:47], v[92:95]
	ds_read_b128 v[136:139], v49 offset:32768
	ds_read_b128 v[144:147], v49 offset:34816
	ds_read_b128 v[148:151], v49 offset:36864
	ds_read_b128 v[152:155], v49 offset:38912
	s_waitcnt lgkmcnt(0)
	v_mfma_f32_16x16x32_bf16 v[104:107], v[132:135], v[44:47], v[104:107]
	ds_read_b128 v[132:135], v49 offset:40960
	ds_read_b128 v[156:159], v49 offset:43008
	ds_read_b128 v[160:163], v49 offset:45056
	ds_read_b128 v[164:167], v49 offset:47104
	v_mfma_f32_16x16x32_bf16 v[108:111], v[140:143], v[44:47], v[108:111]
	s_add_u32 s100, s10, 0x11400200
	s_addc_u32 s101, s11, 0
	s_mov_b32 m0, s22
	s_nop 0
	global_load_lds_dwordx4 v240, s[100:101]
	v_mfma_f32_16x16x32_bf16 v[96:99], v[136:139], v[44:47], v[96:99]
	v_mfma_f32_16x16x32_bf16 v[100:103], v[144:147], v[44:47], v[100:103]
	v_mfma_f32_16x16x32_bf16 v[112:115], v[148:151], v[44:47], v[112:115]
	v_mfma_f32_16x16x32_bf16 v[116:119], v[152:155], v[44:47], v[116:119]
	s_waitcnt lgkmcnt(0)
	v_mfma_f32_16x16x32_bf16 v[120:123], v[132:135], v[44:47], v[120:123]
	ds_read_b128 v[132:135], v49 offset:15360
	ds_read_b128 v[136:139], v49 offset:13312
	ds_read_b128 v[140:143], v49 offset:11264
	ds_read_b128 v[144:147], v49 offset:9216
	v_mfma_f32_16x16x32_bf16 v[124:127], v[156:159], v[44:47], v[124:127]
	v_mfma_f32_16x16x32_bf16 v[128:131], v[160:163], v[44:47], v[128:131]
	ds_read_b128 v[148:151], v49 offset:7168
	ds_read_b128 v[152:155], v49 offset:5120
	ds_read_b128 v[156:159], v49 offset:3072
	ds_read_b128 v[160:163], v49 offset:1024
	v_mfma_f32_16x16x32_bf16 v[44:47], v[164:167], v[44:47], v[50:53]
	s_add_u32 s100, s10, 0x11410200
	s_addc_u32 s101, s11, 0
	s_mov_b32 m0, s21
	s_nop 0
	global_load_lds_dwordx4 v240, s[100:101]
	s_waitcnt lgkmcnt(0)
	v_mfma_f32_16x16x32_bf16 v[50:53], v[160:163], v[40:43], v[72:75]
	v_mfma_f32_16x16x32_bf16 v[72:75], v[156:159], v[40:43], v[76:79]
	v_mfma_f32_16x16x32_bf16 v[76:79], v[152:155], v[40:43], v[80:83]
	v_mfma_f32_16x16x32_bf16 v[80:83], v[148:151], v[40:43], v[84:87]
	v_mfma_f32_16x16x32_bf16 v[84:87], v[144:147], v[40:43], v[88:91]
	v_mfma_f32_16x16x32_bf16 v[88:91], v[140:143], v[40:43], v[92:95]
	s_nop 2
	ds_read_b128 v[92:95], v49 offset:33792
	ds_read_b128 v[140:143], v49 offset:35840
	ds_read_b128 v[144:147], v49 offset:37888
	ds_read_b128 v[148:151], v49 offset:39936
	v_mfma_f32_16x16x32_bf16 v[104:107], v[136:139], v[40:43], v[104:107]
	ds_read_b128 v[136:139], v49 offset:41984
	ds_read_b128 v[152:155], v49 offset:44032
	ds_read_b128 v[156:159], v49 offset:46080
	ds_read_b128 v[160:163], v49 offset:48128
	v_mfma_f32_16x16x32_bf16 v[108:111], v[132:135], v[40:43], v[108:111]
	s_add_u32 s100, s10, 0x11400280
	s_addc_u32 s101, s11, 0
	s_mov_b32 m0, s20
	s_nop 0
	global_load_lds_dwordx4 v240, s[100:101]
	s_waitcnt lgkmcnt(0)
	v_mfma_f32_16x16x32_bf16 v[92:95], v[92:95], v[40:43], v[96:99]
	v_mfma_f32_16x16x32_bf16 v[96:99], v[140:143], v[40:43], v[100:103]
	v_mfma_f32_16x16x32_bf16 v[100:103], v[144:147], v[40:43], v[112:115]
	v_mfma_f32_16x16x32_bf16 v[112:115], v[148:151], v[40:43], v[116:119]
	v_mfma_f32_16x16x32_bf16 v[116:119], v[136:139], v[40:43], v[120:123]
	v_mfma_f32_16x16x32_bf16 v[120:123], v[152:155], v[40:43], v[124:127]
	s_nop 2
	ds_read_b128 v[124:127], v49 offset:30720
	ds_read_b128 v[132:135], v49 offset:28672
	ds_read_b128 v[136:139], v49 offset:26624
	ds_read_b128 v[140:143], v49 offset:24576
	v_mfma_f32_16x16x32_bf16 v[128:131], v[156:159], v[40:43], v[128:131]
	ds_read_b128 v[144:147], v49 offset:22528
	ds_read_b128 v[148:151], v49 offset:20480
	ds_read_b128 v[152:155], v49 offset:18432
	ds_read_b128 v[156:159], v49 offset:16384
	v_mfma_f32_16x16x32_bf16 v[40:43], v[160:163], v[40:43], v[44:47]
	s_add_u32 s100, s10, 0x11410280
	s_addc_u32 s101, s11, 0
	s_mov_b32 m0, s23
	s_nop 0
	global_load_lds_dwordx4 v240, s[100:101]
	s_waitcnt lgkmcnt(0)
	v_mfma_f32_16x16x32_bf16 v[44:47], v[156:159], v[36:39], v[50:53]
	v_mfma_f32_16x16x32_bf16 v[50:53], v[152:155], v[36:39], v[72:75]
	v_mfma_f32_16x16x32_bf16 v[72:75], v[148:151], v[36:39], v[76:79]
	v_mfma_f32_16x16x32_bf16 v[76:79], v[144:147], v[36:39], v[80:83]
	v_mfma_f32_16x16x32_bf16 v[80:83], v[140:143], v[36:39], v[84:87]
	v_mfma_f32_16x16x32_bf16 v[84:87], v[136:139], v[36:39], v[88:91]
	s_nop 2
	ds_read_b128 v[88:91], v49 offset:49152
	ds_read_b128 v[136:139], v49 offset:51200
	ds_read_b128 v[140:143], v49 offset:53248
	ds_read_b128 v[144:147], v49 offset:55296
	v_mfma_f32_16x16x32_bf16 v[104:107], v[132:135], v[36:39], v[104:107]
	ds_read_b128 v[132:135], v49 offset:57344
	ds_read_b128 v[148:151], v49 offset:59392
	ds_read_b128 v[152:155], v49 offset:61440
	ds_read_b128 v[156:159], v49 offset:63488
	v_mfma_f32_16x16x32_bf16 v[108:111], v[124:127], v[36:39], v[108:111]
	s_add_u32 s100, s10, 0x11420200
	s_addc_u32 s101, s11, 0
	s_mov_b32 m0, s24
	s_nop 0
	global_load_lds_dwordx4 v240, s[100:101]
	s_waitcnt lgkmcnt(0)
	v_mfma_f32_16x16x32_bf16 v[88:91], v[88:91], v[36:39], v[92:95]
	v_mfma_f32_16x16x32_bf16 v[92:95], v[136:139], v[36:39], v[96:99]
	v_mfma_f32_16x16x32_bf16 v[96:99], v[140:143], v[36:39], v[100:103]
	v_mfma_f32_16x16x32_bf16 v[100:103], v[144:147], v[36:39], v[112:115]
	v_mfma_f32_16x16x32_bf16 v[112:115], v[132:135], v[36:39], v[116:119]
	v_mfma_f32_16x16x32_bf16 v[116:119], v[148:151], v[36:39], v[120:123]
	s_nop 2
	ds_read_b128 v[120:123], v49 offset:31744
	ds_read_b128 v[124:127], v49 offset:29696
	ds_read_b128 v[132:135], v49 offset:27648
	ds_read_b128 v[136:139], v49 offset:25600
	v_mfma_f32_16x16x32_bf16 v[128:131], v[152:155], v[36:39], v[128:131]
	ds_read_b128 v[140:143], v49 offset:23552
	ds_read_b128 v[144:147], v49 offset:21504
	ds_read_b128 v[148:151], v49 offset:19456
	ds_read_b128 v[152:155], v49 offset:17408
	v_mfma_f32_16x16x32_bf16 v[36:39], v[156:159], v[36:39], v[40:43]
	s_add_u32 s100, s10, 0x11430200
	s_addc_u32 s101, s11, 0
	s_mov_b32 m0, s25
	s_nop 0
	global_load_lds_dwordx4 v240, s[100:101]
	s_waitcnt lgkmcnt(0)
	v_mfma_f32_16x16x32_bf16 v[40:43], v[152:155], v[32:35], v[44:47]
	v_mfma_f32_16x16x32_bf16 v[44:47], v[148:151], v[32:35], v[50:53]
	v_mfma_f32_16x16x32_bf16 v[50:53], v[144:147], v[32:35], v[72:75]
	v_mfma_f32_16x16x32_bf16 v[72:75], v[140:143], v[32:35], v[76:79]
	v_mfma_f32_16x16x32_bf16 v[76:79], v[136:139], v[32:35], v[80:83]
	v_mfma_f32_16x16x32_bf16 v[80:83], v[132:135], v[32:35], v[84:87]
	s_nop 2
	ds_read_b128 v[84:87], v49 offset:50176
	ds_read_b128 v[132:135], v49 offset:52224
	ds_read_b128 v[136:139], v49 offset:54272
	ds_read_b128 v[140:143], v49 offset:56320
	v_mfma_f32_16x16x32_bf16 v[104:107], v[124:127], v[32:35], v[104:107]
	ds_read_b128 v[124:127], v49 offset:58368
	ds_read_b128 v[144:147], v49 offset:60416
	ds_read_b128 v[148:151], v49 offset:62464
	ds_read_b128 v[152:155], v49 offset:64512
	v_mfma_f32_16x16x32_bf16 v[108:111], v[120:123], v[32:35], v[108:111]
	s_add_u32 s100, s10, 0x11420280
	s_addc_u32 s101, s11, 0
	s_mov_b32 m0, s26
	s_nop 0
	global_load_lds_dwordx4 v240, s[100:101]
	s_waitcnt lgkmcnt(0)
	v_mfma_f32_16x16x32_bf16 v[84:87], v[84:87], v[32:35], v[88:91]
	v_mfma_f32_16x16x32_bf16 v[88:91], v[132:135], v[32:35], v[92:95]
	v_mfma_f32_16x16x32_bf16 v[92:95], v[136:139], v[32:35], v[96:99]
	v_mfma_f32_16x16x32_bf16 v[96:99], v[140:143], v[32:35], v[100:103]
	v_mfma_f32_16x16x32_bf16 v[100:103], v[124:127], v[32:35], v[112:115]
	v_mfma_f32_16x16x32_bf16 v[112:115], v[144:147], v[32:35], v[116:119]
	v_mfma_f32_16x16x32_bf16 v[116:119], v[148:151], v[32:35], v[128:131]
	v_mfma_f32_16x16x32_bf16 v[32:35], v[152:155], v[32:35], v[36:39]
	s_add_u32 s100, s10, 0x11430280
	s_addc_u32 s101, s11, 0
	s_mov_b32 m0, s27
	s_nop 0
	global_load_lds_dwordx4 v240, s[100:101]
	s_nop 0
	s_waitcnt vmcnt(0)
	s_waitcnt vmcnt(0)
	s_barrier
	v_mov_b32_e32 v49, v65
	ds_read_b128 v[36:39], v49
	ds_read_b128 v[66:69], v49 offset:2048
	s_waitcnt lgkmcnt(0)
	v_mfma_f32_16x16x32_bf16 v[36:39], v[36:39], v[28:31], v[40:43]
	s_nop 2
	ds_read_b128 v[40:43], v49 offset:4096
	v_mfma_f32_16x16x32_bf16 v[44:47], v[66:69], v[28:31], v[44:47]
	ds_read_b128 v[66:69], v49 offset:6144
	s_waitcnt lgkmcnt(0)
	v_mfma_f32_16x16x32_bf16 v[40:43], v[40:43], v[28:31], v[50:53]
	s_nop 2
	ds_read_b128 v[50:53], v49 offset:8192
	v_mfma_f32_16x16x32_bf16 v[66:69], v[66:69], v[28:31], v[72:75]
	s_nop 2
	ds_read_b128 v[72:75], v49 offset:10240
	s_waitcnt lgkmcnt(0)
	v_mfma_f32_16x16x32_bf16 v[50:53], v[50:53], v[28:31], v[76:79]
	s_nop 2
	ds_read_b128 v[76:79], v49 offset:12288
	ds_read_b128 v[120:123], v49 offset:14336
	v_mfma_f32_16x16x32_bf16 v[72:75], v[72:75], v[28:31], v[80:83]
	s_nop 2
	ds_read_b128 v[80:83], v49 offset:32768
	ds_read_b128 v[124:127], v49 offset:34816
	ds_read_b128 v[128:131], v49 offset:36864
	ds_read_b128 v[132:135], v49 offset:38912
	s_waitcnt lgkmcnt(0)
	v_mfma_f32_16x16x32_bf16 v[76:79], v[76:79], v[28:31], v[104:107]
	s_nop 2
	ds_read_b128 v[104:107], v49 offset:40960
	ds_read_b128 v[136:139], v49 offset:43008
	ds_read_b128 v[140:143], v49 offset:45056
	ds_read_b128 v[144:147], v49 offset:47104
	v_mfma_f32_16x16x32_bf16 v[108:111], v[120:123], v[28:31], v[108:111]
	s_add_u32 s100, s10, 0x11400300
	s_addc_u32 s101, s11, 0
	s_mov_b32 m0, s19
	s_nop 0
	global_load_lds_dwordx4 v240, s[100:101]
	v_mfma_f32_16x16x32_bf16 v[80:83], v[80:83], v[28:31], v[84:87]
	v_mfma_f32_16x16x32_bf16 v[84:87], v[124:127], v[28:31], v[88:91]
	v_mfma_f32_16x16x32_bf16 v[88:91], v[128:131], v[28:31], v[92:95]
	v_mfma_f32_16x16x32_bf16 v[92:95], v[132:135], v[28:31], v[96:99]
	s_waitcnt lgkmcnt(0)
	v_mfma_f32_16x16x32_bf16 v[96:99], v[104:107], v[28:31], v[100:103]
	v_mfma_f32_16x16x32_bf16 v[100:103], v[136:139], v[28:31], v[112:115]
	ds_read_b128 v[104:107], v49 offset:15360
	s_nop 1
	ds_read_b128 v[112:115], v49 offset:13312
	ds_read_b128 v[120:123], v49 offset:11264
	ds_read_b128 v[124:127], v49 offset:9216
	v_mfma_f32_16x16x32_bf16 v[116:119], v[140:143], v[28:31], v[116:119]
	ds_read_b128 v[128:131], v49 offset:7168
	ds_read_b128 v[132:135], v49 offset:5120
	ds_read_b128 v[136:139], v49 offset:3072
	ds_read_b128 v[140:143], v49 offset:1024
	v_mfma_f32_16x16x32_bf16 v[28:31], v[144:147], v[28:31], v[32:35]
	s_add_u32 s100, s10, 0x11410300
	s_addc_u32 s101, s11, 0
	s_mov_b32 m0, s13
	s_nop 0
	global_load_lds_dwordx4 v240, s[100:101]
	s_waitcnt lgkmcnt(0)
	v_mfma_f32_16x16x32_bf16 v[32:35], v[140:143], v[24:27], v[36:39]
	v_mfma_f32_16x16x32_bf16 v[36:39], v[136:139], v[24:27], v[44:47]
	v_mfma_f32_16x16x32_bf16 v[40:43], v[132:135], v[24:27], v[40:43]
	v_mfma_f32_16x16x32_bf16 v[44:47], v[128:131], v[24:27], v[66:69]
	v_mfma_f32_16x16x32_bf16 v[50:53], v[124:127], v[24:27], v[50:53]
	v_mfma_f32_16x16x32_bf16 v[66:69], v[120:123], v[24:27], v[72:75]
	s_nop 2
	ds_read_b128 v[72:75], v49 offset:33792
	ds_read_b128 v[120:123], v49 offset:35840
	ds_read_b128 v[124:127], v49 offset:37888
	ds_read_b128 v[128:131], v49 offset:39936
	v_mfma_f32_16x16x32_bf16 v[76:79], v[112:115], v[24:27], v[76:79]
	ds_read_b128 v[112:115], v49 offset:41984
	ds_read_b128 v[132:135], v49 offset:44032
	ds_read_b128 v[136:139], v49 offset:46080
	ds_read_b128 v[140:143], v49 offset:48128
	v_mfma_f32_16x16x32_bf16 v[104:107], v[104:107], v[24:27], v[108:111]
	s_add_u32 s100, s10, 0x11400380
	s_addc_u32 s101, s11, 0
	s_mov_b32 m0, s12
	s_nop 0
	global_load_lds_dwordx4 v240, s[100:101]
	s_waitcnt lgkmcnt(0)
	v_mfma_f32_16x16x32_bf16 v[72:75], v[72:75], v[24:27], v[80:83]
	v_mfma_f32_16x16x32_bf16 v[80:83], v[120:123], v[24:27], v[84:87]
	v_mfma_f32_16x16x32_bf16 v[84:87], v[124:127], v[24:27], v[88:91]
	v_mfma_f32_16x16x32_bf16 v[88:91], v[128:131], v[24:27], v[92:95]
	v_mfma_f32_16x16x32_bf16 v[92:95], v[112:115], v[24:27], v[96:99]
	v_mfma_f32_16x16x32_bf16 v[96:99], v[132:135], v[24:27], v[100:103]
	s_nop 2
	ds_read_b128 v[100:103], v49 offset:30720
	ds_read_b128 v[108:111], v49 offset:28672
	ds_read_b128 v[112:115], v49 offset:26624
	ds_read_b128 v[120:123], v49 offset:24576
	v_mfma_f32_16x16x32_bf16 v[116:119], v[136:139], v[24:27], v[116:119]
	ds_read_b128 v[124:127], v49 offset:22528
	ds_read_b128 v[128:131], v49 offset:20480
	ds_read_b128 v[132:135], v49 offset:18432
	ds_read_b128 v[136:139], v49 offset:16384
	v_mfma_f32_16x16x32_bf16 v[24:27], v[140:143], v[24:27], v[28:31]
	s_add_u32 s100, s10, 0x11410380
	s_addc_u32 s101, s11, 0
	s_mov_b32 m0, s14
	s_nop 0
	global_load_lds_dwordx4 v240, s[100:101]
	s_waitcnt lgkmcnt(0)
	v_mfma_f32_16x16x32_bf16 v[28:31], v[136:139], v[20:23], v[32:35]
	v_mfma_f32_16x16x32_bf16 v[32:35], v[132:135], v[20:23], v[36:39]
	v_mfma_f32_16x16x32_bf16 v[36:39], v[128:131], v[20:23], v[40:43]
	v_mfma_f32_16x16x32_bf16 v[40:43], v[124:127], v[20:23], v[44:47]
	v_mfma_f32_16x16x32_bf16 v[44:47], v[120:123], v[20:23], v[50:53]
	v_mfma_f32_16x16x32_bf16 v[50:53], v[112:115], v[20:23], v[66:69]
	s_nop 2
	ds_read_b128 v[66:69], v49 offset:49152
	ds_read_b128 v[112:115], v49 offset:51200
	ds_read_b128 v[120:123], v49 offset:53248
	ds_read_b128 v[124:127], v49 offset:55296
	v_mfma_f32_16x16x32_bf16 v[76:79], v[108:111], v[20:23], v[76:79]
	ds_read_b128 v[108:111], v49 offset:57344
	ds_read_b128 v[128:131], v49 offset:59392
	ds_read_b128 v[132:135], v49 offset:61440
	ds_read_b128 v[136:139], v49 offset:63488
	v_mfma_f32_16x16x32_bf16 v[100:103], v[100:103], v[20:23], v[104:107]
	s_add_u32 s100, s10, 0x11420300
	s_addc_u32 s101, s11, 0
	s_mov_b32 m0, s15
	s_nop 0
	global_load_lds_dwordx4 v240, s[100:101]
	s_waitcnt lgkmcnt(0)
	v_mfma_f32_16x16x32_bf16 v[66:69], v[66:69], v[20:23], v[72:75]
	v_mfma_f32_16x16x32_bf16 v[72:75], v[112:115], v[20:23], v[80:83]
	v_mfma_f32_16x16x32_bf16 v[80:83], v[120:123], v[20:23], v[84:87]
	v_mfma_f32_16x16x32_bf16 v[84:87], v[124:127], v[20:23], v[88:91]
	v_mfma_f32_16x16x32_bf16 v[88:91], v[108:111], v[20:23], v[92:95]
	v_mfma_f32_16x16x32_bf16 v[92:95], v[128:131], v[20:23], v[96:99]
	s_nop 2
	ds_read_b128 v[96:99], v49 offset:31744
	ds_read_b128 v[104:107], v49 offset:29696
	ds_read_b128 v[108:111], v49 offset:27648
	ds_read_b128 v[112:115], v49 offset:25600
	v_mfma_f32_16x16x32_bf16 v[116:119], v[132:135], v[20:23], v[116:119]
	ds_read_b128 v[120:123], v49 offset:23552
	ds_read_b128 v[124:127], v49 offset:21504
	ds_read_b128 v[128:131], v49 offset:19456
	ds_read_b128 v[132:135], v49 offset:17408
	v_mfma_f32_16x16x32_bf16 v[20:23], v[136:139], v[20:23], v[24:27]
	s_add_u32 s100, s10, 0x11430300
	s_addc_u32 s101, s11, 0
	s_mov_b32 m0, s16
	s_nop 0
	global_load_lds_dwordx4 v240, s[100:101]
	s_waitcnt lgkmcnt(0)
	v_mfma_f32_16x16x32_bf16 v[24:27], v[132:135], v[16:19], v[28:31]
	v_mfma_f32_16x16x32_bf16 v[28:31], v[128:131], v[16:19], v[32:35]
	v_mfma_f32_16x16x32_bf16 v[32:35], v[124:127], v[16:19], v[36:39]
	v_mfma_f32_16x16x32_bf16 v[36:39], v[120:123], v[16:19], v[40:43]
	v_mfma_f32_16x16x32_bf16 v[40:43], v[112:115], v[16:19], v[44:47]
	v_mfma_f32_16x16x32_bf16 v[50:53], v[108:111], v[16:19], v[50:53]
	s_nop 1
	ds_read_b128 v[44:47], v49 offset:50176
	ds_read_b128 v[108:111], v49 offset:52224
	ds_read_b128 v[112:115], v49 offset:54272
	ds_read_b128 v[120:123], v49 offset:56320
	v_mfma_f32_16x16x32_bf16 v[76:79], v[104:107], v[16:19], v[76:79]
	ds_read_b128 v[104:107], v49 offset:58368
	ds_read_b128 v[124:127], v49 offset:60416
	ds_read_b128 v[128:131], v49 offset:62464
	ds_read_b128 v[132:135], v49 offset:64512
	v_mfma_f32_16x16x32_bf16 v[96:99], v[96:99], v[16:19], v[100:103]
	s_add_u32 s100, s10, 0x11420380
	s_addc_u32 s101, s11, 0
	s_mov_b32 m0, s17
	s_nop 0
	global_load_lds_dwordx4 v240, s[100:101]
	s_waitcnt lgkmcnt(0)
	v_mfma_f32_16x16x32_bf16 v[66:69], v[44:47], v[16:19], v[66:69]
	v_mfma_f32_16x16x32_bf16 v[72:75], v[108:111], v[16:19], v[72:75]
	v_mfma_f32_16x16x32_bf16 v[80:83], v[112:115], v[16:19], v[80:83]
	v_mfma_f32_16x16x32_bf16 v[84:87], v[120:123], v[16:19], v[84:87]
	v_mfma_f32_16x16x32_bf16 v[88:91], v[104:107], v[16:19], v[88:91]
	v_mfma_f32_16x16x32_bf16 v[92:95], v[124:127], v[16:19], v[92:95]
	v_mfma_f32_16x16x32_bf16 v[100:103], v[128:131], v[16:19], v[116:119]
	v_mfma_f32_16x16x32_bf16 v[16:19], v[132:135], v[16:19], v[20:23]
	s_add_u32 s100, s10, 0x11430380
	s_addc_u32 s101, s11, 0
	s_mov_b32 m0, s18
	s_nop 0
	global_load_lds_dwordx4 v240, s[100:101]
	s_waitcnt vmcnt(0)
	s_waitcnt vmcnt(0)
	s_barrier
	v_mov_b32_e32 v49, v48
	ds_read_b128 v[20:23], v49
	ds_read_b128 v[104:107], v49 offset:2048
	s_waitcnt lgkmcnt(0)
	v_mfma_f32_16x16x32_bf16 v[20:23], v[20:23], v[12:15], v[24:27]
	s_nop 2
	ds_read_b128 v[24:27], v49 offset:4096
	v_mfma_f32_16x16x32_bf16 v[28:31], v[104:107], v[12:15], v[28:31]
	ds_read_b128 v[104:107], v49 offset:6144
	s_waitcnt lgkmcnt(0)
	v_mfma_f32_16x16x32_bf16 v[24:27], v[24:27], v[12:15], v[32:35]
	s_nop 2
	ds_read_b128 v[32:35], v49 offset:8192
	v_mfma_f32_16x16x32_bf16 v[36:39], v[104:107], v[12:15], v[36:39]
	ds_read_b128 v[104:107], v49 offset:10240
	s_waitcnt lgkmcnt(0)
	v_mfma_f32_16x16x32_bf16 v[32:35], v[32:35], v[12:15], v[40:43]
	s_nop 2
	ds_read_b128 v[40:43], v49 offset:12288
	ds_read_b128 v[108:111], v49 offset:14336
	v_mfma_f32_16x16x32_bf16 v[50:53], v[104:107], v[12:15], v[50:53]
	ds_read_b128 v[104:107], v49 offset:32768
	ds_read_b128 v[112:115], v49 offset:34816
	ds_read_b128 v[116:119], v49 offset:36864
	ds_read_b128 v[120:123], v49 offset:38912
	s_waitcnt lgkmcnt(0)
	v_mfma_f32_16x16x32_bf16 v[40:43], v[40:43], v[12:15], v[76:79]
	s_nop 2
	ds_read_b128 v[76:79], v49 offset:40960
	ds_read_b128 v[124:127], v49 offset:43008
	ds_read_b128 v[128:131], v49 offset:45056
	ds_read_b128 v[132:135], v49 offset:47104
	v_mfma_f32_16x16x32_bf16 v[96:99], v[108:111], v[12:15], v[96:99]
	s_add_u32 s100, s10, 0x11c00000
	s_addc_u32 s101, s11, 0
	s_mov_b32 m0, s22
	s_nop 0
	global_load_lds_dwordx4 v241, s[100:101]
	v_mfma_f32_16x16x32_bf16 v[66:69], v[104:107], v[12:15], v[66:69]
	v_mfma_f32_16x16x32_bf16 v[72:75], v[112:115], v[12:15], v[72:75]
	v_mfma_f32_16x16x32_bf16 v[80:83], v[116:119], v[12:15], v[80:83]
	v_mfma_f32_16x16x32_bf16 v[84:87], v[120:123], v[12:15], v[84:87]
	s_waitcnt lgkmcnt(0)
	v_mfma_f32_16x16x32_bf16 v[76:79], v[76:79], v[12:15], v[88:91]
	v_mfma_f32_16x16x32_bf16 v[88:91], v[124:127], v[12:15], v[92:95]
	s_nop 2
	ds_read_b128 v[92:95], v49 offset:15360
	ds_read_b128 v[104:107], v49 offset:13312
	ds_read_b128 v[108:111], v49 offset:11264
	ds_read_b128 v[112:115], v49 offset:9216
	v_mfma_f32_16x16x32_bf16 v[100:103], v[128:131], v[12:15], v[100:103]
	ds_read_b128 v[116:119], v49 offset:7168
	ds_read_b128 v[120:123], v49 offset:5120
	ds_read_b128 v[124:127], v49 offset:3072
	ds_read_b128 v[128:131], v49 offset:1024
	v_mfma_f32_16x16x32_bf16 v[12:15], v[132:135], v[12:15], v[16:19]
	s_add_u32 s100, s10, 0x11c08000
	s_addc_u32 s101, s11, 0
	s_mov_b32 m0, s21
	s_nop 0
	global_load_lds_dwordx4 v241, s[100:101]
	s_waitcnt lgkmcnt(0)
	v_mfma_f32_16x16x32_bf16 v[16:19], v[128:131], v[8:11], v[20:23]
	v_mfma_f32_16x16x32_bf16 v[20:23], v[124:127], v[8:11], v[28:31]
	v_mfma_f32_16x16x32_bf16 v[24:27], v[120:123], v[8:11], v[24:27]
	v_mfma_f32_16x16x32_bf16 v[28:31], v[116:119], v[8:11], v[36:39]
	v_mfma_f32_16x16x32_bf16 v[32:35], v[112:115], v[8:11], v[32:35]
	v_mfma_f32_16x16x32_bf16 v[36:39], v[108:111], v[8:11], v[50:53]
	s_nop 2
	ds_read_b128 v[50:53], v49 offset:33792
	ds_read_b128 v[108:111], v49 offset:35840
	ds_read_b128 v[112:115], v49 offset:37888
	ds_read_b128 v[116:119], v49 offset:39936
	v_mfma_f32_16x16x32_bf16 v[40:43], v[104:107], v[8:11], v[40:43]
	ds_read_b128 v[104:107], v49 offset:41984
	ds_read_b128 v[120:123], v49 offset:44032
	ds_read_b128 v[124:127], v49 offset:46080
	ds_read_b128 v[128:131], v49 offset:48128
	v_mfma_f32_16x16x32_bf16 v[92:95], v[92:95], v[8:11], v[96:99]
	s_add_u32 s100, s10, 0x11c00080
	s_addc_u32 s101, s11, 0
	s_mov_b32 m0, s20
	s_nop 0
	global_load_lds_dwordx4 v241, s[100:101]
	s_waitcnt lgkmcnt(0)
	v_mfma_f32_16x16x32_bf16 v[50:53], v[50:53], v[8:11], v[66:69]
	v_mfma_f32_16x16x32_bf16 v[66:69], v[108:111], v[8:11], v[72:75]
	v_mfma_f32_16x16x32_bf16 v[72:75], v[112:115], v[8:11], v[80:83]
	v_mfma_f32_16x16x32_bf16 v[80:83], v[116:119], v[8:11], v[84:87]
	v_mfma_f32_16x16x32_bf16 v[76:79], v[104:107], v[8:11], v[76:79]
	v_mfma_f32_16x16x32_bf16 v[84:87], v[120:123], v[8:11], v[88:91]
	s_nop 2
	ds_read_b128 v[88:91], v49 offset:30720
	ds_read_b128 v[96:99], v49 offset:28672
	ds_read_b128 v[104:107], v49 offset:26624
	ds_read_b128 v[108:111], v49 offset:24576
	v_mfma_f32_16x16x32_bf16 v[100:103], v[124:127], v[8:11], v[100:103]
	ds_read_b128 v[112:115], v49 offset:22528
	ds_read_b128 v[116:119], v49 offset:20480
	ds_read_b128 v[120:123], v49 offset:18432
	ds_read_b128 v[124:127], v49 offset:16384
	v_mfma_f32_16x16x32_bf16 v[8:11], v[128:131], v[8:11], v[12:15]
	s_add_u32 s100, s10, 0x11c08080
	s_addc_u32 s101, s11, 0
	s_mov_b32 m0, s23
	s_nop 0
	global_load_lds_dwordx4 v241, s[100:101]
	s_waitcnt lgkmcnt(0)
	v_mfma_f32_16x16x32_bf16 v[12:15], v[124:127], v[4:7], v[16:19]
	v_mfma_f32_16x16x32_bf16 v[16:19], v[120:123], v[4:7], v[20:23]
	v_mfma_f32_16x16x32_bf16 v[20:23], v[116:119], v[4:7], v[24:27]
	v_mfma_f32_16x16x32_bf16 v[24:27], v[112:115], v[4:7], v[28:31]
	v_mfma_f32_16x16x32_bf16 v[28:31], v[108:111], v[4:7], v[32:35]
	v_mfma_f32_16x16x32_bf16 v[32:35], v[104:107], v[4:7], v[36:39]
	s_nop 2
	ds_read_b128 v[36:39], v49 offset:49152
	ds_read_b128 v[104:107], v49 offset:51200
	ds_read_b128 v[108:111], v49 offset:53248
	ds_read_b128 v[112:115], v49 offset:55296
	v_mfma_f32_16x16x32_bf16 v[96:99], v[96:99], v[4:7], v[40:43]
	s_nop 2
	ds_read_b128 v[40:43], v49 offset:57344
	ds_read_b128 v[116:119], v49 offset:59392
	ds_read_b128 v[120:123], v49 offset:61440
	ds_read_b128 v[124:127], v49 offset:63488
	v_mfma_f32_16x16x32_bf16 v[88:91], v[88:91], v[4:7], v[92:95]
	s_add_u32 s100, s10, 0x11c10000
	s_addc_u32 s101, s11, 0
	s_mov_b32 m0, s24
	s_nop 0
	global_load_lds_dwordx4 v241, s[100:101]
	s_waitcnt lgkmcnt(0)
	v_mfma_f32_16x16x32_bf16 v[50:53], v[36:39], v[4:7], v[50:53]
	v_mfma_f32_16x16x32_bf16 v[66:69], v[104:107], v[4:7], v[66:69]
	v_mfma_f32_16x16x32_bf16 v[72:75], v[108:111], v[4:7], v[72:75]
	v_mfma_f32_16x16x32_bf16 v[80:83], v[112:115], v[4:7], v[80:83]
	v_mfma_f32_16x16x32_bf16 v[76:79], v[40:43], v[4:7], v[76:79]
	ds_read_b128 v[92:95], v49 offset:31744
	ds_read_b128 v[36:39], v49 offset:29696
	ds_read_b128 v[40:43], v49 offset:27648
	ds_read_b128 v[104:107], v49 offset:25600
	v_mfma_f32_16x16x32_bf16 v[84:87], v[116:119], v[4:7], v[84:87]
	v_mfma_f32_16x16x32_bf16 v[100:103], v[120:123], v[4:7], v[100:103]
	ds_read_b128 v[108:111], v49 offset:23552
	ds_read_b128 v[112:115], v49 offset:21504
	ds_read_b128 v[116:119], v49 offset:19456
	ds_read_b128 v[120:123], v49 offset:17408
	v_mfma_f32_16x16x32_bf16 v[124:127], v[124:127], v[4:7], v[8:11]
	s_add_u32 s100, s10, 0x11c18000
	s_addc_u32 s101, s11, 0
	s_mov_b32 m0, s25
	s_nop 0
	global_load_lds_dwordx4 v241, s[100:101]
	s_waitcnt lgkmcnt(0)
	v_mfma_f32_16x16x32_bf16 v[120:123], v[120:123], v[0:3], v[12:15]
	v_mfma_f32_16x16x32_bf16 v[116:119], v[116:119], v[0:3], v[16:19]
	ds_read_b128 v[4:7], v49 offset:50176
	ds_read_b128 v[8:11], v49 offset:52224
	ds_read_b128 v[12:15], v49 offset:54272
	ds_read_b128 v[16:19], v49 offset:56320
	v_mfma_f32_16x16x32_bf16 v[36:39], v[36:39], v[0:3], v[96:99]
	s_nop 2
	ds_read_b128 v[96:99], v49 offset:58368
	ds_read_b128 v[128:131], v49 offset:60416
	ds_read_b128 v[132:135], v49 offset:62464
	ds_read_b128 v[136:139], v49 offset:64512
	v_mfma_f32_16x16x32_bf16 v[112:115], v[112:115], v[0:3], v[20:23]
	v_mfma_f32_16x16x32_bf16 v[108:111], v[108:111], v[0:3], v[24:27]
	v_mfma_f32_16x16x32_bf16 v[104:107], v[104:107], v[0:3], v[28:31]
	v_mfma_f32_16x16x32_bf16 v[40:43], v[40:43], v[0:3], v[32:35]
	v_mfma_f32_16x16x32_bf16 v[32:35], v[92:95], v[0:3], v[88:91]
	s_add_u32 s100, s10, 0x11c10080
	s_addc_u32 s101, s11, 0
	s_mov_b32 m0, s26
	s_nop 0
	global_load_lds_dwordx4 v241, s[100:101]
	s_waitcnt lgkmcnt(0)
	v_mfma_f32_16x16x32_bf16 v[28:31], v[4:7], v[0:3], v[50:53]
	v_mfma_f32_16x16x32_bf16 v[24:27], v[8:11], v[0:3], v[66:69]
	v_mfma_f32_16x16x32_bf16 v[20:23], v[12:15], v[0:3], v[72:75]
	v_mfma_f32_16x16x32_bf16 v[16:19], v[16:19], v[0:3], v[80:83]
	v_mfma_f32_16x16x32_bf16 v[12:15], v[96:99], v[0:3], v[76:79]
	v_mfma_f32_16x16x32_bf16 v[8:11], v[128:131], v[0:3], v[84:87]
	v_mfma_f32_16x16x32_bf16 v[4:7], v[132:135], v[0:3], v[100:103]
	v_mfma_f32_16x16x32_bf16 v[0:3], v[136:139], v[0:3], v[124:127]
	s_add_u32 s100, s10, 0x11c18080
	s_addc_u32 s101, s11, 0
	s_mov_b32 m0, s27
	s_nop 0
	global_load_lds_dwordx4 v241, s[100:101]
	v_max_f32_e32 v49, v123, v123
	v_max_f32_e32 v50, v122, v122
	v_max_f32_e32 v49, v50, v49
	v_max_f32_e32 v50, v117, v117
	v_max_f32_e32 v51, v116, v116
	v_max_f32_e32 v50, v51, v50
	v_max_f32_e32 v51, v119, v119
	v_max_f32_e32 v52, v118, v118
	v_max3_f32 v49, v120, v121, v49
	v_max_f32_e32 v51, v52, v51
	v_max3_f32 v49, v49, v50, v51
	v_max_f32_e32 v50, v113, v113
	v_max_f32_e32 v51, v112, v112
	v_max_f32_e32 v50, v51, v50
	v_max_f32_e32 v51, v115, v115
	v_max_f32_e32 v52, v114, v114
	v_max_f32_e32 v51, v52, v51
	v_max3_f32 v49, v49, v50, v51
	v_max_f32_e32 v50, v109, v109
	v_max_f32_e32 v51, v108, v108
	v_max_f32_e32 v50, v51, v50
	v_max_f32_e32 v51, v111, v111
	v_max_f32_e32 v52, v110, v110
	v_max_f32_e32 v51, v52, v51
	v_max3_f32 v49, v49, v50, v51
	v_max_f32_e32 v50, v105, v105
	v_max_f32_e32 v51, v104, v104
	v_max_f32_e32 v50, v51, v50
	v_max_f32_e32 v51, v107, v107
	v_max_f32_e32 v52, v106, v106
	v_max_f32_e32 v51, v52, v51
	v_max3_f32 v49, v49, v50, v51
	v_max_f32_e32 v50, v41, v41
	v_max_f32_e32 v51, v40, v40
	v_max_f32_e32 v50, v51, v50
	v_max_f32_e32 v51, v43, v43
	v_max_f32_e32 v52, v42, v42
	v_max_f32_e32 v51, v52, v51
	v_max3_f32 v49, v49, v50, v51
	v_max_f32_e32 v50, v37, v37
	v_max_f32_e32 v51, v36, v36
	v_max_f32_e32 v50, v51, v50
	v_max_f32_e32 v51, v39, v39
	v_max_f32_e32 v52, v38, v38
	v_max_f32_e32 v51, v52, v51
	v_max3_f32 v49, v49, v50, v51
	v_max_f32_e32 v50, v33, v33
	v_max_f32_e32 v51, v32, v32
	v_max_f32_e32 v50, v51, v50
	v_max_f32_e32 v51, v35, v35
	v_max_f32_e32 v52, v34, v34
	v_max_f32_e32 v51, v52, v51
	v_max3_f32 v49, v49, v50, v51
	v_max_f32_e32 v50, v29, v29
	v_max_f32_e32 v51, v28, v28
	v_max_f32_e32 v50, v51, v50
	v_max_f32_e32 v51, v31, v31
	v_max_f32_e32 v52, v30, v30
	v_max_f32_e32 v51, v52, v51
	v_max3_f32 v49, v49, v50, v51
	v_max_f32_e32 v50, v25, v25
	v_max_f32_e32 v51, v24, v24
	v_max_f32_e32 v50, v51, v50
	v_max_f32_e32 v51, v27, v27
	v_max_f32_e32 v52, v26, v26
	v_max_f32_e32 v51, v52, v51
	v_max3_f32 v49, v49, v50, v51
	v_max_f32_e32 v50, v21, v21
	v_max_f32_e32 v51, v20, v20
	v_max_f32_e32 v50, v51, v50
	v_max_f32_e32 v51, v23, v23
	v_max_f32_e32 v52, v22, v22
	v_max_f32_e32 v51, v52, v51
	v_max3_f32 v49, v49, v50, v51
	v_max_f32_e32 v50, v17, v17
	v_max_f32_e32 v51, v16, v16
	v_max_f32_e32 v50, v51, v50
	v_max_f32_e32 v51, v19, v19
	v_max_f32_e32 v52, v18, v18
	v_max_f32_e32 v51, v52, v51
	v_max3_f32 v49, v49, v50, v51
	v_max_f32_e32 v50, v13, v13
	v_max_f32_e32 v51, v12, v12
	v_max_f32_e32 v50, v51, v50
	v_max_f32_e32 v51, v15, v15
	v_max_f32_e32 v52, v14, v14
	v_max_f32_e32 v51, v52, v51
	v_max3_f32 v49, v49, v50, v51
	v_max_f32_e32 v50, v9, v9
	v_max_f32_e32 v51, v8, v8
	v_max_f32_e32 v50, v51, v50
	v_max_f32_e32 v51, v11, v11
	v_max_f32_e32 v52, v10, v10
	v_max_f32_e32 v51, v52, v51
	v_max3_f32 v49, v49, v50, v51
	v_max_f32_e32 v50, v5, v5
	v_max_f32_e32 v51, v4, v4
	v_max_f32_e32 v50, v51, v50
	v_max_f32_e32 v51, v7, v7
	v_max_f32_e32 v52, v6, v6
	v_max_f32_e32 v51, v52, v51
	v_max3_f32 v49, v49, v50, v51
	v_max_f32_e32 v50, v1, v1
	v_max_f32_e32 v51, v0, v0
	v_max_f32_e32 v50, v51, v50
	v_max_f32_e32 v51, v3, v3
	v_max_f32_e32 v52, v2, v2
	v_max_f32_e32 v51, v52, v51
	v_max3_f32 v49, v49, v50, v51
	v_mbcnt_lo_u32_b32 v50, -1, 0
	v_mbcnt_hi_u32_b32 v50, -1, v50
	v_and_b32_e32 v52, 64, v50
	v_xor_b32_e32 v51, 16, v50
	v_add_u32_e32 v52, 64, v52
	v_cmp_lt_i32_e32 vcc, v51, v52
	s_nop 1
	v_cndmask_b32_e32 v51, v50, v51, vcc
	v_lshlrev_b32_e32 v51, 2, v51
	ds_bpermute_b32 v53, v51, v49
	s_waitcnt lgkmcnt(0)
	v_max_f32_e32 v53, v53, v53
	v_max_f32_e32 v49, v49, v53
	v_xor_b32_e32 v53, 32, v50
	v_cmp_lt_i32_e32 vcc, v53, v52
	s_nop 1
	v_cndmask_b32_e32 v50, v50, v53, vcc
	v_lshlrev_b32_e32 v50, 2, v50
	ds_bpermute_b32 v52, v50, v49
	s_waitcnt lgkmcnt(0)
	v_max_f32_e32 v52, v52, v52
	v_max_f32_e32 v49, v49, v52
	v_sub_f32_e32 v52, v120, v49
	v_exp_f32_e32 v52, v52
	v_sub_f32_e32 v53, v121, v49
	v_exp_f32_e32 v53, v53
	v_sub_f32_e32 v54, v122, v49
	v_exp_f32_e32 v54, v54
	v_sub_f32_e32 v55, v123, v49
	v_exp_f32_e32 v55, v55
	v_sub_f32_e32 v59, v116, v49
	v_add_f32_e32 v57, 0, v52
	v_exp_f32_e32 v59, v59
	v_sub_f32_e32 v62, v117, v49
	v_add_f32_e32 v57, v53, v57
	v_exp_f32_e32 v62, v62
	v_sub_f32_e32 v63, v118, v49
	v_add_f32_e32 v57, v54, v57
	v_exp_f32_e32 v63, v63
	v_sub_f32_e32 v64, v119, v49
	v_add_f32_e32 v57, v55, v57
	v_exp_f32_e32 v64, v64
	v_sub_f32_e32 v66, v112, v49
	v_add_f32_e32 v57, v59, v57
	v_exp_f32_e32 v66, v66
	v_sub_f32_e32 v67, v113, v49
	v_add_f32_e32 v57, v62, v57
	v_exp_f32_e32 v67, v67
	v_sub_f32_e32 v68, v114, v49
	v_add_f32_e32 v57, v63, v57
	v_exp_f32_e32 v68, v68
	v_sub_f32_e32 v69, v115, v49
	v_add_f32_e32 v57, v64, v57
	v_exp_f32_e32 v69, v69
	v_sub_f32_e32 v71, v108, v49
	v_add_f32_e32 v57, v66, v57
	v_exp_f32_e32 v71, v71
	v_sub_f32_e32 v72, v109, v49
	v_add_f32_e32 v57, v67, v57
	v_exp_f32_e32 v72, v72
	v_sub_f32_e32 v73, v110, v49
	v_add_f32_e32 v57, v68, v57
	v_exp_f32_e32 v73, v73
	v_sub_f32_e32 v74, v111, v49
	v_add_f32_e32 v57, v69, v57
	v_exp_f32_e32 v74, v74
	v_sub_f32_e32 v75, v104, v49
	v_add_f32_e32 v57, v71, v57
	v_exp_f32_e32 v75, v75
	v_sub_f32_e32 v76, v105, v49
	v_add_f32_e32 v57, v72, v57
	v_exp_f32_e32 v76, v76
	v_sub_f32_e32 v77, v106, v49
	v_add_f32_e32 v57, v73, v57
	v_exp_f32_e32 v77, v77
	v_sub_f32_e32 v78, v107, v49
	v_add_f32_e32 v57, v74, v57
	v_exp_f32_e32 v78, v78
	v_sub_f32_e32 v40, v40, v49
	v_add_f32_e32 v57, v75, v57
	v_exp_f32_e32 v40, v40
	v_sub_f32_e32 v41, v41, v49
	v_add_f32_e32 v57, v76, v57
	v_exp_f32_e32 v41, v41
	v_sub_f32_e32 v42, v42, v49
	v_add_f32_e32 v57, v77, v57
	v_exp_f32_e32 v42, v42
	v_sub_f32_e32 v43, v43, v49
	v_add_f32_e32 v57, v78, v57
	v_exp_f32_e32 v43, v43
	v_sub_f32_e32 v36, v36, v49
	v_add_f32_e32 v57, v40, v57
	v_exp_f32_e32 v36, v36
	v_sub_f32_e32 v37, v37, v49
	v_add_f32_e32 v57, v41, v57
	v_exp_f32_e32 v37, v37
	v_sub_f32_e32 v38, v38, v49
	v_add_f32_e32 v57, v42, v57
	v_exp_f32_e32 v38, v38
	v_sub_f32_e32 v39, v39, v49
	v_add_f32_e32 v57, v43, v57
	v_exp_f32_e32 v39, v39
	v_sub_f32_e32 v32, v32, v49
	v_add_f32_e32 v57, v36, v57
	v_exp_f32_e32 v32, v32
	v_sub_f32_e32 v33, v33, v49
	v_add_f32_e32 v57, v37, v57
	v_exp_f32_e32 v33, v33
	v_sub_f32_e32 v34, v34, v49
	v_add_f32_e32 v57, v38, v57
	v_exp_f32_e32 v34, v34
	v_sub_f32_e32 v35, v35, v49
	v_add_f32_e32 v57, v39, v57
	v_exp_f32_e32 v35, v35
	v_sub_f32_e32 v28, v28, v49
	v_add_f32_e32 v57, v32, v57
	v_exp_f32_e32 v79, v28
	v_sub_f32_e32 v28, v29, v49
	v_add_f32_e32 v57, v33, v57
	v_exp_f32_e32 v80, v28
	v_sub_f32_e32 v28, v30, v49
	v_add_f32_e32 v57, v34, v57
	v_exp_f32_e32 v81, v28
	v_sub_f32_e32 v28, v31, v49
	v_add_f32_e32 v57, v35, v57
	v_exp_f32_e32 v82, v28
	v_sub_f32_e32 v24, v24, v49
	v_add_f32_e32 v28, v79, v57
	v_exp_f32_e32 v57, v24
	v_sub_f32_e32 v24, v25, v49
	v_add_f32_e32 v28, v80, v28
	v_exp_f32_e32 v83, v24
	v_sub_f32_e32 v24, v26, v49
	v_add_f32_e32 v28, v81, v28
	v_exp_f32_e32 v84, v24
	v_sub_f32_e32 v24, v27, v49
	v_add_f32_e32 v28, v82, v28
	v_exp_f32_e32 v85, v24
	v_sub_f32_e32 v20, v20, v49
	v_add_f32_e32 v24, v57, v28
	v_exp_f32_e32 v86, v20
	v_sub_f32_e32 v20, v21, v49
	v_add_f32_e32 v24, v83, v24
	v_exp_f32_e32 v87, v20
	v_sub_f32_e32 v20, v22, v49
	v_add_f32_e32 v24, v84, v24
	v_exp_f32_e32 v88, v20
	v_sub_f32_e32 v20, v23, v49
	v_add_f32_e32 v24, v85, v24
	v_exp_f32_e32 v89, v20
	v_sub_f32_e32 v16, v16, v49
	v_add_f32_e32 v20, v86, v24
	v_exp_f32_e32 v90, v16
	v_sub_f32_e32 v16, v17, v49
	v_add_f32_e32 v20, v87, v20
	v_exp_f32_e32 v91, v16
	v_sub_f32_e32 v16, v18, v49
	v_add_f32_e32 v20, v88, v20
	v_exp_f32_e32 v92, v16
	v_sub_f32_e32 v16, v19, v49
	v_add_f32_e32 v20, v89, v20
	v_exp_f32_e32 v93, v16
	v_sub_f32_e32 v12, v12, v49
	v_add_f32_e32 v16, v90, v20
	v_exp_f32_e32 v94, v12
	v_sub_f32_e32 v12, v13, v49
	v_add_f32_e32 v16, v91, v16
	v_exp_f32_e32 v95, v12
	v_sub_f32_e32 v12, v14, v49
	v_add_f32_e32 v16, v92, v16
	v_exp_f32_e32 v96, v12
	v_sub_f32_e32 v12, v15, v49
	v_add_f32_e32 v16, v93, v16
	v_exp_f32_e32 v97, v12
	v_sub_f32_e32 v8, v8, v49
	v_add_f32_e32 v12, v94, v16
	v_exp_f32_e32 v98, v8
	v_sub_f32_e32 v8, v9, v49
	v_add_f32_e32 v12, v95, v12
	v_exp_f32_e32 v99, v8
	v_sub_f32_e32 v8, v10, v49
	v_add_f32_e32 v12, v96, v12
	v_exp_f32_e32 v100, v8
	v_sub_f32_e32 v8, v11, v49
	v_add_f32_e32 v12, v97, v12
	v_exp_f32_e32 v11, v8
	v_sub_f32_e32 v4, v4, v49
	v_add_f32_e32 v8, v98, v12
	v_exp_f32_e32 v101, v4
	v_sub_f32_e32 v4, v5, v49
	v_add_f32_e32 v8, v99, v8
	v_exp_f32_e32 v102, v4
	v_sub_f32_e32 v4, v6, v49
	v_add_f32_e32 v8, v100, v8
	v_exp_f32_e32 v103, v4
	v_sub_f32_e32 v4, v7, v49
	v_add_f32_e32 v8, v11, v8
	v_exp_f32_e32 v104, v4
	v_sub_f32_e32 v0, v0, v49
	v_add_f32_e32 v4, v101, v8
	v_exp_f32_e32 v105, v0
	v_sub_f32_e32 v0, v1, v49
	v_add_f32_e32 v4, v102, v4
	v_exp_f32_e32 v106, v0
	v_sub_f32_e32 v0, v2, v49
	v_add_f32_e32 v4, v103, v4
	v_exp_f32_e32 v107, v0
	v_sub_f32_e32 v0, v3, v49
	v_add_f32_e32 v4, v104, v4
	v_exp_f32_e32 v3, v0
	v_add_f32_e32 v0, v105, v4
	v_add_f32_e32 v0, v106, v0
	v_add_f32_e32 v0, v107, v0
	v_add_f32_e32 v0, v3, v0
	ds_bpermute_b32 v1, v51, v0
	v_cvt_pk_bf16_f32 v28, v52, v53
	v_cvt_pk_bf16_f32 v29, v54, v55
	v_cvt_pk_bf16_f32 v30, v59, v62
	v_cvt_pk_bf16_f32 v31, v63, v64
	s_waitcnt lgkmcnt(0)
	v_add_f32_e32 v0, v0, v1
	ds_bpermute_b32 v1, v50, v0
	v_cvt_pk_bf16_f32 v20, v66, v67
	v_cvt_pk_bf16_f32 v21, v68, v69
	v_cvt_pk_bf16_f32 v22, v71, v72
	v_cvt_pk_bf16_f32 v23, v73, v74
	s_waitcnt lgkmcnt(0)
	v_add_f32_e32 v49, v0, v1
	v_cvt_pk_bf16_f32 v24, v75, v76
	v_cvt_pk_bf16_f32 v25, v77, v78
	v_cvt_pk_bf16_f32 v26, v40, v41
	v_cvt_pk_bf16_f32 v27, v42, v43
	v_cvt_pk_bf16_f32 v16, v36, v37
	v_cvt_pk_bf16_f32 v17, v38, v39
	v_cvt_pk_bf16_f32 v18, v32, v33
	v_cvt_pk_bf16_f32 v19, v34, v35
	v_cvt_pk_bf16_f32 v12, v79, v80
	v_cvt_pk_bf16_f32 v13, v81, v82
	v_cvt_pk_bf16_f32 v14, v57, v83
	v_cvt_pk_bf16_f32 v15, v84, v85
	v_cvt_pk_bf16_f32 v4, v86, v87
	v_cvt_pk_bf16_f32 v5, v88, v89
	v_cvt_pk_bf16_f32 v6, v90, v91
	v_cvt_pk_bf16_f32 v7, v92, v93
	v_cvt_pk_bf16_f32 v8, v94, v95
	v_cvt_pk_bf16_f32 v9, v96, v97
	v_cvt_pk_bf16_f32 v10, v98, v99
	v_cvt_pk_bf16_f32 v11, v100, v11
	v_cvt_pk_bf16_f32 v0, v101, v102
	v_cvt_pk_bf16_f32 v1, v103, v104
	v_cvt_pk_bf16_f32 v2, v105, v106
	v_cvt_pk_bf16_f32 v3, v107, v3
	s_waitcnt vmcnt(0)
	s_waitcnt vmcnt(0)
	s_barrier
	v_mov_b32_e32 v64, v65
	v_div_scale_f32 v62, vcc, 1.0, v49, 1.0
	v_lshlrev_b32_e32 v54, 2, v70
	v_ashrrev_i32_e32 v55, 31, v54
	ds_read_b128 v[32:35], v64
	ds_read_b128 v[36:39], v64 offset:2048
	v_div_scale_f32 v57, s[0:1], v49, v49, 1.0
	v_rcp_f32_e32 v59, v57
	s_waitcnt lgkmcnt(0)
	v_mfma_f32_16x16x32_bf16 v[44:47], v[32:35], v[28:31], 0
	v_fma_f32 v40, -v57, v59, 1.0
	v_fmac_f32_e32 v59, v40, v59
	ds_read_b128 v[40:43], v64 offset:4096
	ds_read_b128 v[32:35], v64 offset:6144
	v_mul_f32_e32 v63, v62, v59
	v_fma_f32 v66, -v57, v63, v62
	v_fmac_f32_e32 v63, v66, v59
	v_mfma_f32_16x16x32_bf16 v[50:53], v[36:39], v[28:31], 0
	v_fma_f32 v36, -v57, v63, v62
	ds_read_b128 v[66:69], v64 offset:8192
	ds_read_b128 v[70:73], v64 offset:10240
	v_div_fmas_f32 v36, v36, v59, v63
	s_waitcnt lgkmcnt(0)
	v_mfma_f32_16x16x32_bf16 v[74:77], v[32:35], v[28:31], 0
	v_lshl_add_u64 v[34:35], v[54:55], 1, v[60:61]
	ds_read_b128 v[60:63], v64 offset:12288
	ds_read_b128 v[78:81], v64 offset:14336
	ds_read_b128 v[82:85], v64 offset:32768
	ds_read_b128 v[86:89], v64 offset:34816
	ds_read_b128 v[90:93], v64 offset:36864
	ds_read_b128 v[94:97], v64 offset:38912
	ds_read_b128 v[98:101], v64 offset:40960
	ds_read_b128 v[102:105], v64 offset:43008
	ds_read_b128 v[106:109], v64 offset:45056
	ds_read_b128 v[110:113], v64 offset:47104
	s_mov_b64 s[0:1], 0x1000000
	v_mfma_f32_16x16x32_bf16 v[38:41], v[40:43], v[28:31], 0
	v_div_fixup_f32 v36, v36, v49, 1.0
	v_lshl_add_u64 v[32:33], v[34:35], 0, s[0:1]
	v_mfma_f32_16x16x32_bf16 v[66:69], v[66:69], v[28:31], 0
	v_mfma_f32_16x16x32_bf16 v[70:73], v[70:73], v[28:31], 0
	s_waitcnt lgkmcnt(0)
	v_mfma_f32_16x16x32_bf16 v[60:63], v[60:63], v[28:31], 0
	v_mfma_f32_16x16x32_bf16 v[78:81], v[78:81], v[28:31], 0
	s_add_u32 s100, s10, 0x11c00100
	s_addc_u32 s101, s11, 0
	s_mov_b32 m0, s19
	s_nop 0
	global_load_lds_dwordx4 v241, s[100:101]
	ds_read_b128 v[114:117], v64 offset:30720
	ds_read_b128 v[118:121], v64 offset:28672
	ds_read_b128 v[122:125], v64 offset:26624
	ds_read_b128 v[126:129], v64 offset:24576
	ds_read_b128 v[130:133], v64 offset:22528
	ds_read_b128 v[134:137], v64 offset:20480
	ds_read_b128 v[138:141], v64 offset:18432
	ds_read_b128 v[142:145], v64 offset:16384
	v_mfma_f32_16x16x32_bf16 v[82:85], v[82:85], v[28:31], 0
	v_mfma_f32_16x16x32_bf16 v[86:89], v[86:89], v[28:31], 0
	v_mfma_f32_16x16x32_bf16 v[90:93], v[90:93], v[28:31], 0
	v_mfma_f32_16x16x32_bf16 v[94:97], v[94:97], v[28:31], 0
	v_mfma_f32_16x16x32_bf16 v[98:101], v[98:101], v[28:31], 0
	v_mfma_f32_16x16x32_bf16 v[102:105], v[102:105], v[28:31], 0
	v_mfma_f32_16x16x32_bf16 v[106:109], v[106:109], v[28:31], 0
	v_mfma_f32_16x16x32_bf16 v[110:113], v[110:113], v[28:31], 0
	s_add_u32 s100, s10, 0x11c08100
	s_addc_u32 s101, s11, 0
	s_mov_b32 m0, s13
	s_nop 0
	global_load_lds_dwordx4 v241, s[100:101]
	s_waitcnt lgkmcnt(0)
	v_mfma_f32_16x16x32_bf16 v[42:45], v[142:145], v[24:27], v[44:47]
	v_mfma_f32_16x16x32_bf16 v[50:53], v[138:141], v[24:27], v[50:53]
	v_mfma_f32_16x16x32_bf16 v[38:41], v[134:137], v[24:27], v[38:41]
	v_mfma_f32_16x16x32_bf16 v[74:77], v[130:133], v[24:27], v[74:77]
	v_mfma_f32_16x16x32_bf16 v[66:69], v[126:129], v[24:27], v[66:69]
	v_mfma_f32_16x16x32_bf16 v[70:73], v[122:125], v[24:27], v[70:73]
	ds_read_b128 v[122:125], v64 offset:49152
	ds_read_b128 v[126:129], v64 offset:51200
	ds_read_b128 v[130:133], v64 offset:53248
	ds_read_b128 v[134:137], v64 offset:55296
	v_mfma_f32_16x16x32_bf16 v[60:63], v[118:121], v[24:27], v[60:63]
	ds_read_b128 v[118:121], v64 offset:57344
	ds_read_b128 v[138:141], v64 offset:59392
	ds_read_b128 v[142:145], v64 offset:61440
	ds_read_b128 v[146:149], v64 offset:63488
	v_mfma_f32_16x16x32_bf16 v[78:81], v[114:117], v[24:27], v[78:81]
	s_add_u32 s100, s10, 0x11c00180
	s_addc_u32 s101, s11, 0
	s_mov_b32 m0, s12
	s_nop 0
	global_load_lds_dwordx4 v241, s[100:101]
	s_waitcnt lgkmcnt(0)
	v_mfma_f32_16x16x32_bf16 v[82:85], v[122:125], v[24:27], v[82:85]
	v_mfma_f32_16x16x32_bf16 v[86:89], v[126:129], v[24:27], v[86:89]
	v_mfma_f32_16x16x32_bf16 v[90:93], v[130:133], v[24:27], v[90:93]
	v_mfma_f32_16x16x32_bf16 v[94:97], v[134:137], v[24:27], v[94:97]
	v_mfma_f32_16x16x32_bf16 v[98:101], v[118:121], v[24:27], v[98:101]
	ds_read_b128 v[114:117], v64 offset:15360
	ds_read_b128 v[118:121], v64 offset:13312
	ds_read_b128 v[122:125], v64 offset:11264
	ds_read_b128 v[126:129], v64 offset:9216
	v_mfma_f32_16x16x32_bf16 v[102:105], v[138:141], v[24:27], v[102:105]
	v_mfma_f32_16x16x32_bf16 v[106:109], v[142:145], v[24:27], v[106:109]
	ds_read_b128 v[130:133], v64 offset:7168
	ds_read_b128 v[134:137], v64 offset:5120
	ds_read_b128 v[138:141], v64 offset:3072
	ds_read_b128 v[142:145], v64 offset:1024
	v_mfma_f32_16x16x32_bf16 v[110:113], v[146:149], v[24:27], v[110:113]
	s_add_u32 s100, s10, 0x11c08180
	s_addc_u32 s101, s11, 0
	s_mov_b32 m0, s14
	s_nop 0
	global_load_lds_dwordx4 v241, s[100:101]
	s_waitcnt lgkmcnt(0)
	v_mfma_f32_16x16x32_bf16 v[42:45], v[142:145], v[20:23], v[42:45]
	v_mfma_f32_16x16x32_bf16 v[50:53], v[138:141], v[20:23], v[50:53]
	v_mfma_f32_16x16x32_bf16 v[38:41], v[134:137], v[20:23], v[38:41]
	v_mfma_f32_16x16x32_bf16 v[74:77], v[130:133], v[20:23], v[74:77]
	v_mfma_f32_16x16x32_bf16 v[66:69], v[126:129], v[20:23], v[66:69]
	v_mfma_f32_16x16x32_bf16 v[70:73], v[122:125], v[20:23], v[70:73]
	ds_read_b128 v[122:125], v64 offset:33792
	ds_read_b128 v[126:129], v64 offset:35840
	ds_read_b128 v[130:133], v64 offset:37888
	ds_read_b128 v[134:137], v64 offset:39936
	v_mfma_f32_16x16x32_bf16 v[60:63], v[118:121], v[20:23], v[60:63]
	ds_read_b128 v[118:121], v64 offset:41984
	ds_read_b128 v[138:141], v64 offset:44032
	ds_read_b128 v[142:145], v64 offset:46080
	ds_read_b128 v[146:149], v64 offset:48128
	v_mfma_f32_16x16x32_bf16 v[78:81], v[114:117], v[20:23], v[78:81]
	s_add_u32 s100, s10, 0x11c10100
	s_addc_u32 s101, s11, 0
	s_mov_b32 m0, s15
	s_nop 0
	global_load_lds_dwordx4 v241, s[100:101]
	s_waitcnt lgkmcnt(0)
	v_mfma_f32_16x16x32_bf16 v[82:85], v[122:125], v[20:23], v[82:85]
	v_mfma_f32_16x16x32_bf16 v[86:89], v[126:129], v[20:23], v[86:89]
	v_mfma_f32_16x16x32_bf16 v[90:93], v[130:133], v[20:23], v[90:93]
	v_mfma_f32_16x16x32_bf16 v[94:97], v[134:137], v[20:23], v[94:97]
	v_mfma_f32_16x16x32_bf16 v[98:101], v[118:121], v[20:23], v[98:101]
	ds_read_b128 v[114:117], v64 offset:31744
	ds_read_b128 v[118:121], v64 offset:29696
	ds_read_b128 v[122:125], v64 offset:27648
	ds_read_b128 v[126:129], v64 offset:25600
	v_mfma_f32_16x16x32_bf16 v[102:105], v[138:141], v[20:23], v[102:105]
	v_mfma_f32_16x16x32_bf16 v[106:109], v[142:145], v[20:23], v[106:109]
	ds_read_b128 v[130:133], v64 offset:23552
	ds_read_b128 v[134:137], v64 offset:21504
	ds_read_b128 v[138:141], v64 offset:19456
	ds_read_b128 v[142:145], v64 offset:17408
	v_mfma_f32_16x16x32_bf16 v[110:113], v[146:149], v[20:23], v[110:113]
	s_add_u32 s100, s10, 0x11c18100
	s_addc_u32 s101, s11, 0
	s_mov_b32 m0, s16
	s_nop 0
	global_load_lds_dwordx4 v241, s[100:101]
	s_waitcnt lgkmcnt(0)
	v_mfma_f32_16x16x32_bf16 v[42:45], v[142:145], v[16:19], v[42:45]
	v_mfma_f32_16x16x32_bf16 v[50:53], v[138:141], v[16:19], v[50:53]
	v_mfma_f32_16x16x32_bf16 v[38:41], v[134:137], v[16:19], v[38:41]
	v_mfma_f32_16x16x32_bf16 v[74:77], v[130:133], v[16:19], v[74:77]
	v_mfma_f32_16x16x32_bf16 v[66:69], v[126:129], v[16:19], v[66:69]
	v_mfma_f32_16x16x32_bf16 v[70:73], v[122:125], v[16:19], v[70:73]
	ds_read_b128 v[122:125], v64 offset:50176
	ds_read_b128 v[126:129], v64 offset:52224
	ds_read_b128 v[130:133], v64 offset:54272
	ds_read_b128 v[134:137], v64 offset:56320
	v_mfma_f32_16x16x32_bf16 v[60:63], v[118:121], v[16:19], v[60:63]
	ds_read_b128 v[118:121], v64 offset:58368
	ds_read_b128 v[138:141], v64 offset:60416
	ds_read_b128 v[142:145], v64 offset:62464
	ds_read_b128 v[146:149], v64 offset:64512
	v_mfma_f32_16x16x32_bf16 v[78:81], v[114:117], v[16:19], v[78:81]
	s_add_u32 s100, s10, 0x11c10180
	s_addc_u32 s101, s11, 0
	s_mov_b32 m0, s17
	s_nop 0
	global_load_lds_dwordx4 v241, s[100:101]
	s_waitcnt lgkmcnt(0)
	v_mfma_f32_16x16x32_bf16 v[82:85], v[122:125], v[16:19], v[82:85]
	v_mfma_f32_16x16x32_bf16 v[86:89], v[126:129], v[16:19], v[86:89]
	v_mfma_f32_16x16x32_bf16 v[90:93], v[130:133], v[16:19], v[90:93]
	v_mfma_f32_16x16x32_bf16 v[94:97], v[134:137], v[16:19], v[94:97]
	v_mfma_f32_16x16x32_bf16 v[98:101], v[118:121], v[16:19], v[98:101]
	v_mfma_f32_16x16x32_bf16 v[102:105], v[138:141], v[16:19], v[102:105]
	v_mfma_f32_16x16x32_bf16 v[106:109], v[142:145], v[16:19], v[106:109]
	v_mfma_f32_16x16x32_bf16 v[110:113], v[146:149], v[16:19], v[110:113]
	s_add_u32 s100, s10, 0x11c18180
	s_addc_u32 s101, s11, 0
	s_mov_b32 m0, s18
	s_nop 0
	global_load_lds_dwordx4 v241, s[100:101]
	s_waitcnt vmcnt(0)
	s_waitcnt vmcnt(0)
	s_barrier
	v_mov_b32_e32 v37, v48
	ds_read_b128 v[114:117], v37
	ds_read_b128 v[118:121], v37 offset:2048
	s_waitcnt lgkmcnt(0)
	v_mfma_f32_16x16x32_bf16 v[42:45], v[114:117], v[12:15], v[42:45]
	ds_read_b128 v[114:117], v37 offset:4096
	v_mfma_f32_16x16x32_bf16 v[50:53], v[118:121], v[12:15], v[50:53]
	ds_read_b128 v[118:121], v37 offset:6144
	s_waitcnt lgkmcnt(0)
	v_mfma_f32_16x16x32_bf16 v[38:41], v[114:117], v[12:15], v[38:41]
	ds_read_b128 v[114:117], v37 offset:8192
	v_mfma_f32_16x16x32_bf16 v[74:77], v[118:121], v[12:15], v[74:77]
	ds_read_b128 v[118:121], v37 offset:10240
	s_waitcnt lgkmcnt(0)
	v_mfma_f32_16x16x32_bf16 v[66:69], v[114:117], v[12:15], v[66:69]
	ds_read_b128 v[114:117], v37 offset:12288
	ds_read_b128 v[122:125], v37 offset:14336
	v_mfma_f32_16x16x32_bf16 v[70:73], v[118:121], v[12:15], v[70:73]
	ds_read_b128 v[118:121], v37 offset:32768
	ds_read_b128 v[126:129], v37 offset:34816
	ds_read_b128 v[130:133], v37 offset:36864
	ds_read_b128 v[134:137], v37 offset:38912
	s_waitcnt lgkmcnt(0)
	v_mfma_f32_16x16x32_bf16 v[60:63], v[114:117], v[12:15], v[60:63]
	ds_read_b128 v[114:117], v37 offset:40960
	ds_read_b128 v[138:141], v37 offset:43008
	ds_read_b128 v[142:145], v37 offset:45056
	ds_read_b128 v[146:149], v37 offset:47104
	v_mfma_f32_16x16x32_bf16 v[78:81], v[122:125], v[12:15], v[78:81]
	s_add_u32 s100, s10, 0x11c20000
	s_addc_u32 s101, s11, 0
	s_mov_b32 m0, s22
	s_nop 0
	global_load_lds_dwordx4 v241, s[100:101]
	v_mfma_f32_16x16x32_bf16 v[82:85], v[118:121], v[12:15], v[82:85]
	v_mfma_f32_16x16x32_bf16 v[86:89], v[126:129], v[12:15], v[86:89]
	v_mfma_f32_16x16x32_bf16 v[90:93], v[130:133], v[12:15], v[90:93]
	v_mfma_f32_16x16x32_bf16 v[94:97], v[134:137], v[12:15], v[94:97]
	s_waitcnt lgkmcnt(0)
	v_mfma_f32_16x16x32_bf16 v[98:101], v[114:117], v[12:15], v[98:101]
	ds_read_b128 v[114:117], v37 offset:30720
	ds_read_b128 v[118:121], v37 offset:28672
	ds_read_b128 v[122:125], v37 offset:26624
	ds_read_b128 v[126:129], v37 offset:24576
	v_mfma_f32_16x16x32_bf16 v[102:105], v[138:141], v[12:15], v[102:105]
	v_mfma_f32_16x16x32_bf16 v[106:109], v[142:145], v[12:15], v[106:109]
	ds_read_b128 v[130:133], v37 offset:22528
	ds_read_b128 v[134:137], v37 offset:20480
	ds_read_b128 v[138:141], v37 offset:18432
	ds_read_b128 v[142:145], v37 offset:16384
	v_mfma_f32_16x16x32_bf16 v[110:113], v[146:149], v[12:15], v[110:113]
	s_add_u32 s100, s10, 0x11c28000
	s_addc_u32 s101, s11, 0
	s_mov_b32 m0, s21
	s_nop 0
	global_load_lds_dwordx4 v241, s[100:101]
	s_waitcnt lgkmcnt(0)
	v_mfma_f32_16x16x32_bf16 v[42:45], v[142:145], v[8:11], v[42:45]
	v_mfma_f32_16x16x32_bf16 v[50:53], v[138:141], v[8:11], v[50:53]
	v_mfma_f32_16x16x32_bf16 v[38:41], v[134:137], v[8:11], v[38:41]
	v_mfma_f32_16x16x32_bf16 v[74:77], v[130:133], v[8:11], v[74:77]
	v_mfma_f32_16x16x32_bf16 v[66:69], v[126:129], v[8:11], v[66:69]
	v_mfma_f32_16x16x32_bf16 v[70:73], v[122:125], v[8:11], v[70:73]
	ds_read_b128 v[122:125], v37 offset:49152
	ds_read_b128 v[126:129], v37 offset:51200
	ds_read_b128 v[130:133], v37 offset:53248
	ds_read_b128 v[134:137], v37 offset:55296
	v_mfma_f32_16x16x32_bf16 v[60:63], v[118:121], v[8:11], v[60:63]
	ds_read_b128 v[118:121], v37 offset:57344
	ds_read_b128 v[138:141], v37 offset:59392
	ds_read_b128 v[142:145], v37 offset:61440
	ds_read_b128 v[146:149], v37 offset:63488
	v_mfma_f32_16x16x32_bf16 v[78:81], v[114:117], v[8:11], v[78:81]
	s_add_u32 s100, s10, 0x11c20080
	s_addc_u32 s101, s11, 0
	s_mov_b32 m0, s20
	s_nop 0
	global_load_lds_dwordx4 v241, s[100:101]
	s_waitcnt lgkmcnt(0)
	v_mfma_f32_16x16x32_bf16 v[82:85], v[122:125], v[8:11], v[82:85]
	v_mfma_f32_16x16x32_bf16 v[86:89], v[126:129], v[8:11], v[86:89]
	v_mfma_f32_16x16x32_bf16 v[90:93], v[130:133], v[8:11], v[90:93]
	v_mfma_f32_16x16x32_bf16 v[94:97], v[134:137], v[8:11], v[94:97]
	v_mfma_f32_16x16x32_bf16 v[98:101], v[118:121], v[8:11], v[98:101]
	ds_read_b128 v[114:117], v37 offset:15360
	ds_read_b128 v[118:121], v37 offset:13312
	ds_read_b128 v[122:125], v37 offset:11264
	ds_read_b128 v[126:129], v37 offset:9216
	v_mfma_f32_16x16x32_bf16 v[102:105], v[138:141], v[8:11], v[102:105]
	v_mfma_f32_16x16x32_bf16 v[106:109], v[142:145], v[8:11], v[106:109]
	ds_read_b128 v[130:133], v37 offset:7168
	ds_read_b128 v[134:137], v37 offset:5120
	ds_read_b128 v[138:141], v37 offset:3072
	ds_read_b128 v[142:145], v37 offset:1024
	v_mfma_f32_16x16x32_bf16 v[110:113], v[146:149], v[8:11], v[110:113]
	s_add_u32 s100, s10, 0x11c28080
	s_addc_u32 s101, s11, 0
	s_mov_b32 m0, s23
	s_nop 0
	global_load_lds_dwordx4 v241, s[100:101]
	s_waitcnt lgkmcnt(0)
	v_mfma_f32_16x16x32_bf16 v[42:45], v[142:145], v[4:7], v[42:45]
	v_mfma_f32_16x16x32_bf16 v[50:53], v[138:141], v[4:7], v[50:53]
	v_mfma_f32_16x16x32_bf16 v[38:41], v[134:137], v[4:7], v[38:41]
	v_mfma_f32_16x16x32_bf16 v[74:77], v[130:133], v[4:7], v[74:77]
	v_mfma_f32_16x16x32_bf16 v[66:69], v[126:129], v[4:7], v[66:69]
	v_mfma_f32_16x16x32_bf16 v[70:73], v[122:125], v[4:7], v[70:73]
	ds_read_b128 v[122:125], v37 offset:33792
	ds_read_b128 v[126:129], v37 offset:35840
	ds_read_b128 v[130:133], v37 offset:37888
	ds_read_b128 v[134:137], v37 offset:39936
	v_mfma_f32_16x16x32_bf16 v[60:63], v[118:121], v[4:7], v[60:63]
	ds_read_b128 v[118:121], v37 offset:41984
	ds_read_b128 v[138:141], v37 offset:44032
	ds_read_b128 v[142:145], v37 offset:46080
	ds_read_b128 v[146:149], v37 offset:48128
	v_mfma_f32_16x16x32_bf16 v[78:81], v[114:117], v[4:7], v[78:81]
	s_add_u32 s100, s10, 0x11c30000
	s_addc_u32 s101, s11, 0
	s_mov_b32 m0, s24
	s_nop 0
	global_load_lds_dwordx4 v241, s[100:101]
	s_waitcnt lgkmcnt(0)
	v_mfma_f32_16x16x32_bf16 v[82:85], v[122:125], v[4:7], v[82:85]
	v_mfma_f32_16x16x32_bf16 v[86:89], v[126:129], v[4:7], v[86:89]
	v_mfma_f32_16x16x32_bf16 v[90:93], v[130:133], v[4:7], v[90:93]
	v_mfma_f32_16x16x32_bf16 v[94:97], v[134:137], v[4:7], v[94:97]
	v_mfma_f32_16x16x32_bf16 v[98:101], v[118:121], v[4:7], v[98:101]
	ds_read_b128 v[114:117], v37 offset:31744
	ds_read_b128 v[118:121], v37 offset:29696
	ds_read_b128 v[122:125], v37 offset:27648
	ds_read_b128 v[126:129], v37 offset:25600
	v_mfma_f32_16x16x32_bf16 v[102:105], v[138:141], v[4:7], v[102:105]
	v_mfma_f32_16x16x32_bf16 v[106:109], v[142:145], v[4:7], v[106:109]
	ds_read_b128 v[130:133], v37 offset:23552
	ds_read_b128 v[134:137], v37 offset:21504
	ds_read_b128 v[138:141], v37 offset:19456
	ds_read_b128 v[142:145], v37 offset:17408
	v_mfma_f32_16x16x32_bf16 v[110:113], v[146:149], v[4:7], v[110:113]
	s_add_u32 s100, s10, 0x11c38000
	s_addc_u32 s101, s11, 0
	s_mov_b32 m0, s25
	s_nop 0
	global_load_lds_dwordx4 v241, s[100:101]
	s_waitcnt lgkmcnt(0)
	v_mfma_f32_16x16x32_bf16 v[42:45], v[142:145], v[0:3], v[42:45]
	v_mfma_f32_16x16x32_bf16 v[50:53], v[138:141], v[0:3], v[50:53]
	v_mfma_f32_16x16x32_bf16 v[38:41], v[134:137], v[0:3], v[38:41]
	v_mfma_f32_16x16x32_bf16 v[74:77], v[130:133], v[0:3], v[74:77]
	v_mfma_f32_16x16x32_bf16 v[66:69], v[126:129], v[0:3], v[66:69]
	v_mfma_f32_16x16x32_bf16 v[70:73], v[122:125], v[0:3], v[70:73]
	ds_read_b128 v[122:125], v37 offset:50176
	ds_read_b128 v[126:129], v37 offset:52224
	ds_read_b128 v[130:133], v37 offset:54272
	ds_read_b128 v[134:137], v37 offset:56320
	v_mfma_f32_16x16x32_bf16 v[60:63], v[118:121], v[0:3], v[60:63]
	ds_read_b128 v[118:121], v37 offset:58368
	ds_read_b128 v[138:141], v37 offset:60416
	ds_read_b128 v[142:145], v37 offset:62464
	ds_read_b128 v[146:149], v37 offset:64512
	v_mfma_f32_16x16x32_bf16 v[78:81], v[114:117], v[0:3], v[78:81]
	s_add_u32 s100, s10, 0x11c30080
	s_addc_u32 s101, s11, 0
	s_mov_b32 m0, s26
	s_nop 0
	global_load_lds_dwordx4 v241, s[100:101]
	s_waitcnt lgkmcnt(0)
	v_mfma_f32_16x16x32_bf16 v[82:85], v[122:125], v[0:3], v[82:85]
	v_mfma_f32_16x16x32_bf16 v[86:89], v[126:129], v[0:3], v[86:89]
	v_mfma_f32_16x16x32_bf16 v[90:93], v[130:133], v[0:3], v[90:93]
	v_mfma_f32_16x16x32_bf16 v[94:97], v[134:137], v[0:3], v[94:97]
	v_mfma_f32_16x16x32_bf16 v[98:101], v[118:121], v[0:3], v[98:101]
	v_mfma_f32_16x16x32_bf16 v[102:105], v[138:141], v[0:3], v[102:105]
	v_mfma_f32_16x16x32_bf16 v[106:109], v[142:145], v[0:3], v[106:109]
	v_mfma_f32_16x16x32_bf16 v[110:113], v[146:149], v[0:3], v[110:113]
	s_add_u32 s100, s10, 0x11c38080
	s_addc_u32 s101, s11, 0
	s_mov_b32 m0, s27
	s_nop 0
	global_load_lds_dwordx4 v241, s[100:101]
	s_mov_b32 s0, 0x1000000
	v_add_co_u32_e32 v34, vcc, s0, v34
	v_mul_f32_e32 v37, v36, v42
	v_mul_f32_e32 v42, v36, v43
	v_mul_f32_e32 v43, v36, v45
	v_addc_co_u32_e32 v35, vcc, 0, v35, vcc
	v_cvt_pk_bf16_f32 v42, v37, v42
	v_mul_f32_e32 v37, v36, v44
	v_cvt_pk_bf16_f32 v43, v37, v43
	global_store_dwordx2 v[34:35], v[42:43], off
	v_mul_f32_e32 v34, v36, v50
	v_mul_f32_e32 v35, v36, v51
	v_cvt_pk_bf16_f32 v34, v34, v35
	v_mul_f32_e32 v35, v36, v52
	v_mul_f32_e32 v37, v36, v53
	v_cvt_pk_bf16_f32 v35, v35, v37
	global_store_dwordx2 v[32:33], v[34:35], off offset:32
	v_mul_f32_e32 v34, v36, v38
	v_mul_f32_e32 v35, v36, v39
	v_cvt_pk_bf16_f32 v34, v34, v35
	v_mul_f32_e32 v35, v36, v40
	v_mul_f32_e32 v37, v36, v41
	v_cvt_pk_bf16_f32 v35, v35, v37
	global_store_dwordx2 v[32:33], v[34:35], off offset:64
	v_mul_f32_e32 v34, v36, v74
	v_mul_f32_e32 v35, v36, v75
	v_cvt_pk_bf16_f32 v34, v34, v35
	v_mul_f32_e32 v35, v36, v76
	v_mul_f32_e32 v37, v36, v77
	v_cvt_pk_bf16_f32 v35, v35, v37
	global_store_dwordx2 v[32:33], v[34:35], off offset:96
	v_mul_f32_e32 v34, v36, v66
	v_mul_f32_e32 v35, v36, v67
	v_cvt_pk_bf16_f32 v34, v34, v35
	v_mul_f32_e32 v35, v36, v68
	v_mul_f32_e32 v37, v36, v69
	v_cvt_pk_bf16_f32 v35, v35, v37
	global_store_dwordx2 v[32:33], v[34:35], off offset:128
	v_mul_f32_e32 v34, v36, v70
	v_mul_f32_e32 v35, v36, v71
	v_cvt_pk_bf16_f32 v34, v34, v35
	v_mul_f32_e32 v35, v36, v72
	v_mul_f32_e32 v37, v36, v73
	v_cvt_pk_bf16_f32 v35, v35, v37
	global_store_dwordx2 v[32:33], v[34:35], off offset:160
	v_mul_f32_e32 v34, v36, v60
	v_mul_f32_e32 v35, v36, v61
	v_cvt_pk_bf16_f32 v34, v34, v35
	v_mul_f32_e32 v35, v36, v62
	v_mul_f32_e32 v37, v36, v63
	v_cvt_pk_bf16_f32 v35, v35, v37
	global_store_dwordx2 v[32:33], v[34:35], off offset:192
	v_mul_f32_e32 v34, v36, v78
	v_mul_f32_e32 v35, v36, v79
	v_cvt_pk_bf16_f32 v34, v34, v35
	v_mul_f32_e32 v35, v36, v80
	v_mul_f32_e32 v37, v36, v81
	v_cvt_pk_bf16_f32 v35, v35, v37
	global_store_dwordx2 v[32:33], v[34:35], off offset:224
	v_mul_f32_e32 v34, v36, v82
	v_mul_f32_e32 v35, v36, v83
	v_cvt_pk_bf16_f32 v34, v34, v35
	v_mul_f32_e32 v35, v36, v84
	v_mul_f32_e32 v37, v36, v85
	v_cvt_pk_bf16_f32 v35, v35, v37
	global_store_dwordx2 v[32:33], v[34:35], off offset:256
	v_mul_f32_e32 v34, v36, v86
	v_mul_f32_e32 v35, v36, v87
	v_cvt_pk_bf16_f32 v34, v34, v35
	v_mul_f32_e32 v35, v36, v88
	v_mul_f32_e32 v37, v36, v89
	v_cvt_pk_bf16_f32 v35, v35, v37
	global_store_dwordx2 v[32:33], v[34:35], off offset:288
	v_mul_f32_e32 v34, v36, v90
	v_mul_f32_e32 v35, v36, v91
	v_cvt_pk_bf16_f32 v34, v34, v35
	v_mul_f32_e32 v35, v36, v92
	v_mul_f32_e32 v37, v36, v93
	v_cvt_pk_bf16_f32 v35, v35, v37
	global_store_dwordx2 v[32:33], v[34:35], off offset:320
	v_mul_f32_e32 v34, v36, v94
	v_mul_f32_e32 v35, v36, v95
	v_cvt_pk_bf16_f32 v34, v34, v35
	v_mul_f32_e32 v35, v36, v96
	v_mul_f32_e32 v37, v36, v97
	v_cvt_pk_bf16_f32 v35, v35, v37
	global_store_dwordx2 v[32:33], v[34:35], off offset:352
	v_mul_f32_e32 v34, v36, v98
	v_mul_f32_e32 v35, v36, v99
	v_cvt_pk_bf16_f32 v34, v34, v35
	v_mul_f32_e32 v35, v36, v100
	v_mul_f32_e32 v37, v36, v101
	v_cvt_pk_bf16_f32 v35, v35, v37
	global_store_dwordx2 v[32:33], v[34:35], off offset:384
	v_mul_f32_e32 v34, v36, v102
	v_mul_f32_e32 v35, v36, v103
	v_cvt_pk_bf16_f32 v34, v34, v35
	v_mul_f32_e32 v35, v36, v104
	v_mul_f32_e32 v37, v36, v105
	v_cvt_pk_bf16_f32 v35, v35, v37
	global_store_dwordx2 v[32:33], v[34:35], off offset:416
	v_mul_f32_e32 v34, v36, v106
	v_mul_f32_e32 v35, v36, v107
	v_cvt_pk_bf16_f32 v34, v34, v35
	v_mul_f32_e32 v35, v36, v108
	v_mul_f32_e32 v37, v36, v109
	v_cvt_pk_bf16_f32 v35, v35, v37
	global_store_dwordx2 v[32:33], v[34:35], off offset:448
	v_mul_f32_e32 v34, v36, v110
	v_mul_f32_e32 v35, v36, v111
	v_cvt_pk_bf16_f32 v34, v34, v35
	v_mul_f32_e32 v35, v36, v112
	v_mul_f32_e32 v37, v36, v113
	v_cvt_pk_bf16_f32 v35, v35, v37
	global_store_dwordx2 v[32:33], v[34:35], off offset:480
	s_waitcnt vmcnt(0)
	s_waitcnt vmcnt(0)
	s_barrier
	ds_read_b128 v[38:41], v65
	ds_read_b128 v[42:45], v65 offset:2048
	ds_read_b128 v[50:53], v65 offset:4096
	ds_read_b128 v[54:57], v65 offset:6144
	ds_read_b128 v[58:61], v65 offset:8192
	ds_read_b128 v[66:69], v65 offset:10240
	ds_read_b128 v[70:73], v65 offset:12288
	ds_read_b128 v[74:77], v65 offset:14336
	ds_read_b128 v[78:81], v65 offset:32768
	ds_read_b128 v[82:85], v65 offset:34816
	ds_read_b128 v[86:89], v65 offset:36864
	ds_read_b128 v[90:93], v65 offset:38912
	ds_read_b128 v[94:97], v65 offset:40960
	ds_read_b128 v[98:101], v65 offset:43008
	ds_read_b128 v[102:105], v65 offset:45056
	ds_read_b128 v[106:109], v65 offset:47104
	s_waitcnt lgkmcnt(0)
	v_mfma_f32_16x16x32_bf16 v[38:41], v[38:41], v[28:31], 0
	v_mfma_f32_16x16x32_bf16 v[42:45], v[42:45], v[28:31], 0
	v_mfma_f32_16x16x32_bf16 v[50:53], v[50:53], v[28:31], 0
	v_mfma_f32_16x16x32_bf16 v[54:57], v[54:57], v[28:31], 0
	v_mfma_f32_16x16x32_bf16 v[58:61], v[58:61], v[28:31], 0
	v_mfma_f32_16x16x32_bf16 v[66:69], v[66:69], v[28:31], 0
	v_mfma_f32_16x16x32_bf16 v[70:73], v[70:73], v[28:31], 0
	v_mfma_f32_16x16x32_bf16 v[74:77], v[74:77], v[28:31], 0
	s_add_u32 s100, s10, 0x11c20100
	s_addc_u32 s101, s11, 0
	s_mov_b32 m0, s19
	s_nop 0
	global_load_lds_dwordx4 v241, s[100:101]
	ds_read_b128 v[110:113], v65 offset:30720
	ds_read_b128 v[114:117], v65 offset:28672
	ds_read_b128 v[118:121], v65 offset:26624
	ds_read_b128 v[122:125], v65 offset:24576
	ds_read_b128 v[126:129], v65 offset:22528
	ds_read_b128 v[130:133], v65 offset:20480
	ds_read_b128 v[134:137], v65 offset:18432
	ds_read_b128 v[138:141], v65 offset:16384
	v_mfma_f32_16x16x32_bf16 v[78:81], v[78:81], v[28:31], 0
	v_mfma_f32_16x16x32_bf16 v[82:85], v[82:85], v[28:31], 0
	v_mfma_f32_16x16x32_bf16 v[86:89], v[86:89], v[28:31], 0
	v_mfma_f32_16x16x32_bf16 v[90:93], v[90:93], v[28:31], 0
	v_mfma_f32_16x16x32_bf16 v[94:97], v[94:97], v[28:31], 0
	v_mfma_f32_16x16x32_bf16 v[98:101], v[98:101], v[28:31], 0
	v_mfma_f32_16x16x32_bf16 v[102:105], v[102:105], v[28:31], 0
	v_mfma_f32_16x16x32_bf16 v[28:31], v[106:109], v[28:31], 0
	s_add_u32 s100, s10, 0x11c28100
	s_addc_u32 s101, s11, 0
	s_mov_b32 m0, s13
	s_nop 0
	global_load_lds_dwordx4 v241, s[100:101]
	s_waitcnt lgkmcnt(0)
	v_mfma_f32_16x16x32_bf16 v[38:41], v[138:141], v[24:27], v[38:41]
	v_mfma_f32_16x16x32_bf16 v[42:45], v[134:137], v[24:27], v[42:45]
	v_mfma_f32_16x16x32_bf16 v[50:53], v[130:133], v[24:27], v[50:53]
	v_mfma_f32_16x16x32_bf16 v[54:57], v[126:129], v[24:27], v[54:57]
	v_mfma_f32_16x16x32_bf16 v[58:61], v[122:125], v[24:27], v[58:61]
	v_mfma_f32_16x16x32_bf16 v[66:69], v[118:121], v[24:27], v[66:69]
	ds_read_b128 v[106:109], v65 offset:49152
	ds_read_b128 v[118:121], v65 offset:51200
	ds_read_b128 v[122:125], v65 offset:53248
	ds_read_b128 v[126:129], v65 offset:55296
	v_mfma_f32_16x16x32_bf16 v[70:73], v[114:117], v[24:27], v[70:73]
	ds_read_b128 v[114:117], v65 offset:57344
	ds_read_b128 v[130:133], v65 offset:59392
	ds_read_b128 v[134:137], v65 offset:61440
	ds_read_b128 v[138:141], v65 offset:63488
	v_mfma_f32_16x16x32_bf16 v[74:77], v[110:113], v[24:27], v[74:77]
	s_add_u32 s100, s10, 0x11c20180
	s_addc_u32 s101, s11, 0
	s_mov_b32 m0, s12
	s_nop 0
	global_load_lds_dwordx4 v241, s[100:101]
	s_waitcnt lgkmcnt(0)
	v_mfma_f32_16x16x32_bf16 v[78:81], v[106:109], v[24:27], v[78:81]
	v_mfma_f32_16x16x32_bf16 v[82:85], v[118:121], v[24:27], v[82:85]
	v_mfma_f32_16x16x32_bf16 v[86:89], v[122:125], v[24:27], v[86:89]
	v_mfma_f32_16x16x32_bf16 v[90:93], v[126:129], v[24:27], v[90:93]
	v_mfma_f32_16x16x32_bf16 v[94:97], v[114:117], v[24:27], v[94:97]
	ds_read_b128 v[106:109], v65 offset:15360
	ds_read_b128 v[110:113], v65 offset:13312
	ds_read_b128 v[114:117], v65 offset:11264
	ds_read_b128 v[118:121], v65 offset:9216
	v_mfma_f32_16x16x32_bf16 v[98:101], v[130:133], v[24:27], v[98:101]
	v_mfma_f32_16x16x32_bf16 v[102:105], v[134:137], v[24:27], v[102:105]
	ds_read_b128 v[122:125], v65 offset:7168
	ds_read_b128 v[126:129], v65 offset:5120
	ds_read_b128 v[130:133], v65 offset:3072
	ds_read_b128 v[134:137], v65 offset:1024
	v_mfma_f32_16x16x32_bf16 v[24:27], v[138:141], v[24:27], v[28:31]
	s_add_u32 s100, s10, 0x11c28180
	s_addc_u32 s101, s11, 0
	s_mov_b32 m0, s14
	s_nop 0
	global_load_lds_dwordx4 v241, s[100:101]
	s_waitcnt lgkmcnt(0)
	v_mfma_f32_16x16x32_bf16 v[28:31], v[134:137], v[20:23], v[38:41]
	v_mfma_f32_16x16x32_bf16 v[38:41], v[130:133], v[20:23], v[42:45]
	v_mfma_f32_16x16x32_bf16 v[42:45], v[126:129], v[20:23], v[50:53]
	v_mfma_f32_16x16x32_bf16 v[50:53], v[122:125], v[20:23], v[54:57]
	v_mfma_f32_16x16x32_bf16 v[54:57], v[118:121], v[20:23], v[58:61]
	v_mfma_f32_16x16x32_bf16 v[58:61], v[114:117], v[20:23], v[66:69]
	s_nop 2
	ds_read_b128 v[66:69], v65 offset:33792
	ds_read_b128 v[114:117], v65 offset:35840
	ds_read_b128 v[118:121], v65 offset:37888
	ds_read_b128 v[122:125], v65 offset:39936
	v_mfma_f32_16x16x32_bf16 v[70:73], v[110:113], v[20:23], v[70:73]
	ds_read_b128 v[110:113], v65 offset:41984
	ds_read_b128 v[126:129], v65 offset:44032
	ds_read_b128 v[130:133], v65 offset:46080
	ds_read_b128 v[134:137], v65 offset:48128
	v_mfma_f32_16x16x32_bf16 v[74:77], v[106:109], v[20:23], v[74:77]
	s_add_u32 s100, s10, 0x11c30100
	s_addc_u32 s101, s11, 0
	s_mov_b32 m0, s15
	s_nop 0
	global_load_lds_dwordx4 v241, s[100:101]
	s_waitcnt lgkmcnt(0)
	v_mfma_f32_16x16x32_bf16 v[66:69], v[66:69], v[20:23], v[78:81]
	v_mfma_f32_16x16x32_bf16 v[78:81], v[114:117], v[20:23], v[82:85]
	v_mfma_f32_16x16x32_bf16 v[82:85], v[118:121], v[20:23], v[86:89]
	v_mfma_f32_16x16x32_bf16 v[86:89], v[122:125], v[20:23], v[90:93]
	v_mfma_f32_16x16x32_bf16 v[90:93], v[110:113], v[20:23], v[94:97]
	v_mfma_f32_16x16x32_bf16 v[94:97], v[126:129], v[20:23], v[98:101]
	s_nop 2
	ds_read_b128 v[98:101], v65 offset:31744
	ds_read_b128 v[106:109], v65 offset:29696
	ds_read_b128 v[110:113], v65 offset:27648
	ds_read_b128 v[114:117], v65 offset:25600
	v_mfma_f32_16x16x32_bf16 v[102:105], v[130:133], v[20:23], v[102:105]
	ds_read_b128 v[118:121], v65 offset:23552
	ds_read_b128 v[122:125], v65 offset:21504
	ds_read_b128 v[126:129], v65 offset:19456
	ds_read_b128 v[130:133], v65 offset:17408
	v_mfma_f32_16x16x32_bf16 v[20:23], v[134:137], v[20:23], v[24:27]
	s_add_u32 s100, s10, 0x11c38100
	s_addc_u32 s101, s11, 0
	s_mov_b32 m0, s16
	s_nop 0
	global_load_lds_dwordx4 v241, s[100:101]
	s_waitcnt lgkmcnt(0)
	v_mfma_f32_16x16x32_bf16 v[24:27], v[130:133], v[16:19], v[28:31]
	v_mfma_f32_16x16x32_bf16 v[28:31], v[126:129], v[16:19], v[38:41]
	v_mfma_f32_16x16x32_bf16 v[38:41], v[122:125], v[16:19], v[42:45]
	v_mfma_f32_16x16x32_bf16 v[42:45], v[118:121], v[16:19], v[50:53]
	v_mfma_f32_16x16x32_bf16 v[50:53], v[114:117], v[16:19], v[54:57]
	v_mfma_f32_16x16x32_bf16 v[54:57], v[110:113], v[16:19], v[58:61]
	s_nop 2
	ds_read_b128 v[58:61], v65 offset:50176
	ds_read_b128 v[110:113], v65 offset:52224
	ds_read_b128 v[114:117], v65 offset:54272
	ds_read_b128 v[118:121], v65 offset:56320
	v_mfma_f32_16x16x32_bf16 v[70:73], v[106:109], v[16:19], v[70:73]
	ds_read_b128 v[106:109], v65 offset:58368
	ds_read_b128 v[122:125], v65 offset:60416
	ds_read_b128 v[126:129], v65 offset:62464
	ds_read_b128 v[62:65], v65 offset:64512
	v_mfma_f32_16x16x32_bf16 v[74:77], v[98:101], v[16:19], v[74:77]
	s_add_u32 s100, s10, 0x11c30180
	s_addc_u32 s101, s11, 0
	s_mov_b32 m0, s17
	s_nop 0
	global_load_lds_dwordx4 v241, s[100:101]
	s_waitcnt lgkmcnt(0)
	v_mfma_f32_16x16x32_bf16 v[58:61], v[58:61], v[16:19], v[66:69]
	v_mfma_f32_16x16x32_bf16 v[66:69], v[110:113], v[16:19], v[78:81]
	v_mfma_f32_16x16x32_bf16 v[78:81], v[114:117], v[16:19], v[82:85]
	v_mfma_f32_16x16x32_bf16 v[82:85], v[118:121], v[16:19], v[86:89]
	v_mfma_f32_16x16x32_bf16 v[86:89], v[106:109], v[16:19], v[90:93]
	v_mfma_f32_16x16x32_bf16 v[90:93], v[122:125], v[16:19], v[94:97]
	v_mfma_f32_16x16x32_bf16 v[94:97], v[126:129], v[16:19], v[102:105]
	v_mfma_f32_16x16x32_bf16 v[16:19], v[62:65], v[16:19], v[20:23]
	s_add_u32 s100, s10, 0x11c38180
	s_addc_u32 s101, s11, 0
	s_mov_b32 m0, s18
	s_nop 0
	global_load_lds_dwordx4 v241, s[100:101]
	s_waitcnt vmcnt(0)
	s_waitcnt vmcnt(0)
	s_barrier
	s_nop 0
	ds_read_b128 v[20:23], v48
	ds_read_b128 v[62:65], v48 offset:2048
	s_waitcnt lgkmcnt(1)
	v_mfma_f32_16x16x32_bf16 v[20:23], v[20:23], v[12:15], v[24:27]
	s_nop 2
	ds_read_b128 v[24:27], v48 offset:4096
	s_waitcnt lgkmcnt(1)
	v_mfma_f32_16x16x32_bf16 v[28:31], v[62:65], v[12:15], v[28:31]
	ds_read_b128 v[62:65], v48 offset:6144
	s_waitcnt lgkmcnt(1)
	v_mfma_f32_16x16x32_bf16 v[24:27], v[24:27], v[12:15], v[38:41]
	s_nop 2
	ds_read_b128 v[38:41], v48 offset:8192
	s_waitcnt lgkmcnt(1)
	v_mfma_f32_16x16x32_bf16 v[42:45], v[62:65], v[12:15], v[42:45]
	ds_read_b128 v[62:65], v48 offset:10240
	s_waitcnt lgkmcnt(1)
	v_mfma_f32_16x16x32_bf16 v[38:41], v[38:41], v[12:15], v[50:53]
	s_nop 2
	ds_read_b128 v[50:53], v48 offset:12288
	ds_read_b128 v[98:101], v48 offset:14336
	s_waitcnt lgkmcnt(2)
	v_mfma_f32_16x16x32_bf16 v[54:57], v[62:65], v[12:15], v[54:57]
	ds_read_b128 v[62:65], v48 offset:32768
	ds_read_b128 v[102:105], v48 offset:34816
	ds_read_b128 v[106:109], v48 offset:36864
	ds_read_b128 v[110:113], v48 offset:38912
	s_waitcnt lgkmcnt(5)
	v_mfma_f32_16x16x32_bf16 v[50:53], v[50:53], v[12:15], v[70:73]
	s_nop 2
	ds_read_b128 v[70:73], v48 offset:40960
	ds_read_b128 v[114:117], v48 offset:43008
	ds_read_b128 v[118:121], v48 offset:45056
	ds_read_b128 v[122:125], v48 offset:47104
	s_waitcnt lgkmcnt(8)
	v_mfma_f32_16x16x32_bf16 v[74:77], v[98:101], v[12:15], v[74:77]
	s_waitcnt lgkmcnt(7)
	v_mfma_f32_16x16x32_bf16 v[58:61], v[62:65], v[12:15], v[58:61]
	s_waitcnt lgkmcnt(6)
	v_mfma_f32_16x16x32_bf16 v[62:65], v[102:105], v[12:15], v[66:69]
	s_waitcnt lgkmcnt(5)
	v_mfma_f32_16x16x32_bf16 v[66:69], v[106:109], v[12:15], v[78:81]
	s_waitcnt lgkmcnt(4)
	v_mfma_f32_16x16x32_bf16 v[78:81], v[110:113], v[12:15], v[82:85]
	s_waitcnt lgkmcnt(3)
	v_mfma_f32_16x16x32_bf16 v[70:73], v[70:73], v[12:15], v[86:89]
	s_waitcnt lgkmcnt(2)
	v_mfma_f32_16x16x32_bf16 v[82:85], v[114:117], v[12:15], v[90:93]
	s_nop 0
	ds_read_b128 v[86:89], v48 offset:30720
	s_nop 0
	ds_read_b128 v[90:93], v48 offset:28672
	ds_read_b128 v[98:101], v48 offset:26624
	ds_read_b128 v[102:105], v48 offset:24576
	s_waitcnt lgkmcnt(5)
	v_mfma_f32_16x16x32_bf16 v[94:97], v[118:121], v[12:15], v[94:97]
	ds_read_b128 v[106:109], v48 offset:22528
	ds_read_b128 v[110:113], v48 offset:20480
	ds_read_b128 v[114:117], v48 offset:18432
	ds_read_b128 v[118:121], v48 offset:16384
	s_waitcnt lgkmcnt(8)
	v_mfma_f32_16x16x32_bf16 v[12:15], v[122:125], v[12:15], v[16:19]
	s_waitcnt lgkmcnt(0)
	v_mfma_f32_16x16x32_bf16 v[16:19], v[118:121], v[8:11], v[20:23]
	v_mfma_f32_16x16x32_bf16 v[20:23], v[114:117], v[8:11], v[28:31]
	v_mfma_f32_16x16x32_bf16 v[24:27], v[110:113], v[8:11], v[24:27]
	v_mfma_f32_16x16x32_bf16 v[28:31], v[106:109], v[8:11], v[42:45]
	v_mfma_f32_16x16x32_bf16 v[38:41], v[102:105], v[8:11], v[38:41]
	v_mfma_f32_16x16x32_bf16 v[42:45], v[98:101], v[8:11], v[54:57]
	s_nop 2
	ds_read_b128 v[54:57], v48 offset:49152
	ds_read_b128 v[98:101], v48 offset:51200
	ds_read_b128 v[102:105], v48 offset:53248
	ds_read_b128 v[106:109], v48 offset:55296
	v_mfma_f32_16x16x32_bf16 v[50:53], v[90:93], v[8:11], v[50:53]
	ds_read_b128 v[90:93], v48 offset:57344
	ds_read_b128 v[110:113], v48 offset:59392
	ds_read_b128 v[114:117], v48 offset:61440
	ds_read_b128 v[118:121], v48 offset:63488
	v_mfma_f32_16x16x32_bf16 v[74:77], v[86:89], v[8:11], v[74:77]
	s_waitcnt lgkmcnt(7)
	v_mfma_f32_16x16x32_bf16 v[54:57], v[54:57], v[8:11], v[58:61]
	s_waitcnt lgkmcnt(6)
	v_mfma_f32_16x16x32_bf16 v[58:61], v[98:101], v[8:11], v[62:65]
	s_waitcnt lgkmcnt(5)
	v_mfma_f32_16x16x32_bf16 v[62:65], v[102:105], v[8:11], v[66:69]
	s_waitcnt lgkmcnt(4)
	v_mfma_f32_16x16x32_bf16 v[66:69], v[106:109], v[8:11], v[78:81]
	s_waitcnt lgkmcnt(3)
	v_mfma_f32_16x16x32_bf16 v[70:73], v[90:93], v[8:11], v[70:73]
	s_waitcnt lgkmcnt(2)
	v_mfma_f32_16x16x32_bf16 v[78:81], v[110:113], v[8:11], v[82:85]
	s_nop 2
	ds_read_b128 v[82:85], v48 offset:15360
	ds_read_b128 v[86:89], v48 offset:13312
	ds_read_b128 v[90:93], v48 offset:11264
	ds_read_b128 v[98:101], v48 offset:9216
	s_waitcnt lgkmcnt(5)
	v_mfma_f32_16x16x32_bf16 v[94:97], v[114:117], v[8:11], v[94:97]
	ds_read_b128 v[102:105], v48 offset:7168
	ds_read_b128 v[106:109], v48 offset:5120
	ds_read_b128 v[110:113], v48 offset:3072
	ds_read_b128 v[114:117], v48 offset:1024
	s_waitcnt lgkmcnt(8)
	v_mfma_f32_16x16x32_bf16 v[8:11], v[118:121], v[8:11], v[12:15]
	s_waitcnt lgkmcnt(0)
	v_mfma_f32_16x16x32_bf16 v[12:15], v[114:117], v[4:7], v[16:19]
	v_mfma_f32_16x16x32_bf16 v[16:19], v[110:113], v[4:7], v[20:23]
	v_mfma_f32_16x16x32_bf16 v[20:23], v[106:109], v[4:7], v[24:27]
	v_mfma_f32_16x16x32_bf16 v[24:27], v[102:105], v[4:7], v[28:31]
	v_mfma_f32_16x16x32_bf16 v[28:31], v[98:101], v[4:7], v[38:41]
	v_mfma_f32_16x16x32_bf16 v[38:41], v[90:93], v[4:7], v[42:45]
	s_nop 2
	ds_read_b128 v[42:45], v48 offset:33792
	ds_read_b128 v[90:93], v48 offset:35840
	ds_read_b128 v[98:101], v48 offset:37888
	ds_read_b128 v[102:105], v48 offset:39936
	v_mfma_f32_16x16x32_bf16 v[50:53], v[86:89], v[4:7], v[50:53]
	ds_read_b128 v[86:89], v48 offset:41984
	ds_read_b128 v[106:109], v48 offset:44032
	ds_read_b128 v[110:113], v48 offset:46080
	ds_read_b128 v[114:117], v48 offset:48128
	v_mfma_f32_16x16x32_bf16 v[74:77], v[82:85], v[4:7], v[74:77]
	s_waitcnt lgkmcnt(7)
	v_mfma_f32_16x16x32_bf16 v[42:45], v[42:45], v[4:7], v[54:57]
	s_waitcnt lgkmcnt(6)
	v_mfma_f32_16x16x32_bf16 v[54:57], v[90:93], v[4:7], v[58:61]
	s_waitcnt lgkmcnt(5)
	v_mfma_f32_16x16x32_bf16 v[58:61], v[98:101], v[4:7], v[62:65]
	s_waitcnt lgkmcnt(4)
	v_mfma_f32_16x16x32_bf16 v[62:65], v[102:105], v[4:7], v[66:69]
	s_waitcnt lgkmcnt(3)
	v_mfma_f32_16x16x32_bf16 v[66:69], v[86:89], v[4:7], v[70:73]
	s_waitcnt lgkmcnt(2)
	v_mfma_f32_16x16x32_bf16 v[70:73], v[106:109], v[4:7], v[78:81]
	s_nop 2
	ds_read_b128 v[78:81], v48 offset:31744
	ds_read_b128 v[82:85], v48 offset:29696
	ds_read_b128 v[86:89], v48 offset:27648
	ds_read_b128 v[90:93], v48 offset:25600
	s_waitcnt lgkmcnt(5)
	v_mfma_f32_16x16x32_bf16 v[94:97], v[110:113], v[4:7], v[94:97]
	ds_read_b128 v[98:101], v48 offset:23552
	ds_read_b128 v[102:105], v48 offset:21504
	ds_read_b128 v[106:109], v48 offset:19456
	ds_read_b128 v[110:113], v48 offset:17408
	s_waitcnt lgkmcnt(8)
	v_mfma_f32_16x16x32_bf16 v[4:7], v[114:117], v[4:7], v[8:11]
	s_waitcnt lgkmcnt(0)
	v_mfma_f32_16x16x32_bf16 v[8:11], v[110:113], v[0:3], v[12:15]
	v_mfma_f32_16x16x32_bf16 v[12:15], v[106:109], v[0:3], v[16:19]
	v_mfma_f32_16x16x32_bf16 v[16:19], v[102:105], v[0:3], v[20:23]
	v_mfma_f32_16x16x32_bf16 v[20:23], v[98:101], v[0:3], v[24:27]
	v_mfma_f32_16x16x32_bf16 v[24:27], v[90:93], v[0:3], v[28:31]
	v_mfma_f32_16x16x32_bf16 v[28:31], v[86:89], v[0:3], v[38:41]
	s_nop 2
	ds_read_b128 v[38:41], v48 offset:50176
	ds_read_b128 v[86:89], v48 offset:52224
	ds_read_b128 v[90:93], v48 offset:54272
	ds_read_b128 v[98:101], v48 offset:56320
	v_mfma_f32_16x16x32_bf16 v[50:53], v[82:85], v[0:3], v[50:53]
	ds_read_b128 v[82:85], v48 offset:58368
	ds_read_b128 v[102:105], v48 offset:60416
	ds_read_b128 v[106:109], v48 offset:62464
	ds_read_b128 v[46:49], v48 offset:64512
	v_mfma_f32_16x16x32_bf16 v[74:77], v[78:81], v[0:3], v[74:77]
	s_waitcnt lgkmcnt(7)
	v_mfma_f32_16x16x32_bf16 v[38:41], v[38:41], v[0:3], v[42:45]
	s_waitcnt lgkmcnt(6)
	v_mfma_f32_16x16x32_bf16 v[42:45], v[86:89], v[0:3], v[54:57]
	s_waitcnt lgkmcnt(5)
	v_mfma_f32_16x16x32_bf16 v[54:57], v[90:93], v[0:3], v[58:61]
	s_waitcnt lgkmcnt(4)
	v_mfma_f32_16x16x32_bf16 v[58:61], v[98:101], v[0:3], v[62:65]
	s_waitcnt lgkmcnt(3)
	v_mfma_f32_16x16x32_bf16 v[62:65], v[82:85], v[0:3], v[66:69]
	s_waitcnt lgkmcnt(2)
	v_mfma_f32_16x16x32_bf16 v[66:69], v[102:105], v[0:3], v[70:73]
	s_waitcnt lgkmcnt(1)
	v_mfma_f32_16x16x32_bf16 v[70:73], v[106:109], v[0:3], v[94:97]
	s_waitcnt lgkmcnt(0)
	v_mfma_f32_16x16x32_bf16 v[0:3], v[46:49], v[0:3], v[4:7]
	s_nop 2
	v_mul_f32_e32 v4, v36, v8
	v_mul_f32_e32 v5, v36, v9
	v_cvt_pk_bf16_f32 v4, v4, v5
	v_mul_f32_e32 v5, v36, v10
	v_mul_f32_e32 v6, v36, v11
	v_cvt_pk_bf16_f32 v5, v5, v6
	global_store_dwordx2 v[32:33], v[4:5], off offset:512
	v_mul_f32_e32 v4, v36, v12
	v_mul_f32_e32 v5, v36, v13
	v_cvt_pk_bf16_f32 v4, v4, v5
	v_mul_f32_e32 v5, v36, v14
	v_mul_f32_e32 v6, v36, v15
	v_cvt_pk_bf16_f32 v5, v5, v6
	global_store_dwordx2 v[32:33], v[4:5], off offset:544
	v_mul_f32_e32 v4, v36, v16
	v_mul_f32_e32 v5, v36, v17
	v_cvt_pk_bf16_f32 v4, v4, v5
	v_mul_f32_e32 v5, v36, v18
	v_mul_f32_e32 v6, v36, v19
	v_cvt_pk_bf16_f32 v5, v5, v6
	global_store_dwordx2 v[32:33], v[4:5], off offset:576
	v_mul_f32_e32 v4, v36, v20
	v_mul_f32_e32 v5, v36, v21
	v_cvt_pk_bf16_f32 v4, v4, v5
	v_mul_f32_e32 v5, v36, v22
	v_mul_f32_e32 v6, v36, v23
	v_cvt_pk_bf16_f32 v5, v5, v6
	global_store_dwordx2 v[32:33], v[4:5], off offset:608
	v_mul_f32_e32 v4, v36, v24
	v_mul_f32_e32 v5, v36, v25
	v_cvt_pk_bf16_f32 v4, v4, v5
	v_mul_f32_e32 v5, v36, v26
	v_mul_f32_e32 v6, v36, v27
	v_cvt_pk_bf16_f32 v5, v5, v6
	global_store_dwordx2 v[32:33], v[4:5], off offset:640
	v_mul_f32_e32 v4, v36, v28
	v_mul_f32_e32 v5, v36, v29
	v_cvt_pk_bf16_f32 v4, v4, v5
	v_mul_f32_e32 v5, v36, v30
	v_mul_f32_e32 v6, v36, v31
	v_cvt_pk_bf16_f32 v5, v5, v6
	global_store_dwordx2 v[32:33], v[4:5], off offset:672
	v_mul_f32_e32 v4, v36, v50
	v_mul_f32_e32 v5, v36, v51
	v_cvt_pk_bf16_f32 v4, v4, v5
	v_mul_f32_e32 v5, v36, v52
	v_mul_f32_e32 v6, v36, v53
	v_cvt_pk_bf16_f32 v5, v5, v6
	global_store_dwordx2 v[32:33], v[4:5], off offset:704
	v_mul_f32_e32 v4, v36, v74
	v_mul_f32_e32 v5, v36, v75
	v_cvt_pk_bf16_f32 v4, v4, v5
	v_mul_f32_e32 v5, v36, v76
	v_mul_f32_e32 v6, v36, v77
	v_cvt_pk_bf16_f32 v5, v5, v6
	global_store_dwordx2 v[32:33], v[4:5], off offset:736
	v_mul_f32_e32 v4, v36, v38
	v_mul_f32_e32 v5, v36, v39
	v_cvt_pk_bf16_f32 v4, v4, v5
	v_mul_f32_e32 v5, v36, v40
	v_mul_f32_e32 v6, v36, v41
	v_cvt_pk_bf16_f32 v5, v5, v6
	global_store_dwordx2 v[32:33], v[4:5], off offset:768
	v_mul_f32_e32 v4, v36, v42
	v_mul_f32_e32 v5, v36, v43
	v_cvt_pk_bf16_f32 v4, v4, v5
	v_mul_f32_e32 v5, v36, v44
	v_mul_f32_e32 v6, v36, v45
	v_cvt_pk_bf16_f32 v5, v5, v6
	global_store_dwordx2 v[32:33], v[4:5], off offset:800
	v_mul_f32_e32 v4, v36, v54
	v_mul_f32_e32 v5, v36, v55
	v_cvt_pk_bf16_f32 v4, v4, v5
	v_mul_f32_e32 v5, v36, v56
	v_mul_f32_e32 v6, v36, v57
	v_cvt_pk_bf16_f32 v5, v5, v6
	global_store_dwordx2 v[32:33], v[4:5], off offset:832
	v_mul_f32_e32 v4, v36, v58
	v_mul_f32_e32 v5, v36, v59
	v_cvt_pk_bf16_f32 v4, v4, v5
	v_mul_f32_e32 v5, v36, v60
	v_mul_f32_e32 v6, v36, v61
	v_cvt_pk_bf16_f32 v5, v5, v6
	global_store_dwordx2 v[32:33], v[4:5], off offset:864
	v_mul_f32_e32 v4, v36, v62
	v_mul_f32_e32 v5, v36, v63
	v_cvt_pk_bf16_f32 v4, v4, v5
	v_mul_f32_e32 v5, v36, v64
	v_mul_f32_e32 v6, v36, v65
	v_cvt_pk_bf16_f32 v5, v5, v6
	global_store_dwordx2 v[32:33], v[4:5], off offset:896
	v_mul_f32_e32 v4, v36, v66
	v_mul_f32_e32 v5, v36, v67
	v_cvt_pk_bf16_f32 v4, v4, v5
	v_mul_f32_e32 v5, v36, v68
	v_mul_f32_e32 v6, v36, v69
	v_cvt_pk_bf16_f32 v5, v5, v6
	global_store_dwordx2 v[32:33], v[4:5], off offset:928
	v_mul_f32_e32 v4, v36, v70
	v_mul_f32_e32 v5, v36, v71
	v_cvt_pk_bf16_f32 v4, v4, v5
	v_mul_f32_e32 v5, v36, v72
	v_mul_f32_e32 v0, v36, v0
	v_mul_f32_e32 v1, v36, v1
	v_mul_f32_e32 v6, v36, v73
	v_cvt_pk_bf16_f32 v5, v5, v6
	global_store_dwordx2 v[32:33], v[4:5], off offset:960
	v_cvt_pk_bf16_f32 v0, v0, v1
	v_mul_f32_e32 v1, v36, v2
	v_mul_f32_e32 v2, v36, v3
	v_cvt_pk_bf16_f32 v1, v1, v2
	global_store_dwordx2 v[32:33], v[0:1], off offset:992
	s_waitcnt vmcnt(0)
	s_barrier

.LBB0_1739:
.LBB0_1740:
	s_add_i32 s0, 0, 0x23f94
	s_waitcnt vmcnt(0)
	v_mov_b32_e32 v0, s0
	v_mbcnt_lo_u32_b32 v58, -1, 0
	v_mbcnt_hi_u32_b32 v58, -1, v58
	ds_read_b32 v0, v0
	v_lshlrev_b32_e32 v71, 4, v58
	v_and_b32_e32 v59, 15, v58
	s_mov_b32 s1, 0
	v_ashrrev_i32_e32 v70, 4, v58
	s_waitcnt lgkmcnt(0)
	v_readfirstlane_b32 s0, v0
	s_and_b32 s4, s0, 7
	s_mul_i32 s5, s4, 0x1400000
	s_add_u32 s5, s94, s5
	s_addc_u32 s6, s95, 0
	s_lshl_b32 s4, s4, 22
	s_sub_u32 s4, 0, s4
	s_subb_u32 s7, 0, 0
	s_add_u32 s4, s5, s4
	s_addc_u32 s5, s6, s7
	s_lshl_b32 s8, s88, 10
	v_add_u32_e32 v0, s8, v71
	v_ashrrev_i32_e32 v1, 31, v0
	v_lshrrev_b32_e32 v1, 22, v1
	v_add_u32_e32 v1, v0, v1
	v_ashrrev_i32_e32 v1, 10, v1
	v_mul_i32_i24_e32 v2, 0x400, v1
	v_sub_u32_e32 v2, v0, v2
	v_lshrrev_b32_e32 v3, 4, v2
	v_bitop3_b32 v2, v3, v2, 32 bitop3:0x6c
	v_ashrrev_i32_e32 v4, 31, v2
	v_lshrrev_b32_e32 v4, 26, v4
	v_lshlrev_b32_e32 v3, 3, v1
	v_add_u32_e32 v4, v2, v4
	v_and_b32_e32 v3, -16, v3
	v_ashrrev_i32_e32 v5, 6, v4
	v_add_u32_e32 v104, v5, v3
	v_and_b32_e32 v3, 0xc0, v4
	v_lshlrev_b32_e32 v1, 5, v1
	v_sub_u32_e32 v2, v2, v3
	v_mov_b32_e32 v3, 1
	v_and_b32_e32 v1, 32, v1
	v_ashrrev_i16_sdwa v2, v3, sext(v2) dst_sel:DWORD dst_unused:UNUSED_PAD src0_sel:DWORD src1_sel:BYTE_0
	v_add_u32_sdwa v1, v1, sext(v2) dst_sel:DWORD dst_unused:UNUSED_PAD src0_sel:DWORD src1_sel:WORD_0
	v_lshlrev_b32_e32 v2, 10, v104
	v_add_u32_e32 v0, 0x2000, v0
	v_lshl_add_u32 v62, v1, 1, v2
	v_ashrrev_i32_e32 v1, 31, v0
	v_lshrrev_b32_e32 v1, 22, v1
	v_add_u32_e32 v1, v0, v1
	v_ashrrev_i32_e32 v1, 10, v1
	v_mul_i32_i24_e32 v2, 0x400, v1
	v_sub_u32_e32 v0, v0, v2
	v_lshrrev_b32_e32 v2, 4, v0
	s_lshl_b32 s6, s0, 3
	v_bitop3_b32 v0, v2, v0, 32 bitop3:0x6c
	s_and_b32 s6, s6, 56
	s_ashr_i32 s7, s0, 5
	v_ashrrev_i32_e32 v4, 31, v0
	s_add_i32 s9, s6, s7
	v_lshrrev_b32_e32 v4, 26, v4
	s_ashr_i32 s12, s9, 5
	v_lshlrev_b32_e32 v2, 3, v1
	v_add_u32_e32 v4, v0, v4
	s_bfe_u32 s0, s0, 0x20003
	s_lshl_b32 s6, s12, 2
	v_and_b32_e32 v2, -16, v2
	v_ashrrev_i32_e32 v5, 6, v4
	s_or_b32 s6, s6, s0
	v_add_u32_e32 v108, v5, v2
	v_and_b32_e32 v2, 0xffc0, v4
	s_ashr_i32 s7, s6, 31
	v_sub_u32_e32 v0, v0, v2
	s_lshl_b64 s[6:7], s[6:7], 18
	v_lshrrev_b16_e32 v2, 7, v0
	s_add_u32 s10, s94, s6
	v_and_b32_e32 v2, 1, v2
	s_addc_u32 s11, s95, s7
	v_lshlrev_b32_e32 v1, 5, v1
	v_add_u16_e32 v0, v0, v2
	s_add_u32 s6, s10, 0x11600000
	v_and_b32_e32 v1, 32, v1
	v_ashrrev_i16_sdwa v0, v3, sext(v0) dst_sel:DWORD dst_unused:UNUSED_PAD src0_sel:DWORD src1_sel:BYTE_0
	s_addc_u32 s7, s11, 0
	s_lshl_b32 s9, s9, 7
	v_add_u32_sdwa v0, v1, sext(v0) dst_sel:DWORD dst_unused:UNUSED_PAD src0_sel:DWORD src1_sel:WORD_0
	v_lshlrev_b32_e32 v1, 10, v108
	s_lshl_b32 s12, s12, 12
	s_and_b32 s9, s9, 0xf80
	v_lshl_add_u32 v64, v0, 1, v1
	v_lshl_or_b32 v1, s88, 4, v59
	s_or_b32 s9, s12, s9
	v_add_u32_e32 v2, s9, v1
	v_ashrrev_i32_e32 v3, 31, v2
	v_lshlrev_b64 v[2:3], 12, v[2:3]
	s_lshl_b32 s0, s0, 10
	v_lshl_add_u64 v[2:3], s[4:5], 0, v[2:3]
	v_lshlrev_b32_e32 v0, 3, v70
	v_lshl_add_u64 v[2:3], v[2:3], 0, s[0:1]
	s_mov_b64 s[0:1], 0x13000000
	v_ashrrev_i32_e32 v1, 31, v0
	v_lshl_add_u64 v[60:61], v[2:3], 0, s[0:1]
	v_lshl_add_u64 v[0:1], v[0:1], 1, v[60:61]
	s_mov_b64 s[0:1], 0xc00000
	v_lshl_add_u64 v[2:3], v[0:1], 0, s[0:1]
	s_mov_b32 s0, 0xc00000
	v_add_co_u32_e32 v0, vcc, s0, v0
	s_add_i32 s22, s8, 0
	s_nop 0
	v_addc_co_u32_e32 v1, vcc, 0, v1, vcc
	v_mov_b32_e32 v63, 0
	s_mov_b32 m0, s22
	s_add_i32 s21, s22, 0x2000
	global_load_dwordx4 v[72:75], v[2:3], off offset:64
	global_load_dwordx4 v[52:55], v[2:3], off offset:128
	global_load_dwordx4 v[48:51], v[2:3], off offset:192
	global_load_dwordx4 v[44:47], v[2:3], off offset:256
	global_load_dwordx4 v[40:43], v[2:3], off offset:320
	global_load_dwordx4 v[36:39], v[2:3], off offset:384
	global_load_dwordx4 v[32:35], v[2:3], off offset:448
	global_load_dwordx4 v[28:31], v[2:3], off offset:512
	global_load_dwordx4 v[24:27], v[2:3], off offset:576
	global_load_dwordx4 v[20:23], v[2:3], off offset:640
	global_load_dwordx4 v[16:19], v[2:3], off offset:704
	global_load_dwordx4 v[12:15], v[2:3], off offset:768
	global_load_dwordx4 v[8:11], v[2:3], off offset:832
	global_load_dwordx4 v[4:7], v[2:3], off offset:896
	global_load_dwordx4 v[76:79], v[0:1], off
	s_nop 0
	global_load_dwordx4 v[0:3], v[2:3], off offset:960
	v_mov_b32_e32 v65, v63
	global_load_lds_dwordx4 v62, s[6:7]
	v_mov_b32_e32 v240, v62
	s_mov_b32 m0, s21
	v_lshl_add_u64 v[66:67], s[6:7], 0, v[62:63]
	v_lshl_add_u64 v[68:69], s[6:7], 0, v[64:65]
	global_load_lds_dwordx4 v64, s[6:7]
	s_add_i32 s20, s22, 0x4000
	s_mov_b64 s[6:7], 0x80
	s_add_i32 s23, s22, 0x6000
	v_lshl_add_u64 v[56:57], v[66:67], 0, s[6:7]
	s_mov_b32 m0, s20
	s_add_u32 s0, s10, 0x11620000
	global_load_lds_dwordx4 v[56:57], off
	v_lshl_add_u64 v[56:57], v[68:69], 0, s[6:7]
	s_mov_b32 m0, s23
	s_addc_u32 s1, s11, 0
	s_add_i32 s24, s22, 0x8000
	global_load_lds_dwordx4 v[56:57], off
	s_mov_b32 m0, s24
	s_add_i32 s25, s22, 0xa000
	global_load_lds_dwordx4 v62, s[0:1]
	s_mov_b32 m0, s25
	s_mov_b64 s[4:5], 0x180
	global_load_lds_dwordx4 v64, s[0:1]
	s_add_u32 s0, s10, 0x11620080
	s_addc_u32 s1, s11, 0
	s_add_i32 s26, s22, 0xc000
	s_mov_b32 m0, s26
	s_add_i32 s27, s22, 0xe000
	global_load_lds_dwordx4 v62, s[0:1]
	s_mov_b32 m0, s27
	s_add_u32 s8, s10, 0x11e00000
	global_load_lds_dwordx4 v64, s[0:1]
	s_addc_u32 s9, s11, 0
	s_add_i32 s19, s22, 0x10000
	s_mov_b64 s[0:1], 0x100
	v_lshl_add_u64 v[56:57], v[66:67], 0, s[0:1]
	s_mov_b32 m0, s19
	s_add_i32 s13, s22, 0x12000
	s_waitcnt vmcnt(0)
	s_waitcnt vmcnt(0) lgkmcnt(0)
	s_barrier
	global_load_lds_dwordx4 v[56:57], off
	v_lshl_add_u64 v[56:57], v[68:69], 0, s[0:1]
	s_mov_b32 m0, s13
	s_add_i32 s12, s22, 0x14000
	s_add_i32 s14, s22, 0x16000
	global_load_lds_dwordx4 v[56:57], off
	v_lshl_add_u64 v[56:57], v[66:67], 0, s[4:5]
	s_mov_b32 m0, s12
	s_add_u32 s28, s10, 0x11620100
	global_load_lds_dwordx4 v[56:57], off
	v_lshl_add_u64 v[56:57], v[68:69], 0, s[4:5]
	s_mov_b32 m0, s14
	s_addc_u32 s29, s11, 0
	s_add_i32 s15, s22, 0x18000
	global_load_lds_dwordx4 v[56:57], off
	s_mov_b32 m0, s15
	s_add_i32 s16, s22, 0x1a000
	global_load_lds_dwordx4 v62, s[28:29]
	s_mov_b32 m0, s16
	v_and_b32_e32 v57, 48, v58
	global_load_lds_dwordx4 v64, s[28:29]
	s_add_u32 s28, s10, 0x11620180
	s_addc_u32 s29, s11, 0
	s_add_i32 s17, s22, 0x1c000
	s_mov_b32 m0, s17
	s_add_i32 s18, s22, 0x1e000
	global_load_lds_dwordx4 v62, s[28:29]
	s_mov_b32 m0, s18
	v_lshlrev_b32_e32 v58, 2, v58
	global_load_lds_dwordx4 v64, s[28:29]
	v_lshlrev_b32_e32 v56, 6, v59
	v_and_b32_e32 v58, 32, v58
	v_bitop3_b32 v56, v56, v58, v57 bitop3:0x36
	v_and_b32_e32 v57, 0xfffffc00, v71
	v_add3_u32 v65, 0, v56, v57
	v_mov_b32_e32 v71, v65
	ds_read_b128 v[56:59], v71
	ds_read_b128 v[80:83], v71 offset:2048
	s_waitcnt lgkmcnt(0)
	v_mfma_f32_16x16x32_bf16 v[84:87], v[56:59], v[76:79], 0
	ds_read_b128 v[56:59], v71 offset:4096
	ds_read_b128 v[88:91], v71 offset:6144
	ds_read_b128 v[96:99], v71 offset:8192
	ds_read_b128 v[100:103], v71 offset:10240
	s_waitcnt lgkmcnt(0)
	v_mfma_f32_16x16x32_bf16 v[92:95], v[56:59], v[76:79], 0
	v_lshlrev_b32_e32 v56, 9, v104
	ds_read_b128 v[104:107], v71 offset:12288
	v_lshlrev_b32_e32 v57, 9, v108
	ds_read_b128 v[108:111], v71 offset:14336
	ds_read_b128 v[112:115], v71 offset:32768
	ds_read_b128 v[116:119], v71 offset:34816
	ds_read_b128 v[120:123], v71 offset:36864
	ds_read_b128 v[124:127], v71 offset:38912
	ds_read_b128 v[128:131], v71 offset:40960
	ds_read_b128 v[132:135], v71 offset:43008
	ds_read_b128 v[136:139], v71 offset:45056
	ds_read_b128 v[140:143], v71 offset:47104
	v_mfma_f32_16x16x32_bf16 v[80:83], v[80:83], v[76:79], 0
	v_sub_u32_e32 v56, v62, v56
	v_mov_b32_e32 v241, v56
	v_sub_u32_e32 v58, v64, v57
	v_mfma_f32_16x16x32_bf16 v[88:91], v[88:91], v[76:79], 0
	v_mfma_f32_16x16x32_bf16 v[96:99], v[96:99], v[76:79], 0
	v_mfma_f32_16x16x32_bf16 v[100:103], v[100:103], v[76:79], 0
	s_waitcnt lgkmcnt(0)
	v_mfma_f32_16x16x32_bf16 v[104:107], v[104:107], v[76:79], 0
	v_mfma_f32_16x16x32_bf16 v[108:111], v[108:111], v[76:79], 0
	ds_read_b128 v[144:147], v71 offset:15360
	ds_read_b128 v[148:151], v71 offset:13312
	ds_read_b128 v[152:155], v71 offset:11264
	ds_read_b128 v[156:159], v71 offset:9216
	ds_read_b128 v[160:163], v71 offset:7168
	ds_read_b128 v[164:167], v71 offset:5120
	ds_read_b128 v[168:171], v71 offset:3072
	ds_read_b128 v[172:175], v71 offset:1024
	v_mfma_f32_16x16x32_bf16 v[112:115], v[112:115], v[76:79], 0
	v_mfma_f32_16x16x32_bf16 v[116:119], v[116:119], v[76:79], 0
	v_mfma_f32_16x16x32_bf16 v[120:123], v[120:123], v[76:79], 0
	v_mfma_f32_16x16x32_bf16 v[124:127], v[124:127], v[76:79], 0
	v_mfma_f32_16x16x32_bf16 v[128:131], v[128:131], v[76:79], 0
	v_mfma_f32_16x16x32_bf16 v[132:135], v[132:135], v[76:79], 0
	v_mfma_f32_16x16x32_bf16 v[136:139], v[136:139], v[76:79], 0
	v_mfma_f32_16x16x32_bf16 v[76:79], v[140:143], v[76:79], 0
	s_waitcnt lgkmcnt(0)
	v_mfma_f32_16x16x32_bf16 v[84:87], v[172:175], v[72:75], v[84:87]
	v_mfma_f32_16x16x32_bf16 v[80:83], v[168:171], v[72:75], v[80:83]
	v_mfma_f32_16x16x32_bf16 v[92:95], v[164:167], v[72:75], v[92:95]
	v_mfma_f32_16x16x32_bf16 v[88:91], v[160:163], v[72:75], v[88:91]
	v_mfma_f32_16x16x32_bf16 v[96:99], v[156:159], v[72:75], v[96:99]
	v_mfma_f32_16x16x32_bf16 v[100:103], v[152:155], v[72:75], v[100:103]
	ds_read_b128 v[140:143], v71 offset:33792
	ds_read_b128 v[152:155], v71 offset:35840
	ds_read_b128 v[156:159], v71 offset:37888
	ds_read_b128 v[160:163], v71 offset:39936
	v_mfma_f32_16x16x32_bf16 v[104:107], v[148:151], v[72:75], v[104:107]
	ds_read_b128 v[148:151], v71 offset:41984
	ds_read_b128 v[164:167], v71 offset:44032
	ds_read_b128 v[168:171], v71 offset:46080
	ds_read_b128 v[172:175], v71 offset:48128
	v_mfma_f32_16x16x32_bf16 v[108:111], v[144:147], v[72:75], v[108:111]
	s_waitcnt lgkmcnt(0)
	v_mfma_f32_16x16x32_bf16 v[112:115], v[140:143], v[72:75], v[112:115]
	v_mfma_f32_16x16x32_bf16 v[116:119], v[152:155], v[72:75], v[116:119]
	v_mfma_f32_16x16x32_bf16 v[120:123], v[156:159], v[72:75], v[120:123]
	v_mfma_f32_16x16x32_bf16 v[124:127], v[160:163], v[72:75], v[124:127]
	v_mfma_f32_16x16x32_bf16 v[128:131], v[148:151], v[72:75], v[128:131]
	ds_read_b128 v[140:143], v71 offset:30720
	ds_read_b128 v[144:147], v71 offset:28672
	ds_read_b128 v[148:151], v71 offset:26624
	ds_read_b128 v[152:155], v71 offset:24576
	v_mfma_f32_16x16x32_bf16 v[132:135], v[164:167], v[72:75], v[132:135]
	v_mfma_f32_16x16x32_bf16 v[136:139], v[168:171], v[72:75], v[136:139]
	ds_read_b128 v[156:159], v71 offset:22528
	ds_read_b128 v[160:163], v71 offset:20480
	ds_read_b128 v[164:167], v71 offset:18432
	ds_read_b128 v[168:171], v71 offset:16384
	v_mfma_f32_16x16x32_bf16 v[72:75], v[172:175], v[72:75], v[76:79]
	s_waitcnt lgkmcnt(0)
	v_mfma_f32_16x16x32_bf16 v[76:79], v[168:171], v[52:55], v[84:87]
	v_mfma_f32_16x16x32_bf16 v[80:83], v[164:167], v[52:55], v[80:83]
	v_mfma_f32_16x16x32_bf16 v[84:87], v[160:163], v[52:55], v[92:95]
	v_mfma_f32_16x16x32_bf16 v[88:91], v[156:159], v[52:55], v[88:91]
	v_mfma_f32_16x16x32_bf16 v[92:95], v[152:155], v[52:55], v[96:99]
	v_mfma_f32_16x16x32_bf16 v[96:99], v[148:151], v[52:55], v[100:103]
	s_nop 2
	ds_read_b128 v[100:103], v71 offset:49152
	ds_read_b128 v[148:151], v71 offset:51200
	ds_read_b128 v[152:155], v71 offset:53248
	ds_read_b128 v[156:159], v71 offset:55296
	v_mfma_f32_16x16x32_bf16 v[104:107], v[144:147], v[52:55], v[104:107]
	ds_read_b128 v[144:147], v71 offset:57344
	ds_read_b128 v[160:163], v71 offset:59392
	ds_read_b128 v[164:167], v71 offset:61440
	ds_read_b128 v[168:171], v71 offset:63488
	v_mfma_f32_16x16x32_bf16 v[108:111], v[140:143], v[52:55], v[108:111]
	s_waitcnt lgkmcnt(0)
	v_mfma_f32_16x16x32_bf16 v[100:103], v[100:103], v[52:55], v[112:115]
	v_mfma_f32_16x16x32_bf16 v[112:115], v[148:151], v[52:55], v[116:119]
	v_mfma_f32_16x16x32_bf16 v[116:119], v[152:155], v[52:55], v[120:123]
	v_mfma_f32_16x16x32_bf16 v[120:123], v[156:159], v[52:55], v[124:127]
	v_mfma_f32_16x16x32_bf16 v[124:127], v[144:147], v[52:55], v[128:131]
	v_mfma_f32_16x16x32_bf16 v[128:131], v[160:163], v[52:55], v[132:135]
	s_nop 2
	ds_read_b128 v[132:135], v71 offset:31744
	ds_read_b128 v[140:143], v71 offset:29696
	ds_read_b128 v[144:147], v71 offset:27648
	ds_read_b128 v[148:151], v71 offset:25600
	v_mfma_f32_16x16x32_bf16 v[136:139], v[164:167], v[52:55], v[136:139]
	ds_read_b128 v[152:155], v71 offset:23552
	ds_read_b128 v[156:159], v71 offset:21504
	ds_read_b128 v[160:163], v71 offset:19456
	ds_read_b128 v[164:167], v71 offset:17408
	v_mfma_f32_16x16x32_bf16 v[52:55], v[168:171], v[52:55], v[72:75]
	s_waitcnt lgkmcnt(0)
	v_mfma_f32_16x16x32_bf16 v[72:75], v[164:167], v[48:51], v[76:79]
	v_mfma_f32_16x16x32_bf16 v[76:79], v[160:163], v[48:51], v[80:83]
	v_mfma_f32_16x16x32_bf16 v[80:83], v[156:159], v[48:51], v[84:87]
	v_mfma_f32_16x16x32_bf16 v[84:87], v[152:155], v[48:51], v[88:91]
	v_mfma_f32_16x16x32_bf16 v[88:91], v[148:151], v[48:51], v[92:95]
	v_mfma_f32_16x16x32_bf16 v[92:95], v[144:147], v[48:51], v[96:99]
	s_nop 2
	ds_read_b128 v[96:99], v71 offset:50176
	ds_read_b128 v[144:147], v71 offset:52224
	ds_read_b128 v[148:151], v71 offset:54272
	ds_read_b128 v[152:155], v71 offset:56320
	v_mfma_f32_16x16x32_bf16 v[104:107], v[140:143], v[48:51], v[104:107]
	ds_read_b128 v[140:143], v71 offset:58368
	ds_read_b128 v[156:159], v71 offset:60416
	ds_read_b128 v[160:163], v71 offset:62464
	ds_read_b128 v[164:167], v71 offset:64512
	v_mfma_f32_16x16x32_bf16 v[108:111], v[132:135], v[48:51], v[108:111]
	s_waitcnt lgkmcnt(0)
	v_mfma_f32_16x16x32_bf16 v[96:99], v[96:99], v[48:51], v[100:103]
	v_mfma_f32_16x16x32_bf16 v[100:103], v[144:147], v[48:51], v[112:115]
	v_mfma_f32_16x16x32_bf16 v[112:115], v[148:151], v[48:51], v[116:119]
	v_mfma_f32_16x16x32_bf16 v[116:119], v[152:155], v[48:51], v[120:123]
	v_mfma_f32_16x16x32_bf16 v[120:123], v[140:143], v[48:51], v[124:127]
	v_mfma_f32_16x16x32_bf16 v[124:127], v[156:159], v[48:51], v[128:131]
	v_mfma_f32_16x16x32_bf16 v[128:131], v[160:163], v[48:51], v[136:139]
	v_mfma_f32_16x16x32_bf16 v[50:53], v[164:167], v[48:51], v[52:55]
	s_waitcnt vmcnt(0)
	s_waitcnt vmcnt(0)
	s_barrier
	v_add_u32_e32 v48, 0x10000, v65
	v_mov_b32_e32 v49, v48
	ds_read_b128 v[132:135], v49
	ds_read_b128 v[136:139], v49 offset:2048
	s_waitcnt lgkmcnt(0)
	v_mfma_f32_16x16x32_bf16 v[72:75], v[132:135], v[44:47], v[72:75]
	ds_read_b128 v[132:135], v49 offset:4096
	v_mfma_f32_16x16x32_bf16 v[76:79], v[136:139], v[44:47], v[76:79]
	ds_read_b128 v[136:139], v49 offset:6144
	s_waitcnt lgkmcnt(0)
	v_mfma_f32_16x16x32_bf16 v[80:83], v[132:135], v[44:47], v[80:83]
	ds_read_b128 v[132:135], v49 offset:8192
	v_mfma_f32_16x16x32_bf16 v[84:87], v[136:139], v[44:47], v[84:87]
	ds_read_b128 v[136:139], v49 offset:10240
	s_waitcnt lgkmcnt(0)
	v_mfma_f32_16x16x32_bf16 v[88:91], v[132:135], v[44:47], v[88:91]
	ds_read_b128 v[132:135], v49 offset:12288
	ds_read_b128 v[140:143], v49 offset:14336
	v_mfma_f32_16x16x32_bf16 v[92:95], v[136:139], v[44:47], v[92:95]
	ds_read_b128 v[136:139], v49 offset:32768
	ds_read_b128 v[144:147], v49 offset:34816
	ds_read_b128 v[148:151], v49 offset:36864
	ds_read_b128 v[152:155], v49 offset:38912
	s_waitcnt lgkmcnt(0)
	v_mfma_f32_16x16x32_bf16 v[104:107], v[132:135], v[44:47], v[104:107]
	ds_read_b128 v[132:135], v49 offset:40960
	ds_read_b128 v[156:159], v49 offset:43008
	ds_read_b128 v[160:163], v49 offset:45056
	ds_read_b128 v[164:167], v49 offset:47104
	v_mfma_f32_16x16x32_bf16 v[108:111], v[140:143], v[44:47], v[108:111]
	s_add_u32 s100, s10, 0x11600200
	s_addc_u32 s101, s11, 0
	s_mov_b32 m0, s22
	s_nop 0
	global_load_lds_dwordx4 v240, s[100:101]
	v_mfma_f32_16x16x32_bf16 v[96:99], v[136:139], v[44:47], v[96:99]
	v_mfma_f32_16x16x32_bf16 v[100:103], v[144:147], v[44:47], v[100:103]
	v_mfma_f32_16x16x32_bf16 v[112:115], v[148:151], v[44:47], v[112:115]
	v_mfma_f32_16x16x32_bf16 v[116:119], v[152:155], v[44:47], v[116:119]
	s_waitcnt lgkmcnt(0)
	v_mfma_f32_16x16x32_bf16 v[120:123], v[132:135], v[44:47], v[120:123]
	ds_read_b128 v[132:135], v49 offset:15360
	ds_read_b128 v[136:139], v49 offset:13312
	ds_read_b128 v[140:143], v49 offset:11264
	ds_read_b128 v[144:147], v49 offset:9216
	v_mfma_f32_16x16x32_bf16 v[124:127], v[156:159], v[44:47], v[124:127]
	v_mfma_f32_16x16x32_bf16 v[128:131], v[160:163], v[44:47], v[128:131]
	ds_read_b128 v[148:151], v49 offset:7168
	ds_read_b128 v[152:155], v49 offset:5120
	ds_read_b128 v[156:159], v49 offset:3072
	ds_read_b128 v[160:163], v49 offset:1024
	v_mfma_f32_16x16x32_bf16 v[44:47], v[164:167], v[44:47], v[50:53]
	s_add_u32 s100, s10, 0x11610200
	s_addc_u32 s101, s11, 0
	s_mov_b32 m0, s21
	s_nop 0
	global_load_lds_dwordx4 v240, s[100:101]
	s_waitcnt lgkmcnt(0)
	v_mfma_f32_16x16x32_bf16 v[50:53], v[160:163], v[40:43], v[72:75]
	v_mfma_f32_16x16x32_bf16 v[72:75], v[156:159], v[40:43], v[76:79]
	v_mfma_f32_16x16x32_bf16 v[76:79], v[152:155], v[40:43], v[80:83]
	v_mfma_f32_16x16x32_bf16 v[80:83], v[148:151], v[40:43], v[84:87]
	v_mfma_f32_16x16x32_bf16 v[84:87], v[144:147], v[40:43], v[88:91]
	v_mfma_f32_16x16x32_bf16 v[88:91], v[140:143], v[40:43], v[92:95]
	s_nop 2
	ds_read_b128 v[92:95], v49 offset:33792
	ds_read_b128 v[140:143], v49 offset:35840
	ds_read_b128 v[144:147], v49 offset:37888
	ds_read_b128 v[148:151], v49 offset:39936
	v_mfma_f32_16x16x32_bf16 v[104:107], v[136:139], v[40:43], v[104:107]
	ds_read_b128 v[136:139], v49 offset:41984
	ds_read_b128 v[152:155], v49 offset:44032
	ds_read_b128 v[156:159], v49 offset:46080
	ds_read_b128 v[160:163], v49 offset:48128
	v_mfma_f32_16x16x32_bf16 v[108:111], v[132:135], v[40:43], v[108:111]
	s_add_u32 s100, s10, 0x11600280
	s_addc_u32 s101, s11, 0
	s_mov_b32 m0, s20
	s_nop 0
	global_load_lds_dwordx4 v240, s[100:101]
	s_waitcnt lgkmcnt(0)
	v_mfma_f32_16x16x32_bf16 v[92:95], v[92:95], v[40:43], v[96:99]
	v_mfma_f32_16x16x32_bf16 v[96:99], v[140:143], v[40:43], v[100:103]
	v_mfma_f32_16x16x32_bf16 v[100:103], v[144:147], v[40:43], v[112:115]
	v_mfma_f32_16x16x32_bf16 v[112:115], v[148:151], v[40:43], v[116:119]
	v_mfma_f32_16x16x32_bf16 v[116:119], v[136:139], v[40:43], v[120:123]
	v_mfma_f32_16x16x32_bf16 v[120:123], v[152:155], v[40:43], v[124:127]
	s_nop 2
	ds_read_b128 v[124:127], v49 offset:30720
	ds_read_b128 v[132:135], v49 offset:28672
	ds_read_b128 v[136:139], v49 offset:26624
	ds_read_b128 v[140:143], v49 offset:24576
	v_mfma_f32_16x16x32_bf16 v[128:131], v[156:159], v[40:43], v[128:131]
	ds_read_b128 v[144:147], v49 offset:22528
	ds_read_b128 v[148:151], v49 offset:20480
	ds_read_b128 v[152:155], v49 offset:18432
	ds_read_b128 v[156:159], v49 offset:16384
	v_mfma_f32_16x16x32_bf16 v[40:43], v[160:163], v[40:43], v[44:47]
	s_add_u32 s100, s10, 0x11610280
	s_addc_u32 s101, s11, 0
	s_mov_b32 m0, s23
	s_nop 0
	global_load_lds_dwordx4 v240, s[100:101]
	s_waitcnt lgkmcnt(0)
	v_mfma_f32_16x16x32_bf16 v[44:47], v[156:159], v[36:39], v[50:53]
	v_mfma_f32_16x16x32_bf16 v[50:53], v[152:155], v[36:39], v[72:75]
	v_mfma_f32_16x16x32_bf16 v[72:75], v[148:151], v[36:39], v[76:79]
	v_mfma_f32_16x16x32_bf16 v[76:79], v[144:147], v[36:39], v[80:83]
	v_mfma_f32_16x16x32_bf16 v[80:83], v[140:143], v[36:39], v[84:87]
	v_mfma_f32_16x16x32_bf16 v[84:87], v[136:139], v[36:39], v[88:91]
	s_nop 2
	ds_read_b128 v[88:91], v49 offset:49152
	ds_read_b128 v[136:139], v49 offset:51200
	ds_read_b128 v[140:143], v49 offset:53248
	ds_read_b128 v[144:147], v49 offset:55296
	v_mfma_f32_16x16x32_bf16 v[104:107], v[132:135], v[36:39], v[104:107]
	ds_read_b128 v[132:135], v49 offset:57344
	ds_read_b128 v[148:151], v49 offset:59392
	ds_read_b128 v[152:155], v49 offset:61440
	ds_read_b128 v[156:159], v49 offset:63488
	v_mfma_f32_16x16x32_bf16 v[108:111], v[124:127], v[36:39], v[108:111]
	s_add_u32 s100, s10, 0x11620200
	s_addc_u32 s101, s11, 0
	s_mov_b32 m0, s24
	s_nop 0
	global_load_lds_dwordx4 v240, s[100:101]
	s_waitcnt lgkmcnt(0)
	v_mfma_f32_16x16x32_bf16 v[88:91], v[88:91], v[36:39], v[92:95]
	v_mfma_f32_16x16x32_bf16 v[92:95], v[136:139], v[36:39], v[96:99]
	v_mfma_f32_16x16x32_bf16 v[96:99], v[140:143], v[36:39], v[100:103]
	v_mfma_f32_16x16x32_bf16 v[100:103], v[144:147], v[36:39], v[112:115]
	v_mfma_f32_16x16x32_bf16 v[112:115], v[132:135], v[36:39], v[116:119]
	v_mfma_f32_16x16x32_bf16 v[116:119], v[148:151], v[36:39], v[120:123]
	s_nop 2
	ds_read_b128 v[120:123], v49 offset:31744
	ds_read_b128 v[124:127], v49 offset:29696
	ds_read_b128 v[132:135], v49 offset:27648
	ds_read_b128 v[136:139], v49 offset:25600
	v_mfma_f32_16x16x32_bf16 v[128:131], v[152:155], v[36:39], v[128:131]
	ds_read_b128 v[140:143], v49 offset:23552
	ds_read_b128 v[144:147], v49 offset:21504
	ds_read_b128 v[148:151], v49 offset:19456
	ds_read_b128 v[152:155], v49 offset:17408
	v_mfma_f32_16x16x32_bf16 v[36:39], v[156:159], v[36:39], v[40:43]
	s_add_u32 s100, s10, 0x11630200
	s_addc_u32 s101, s11, 0
	s_mov_b32 m0, s25
	s_nop 0
	global_load_lds_dwordx4 v240, s[100:101]
	s_waitcnt lgkmcnt(0)
	v_mfma_f32_16x16x32_bf16 v[40:43], v[152:155], v[32:35], v[44:47]
	v_mfma_f32_16x16x32_bf16 v[44:47], v[148:151], v[32:35], v[50:53]
	v_mfma_f32_16x16x32_bf16 v[50:53], v[144:147], v[32:35], v[72:75]
	v_mfma_f32_16x16x32_bf16 v[72:75], v[140:143], v[32:35], v[76:79]
	v_mfma_f32_16x16x32_bf16 v[76:79], v[136:139], v[32:35], v[80:83]
	v_mfma_f32_16x16x32_bf16 v[80:83], v[132:135], v[32:35], v[84:87]
	s_nop 2
	ds_read_b128 v[84:87], v49 offset:50176
	ds_read_b128 v[132:135], v49 offset:52224
	ds_read_b128 v[136:139], v49 offset:54272
	ds_read_b128 v[140:143], v49 offset:56320
	v_mfma_f32_16x16x32_bf16 v[104:107], v[124:127], v[32:35], v[104:107]
	ds_read_b128 v[124:127], v49 offset:58368
	ds_read_b128 v[144:147], v49 offset:60416
	ds_read_b128 v[148:151], v49 offset:62464
	ds_read_b128 v[152:155], v49 offset:64512
	v_mfma_f32_16x16x32_bf16 v[108:111], v[120:123], v[32:35], v[108:111]
	s_add_u32 s100, s10, 0x11620280
	s_addc_u32 s101, s11, 0
	s_mov_b32 m0, s26
	s_nop 0
	global_load_lds_dwordx4 v240, s[100:101]
	s_waitcnt lgkmcnt(0)
	v_mfma_f32_16x16x32_bf16 v[84:87], v[84:87], v[32:35], v[88:91]
	v_mfma_f32_16x16x32_bf16 v[88:91], v[132:135], v[32:35], v[92:95]
	v_mfma_f32_16x16x32_bf16 v[92:95], v[136:139], v[32:35], v[96:99]
	v_mfma_f32_16x16x32_bf16 v[96:99], v[140:143], v[32:35], v[100:103]
	v_mfma_f32_16x16x32_bf16 v[100:103], v[124:127], v[32:35], v[112:115]
	v_mfma_f32_16x16x32_bf16 v[112:115], v[144:147], v[32:35], v[116:119]
	v_mfma_f32_16x16x32_bf16 v[116:119], v[148:151], v[32:35], v[128:131]
	v_mfma_f32_16x16x32_bf16 v[32:35], v[152:155], v[32:35], v[36:39]
	s_add_u32 s100, s10, 0x11630280
	s_addc_u32 s101, s11, 0
	s_mov_b32 m0, s27
	s_nop 0
	global_load_lds_dwordx4 v240, s[100:101]
	s_nop 0
	s_waitcnt vmcnt(0)
	s_waitcnt vmcnt(0)
	s_barrier
	v_mov_b32_e32 v49, v65
	ds_read_b128 v[36:39], v49
	ds_read_b128 v[66:69], v49 offset:2048
	s_waitcnt lgkmcnt(0)
	v_mfma_f32_16x16x32_bf16 v[36:39], v[36:39], v[28:31], v[40:43]
	s_nop 2
	ds_read_b128 v[40:43], v49 offset:4096
	v_mfma_f32_16x16x32_bf16 v[44:47], v[66:69], v[28:31], v[44:47]
	ds_read_b128 v[66:69], v49 offset:6144
	s_waitcnt lgkmcnt(0)
	v_mfma_f32_16x16x32_bf16 v[40:43], v[40:43], v[28:31], v[50:53]
	s_nop 2
	ds_read_b128 v[50:53], v49 offset:8192
	v_mfma_f32_16x16x32_bf16 v[66:69], v[66:69], v[28:31], v[72:75]
	s_nop 2
	ds_read_b128 v[72:75], v49 offset:10240
	s_waitcnt lgkmcnt(0)
	v_mfma_f32_16x16x32_bf16 v[50:53], v[50:53], v[28:31], v[76:79]
	s_nop 2
	ds_read_b128 v[76:79], v49 offset:12288
	ds_read_b128 v[120:123], v49 offset:14336
	v_mfma_f32_16x16x32_bf16 v[72:75], v[72:75], v[28:31], v[80:83]
	s_nop 2
	ds_read_b128 v[80:83], v49 offset:32768
	ds_read_b128 v[124:127], v49 offset:34816
	ds_read_b128 v[128:131], v49 offset:36864
	ds_read_b128 v[132:135], v49 offset:38912
	s_waitcnt lgkmcnt(0)
	v_mfma_f32_16x16x32_bf16 v[76:79], v[76:79], v[28:31], v[104:107]
	s_nop 2
	ds_read_b128 v[104:107], v49 offset:40960
	ds_read_b128 v[136:139], v49 offset:43008
	ds_read_b128 v[140:143], v49 offset:45056
	ds_read_b128 v[144:147], v49 offset:47104
	v_mfma_f32_16x16x32_bf16 v[108:111], v[120:123], v[28:31], v[108:111]
	s_add_u32 s100, s10, 0x11600300
	s_addc_u32 s101, s11, 0
	s_mov_b32 m0, s19
	s_nop 0
	global_load_lds_dwordx4 v240, s[100:101]
	v_mfma_f32_16x16x32_bf16 v[80:83], v[80:83], v[28:31], v[84:87]
	v_mfma_f32_16x16x32_bf16 v[84:87], v[124:127], v[28:31], v[88:91]
	v_mfma_f32_16x16x32_bf16 v[88:91], v[128:131], v[28:31], v[92:95]
	v_mfma_f32_16x16x32_bf16 v[92:95], v[132:135], v[28:31], v[96:99]
	s_waitcnt lgkmcnt(0)
	v_mfma_f32_16x16x32_bf16 v[96:99], v[104:107], v[28:31], v[100:103]
	v_mfma_f32_16x16x32_bf16 v[100:103], v[136:139], v[28:31], v[112:115]
	ds_read_b128 v[104:107], v49 offset:15360
	s_nop 1
	ds_read_b128 v[112:115], v49 offset:13312
	ds_read_b128 v[120:123], v49 offset:11264
	ds_read_b128 v[124:127], v49 offset:9216
	v_mfma_f32_16x16x32_bf16 v[116:119], v[140:143], v[28:31], v[116:119]
	ds_read_b128 v[128:131], v49 offset:7168
	ds_read_b128 v[132:135], v49 offset:5120
	ds_read_b128 v[136:139], v49 offset:3072
	ds_read_b128 v[140:143], v49 offset:1024
	v_mfma_f32_16x16x32_bf16 v[28:31], v[144:147], v[28:31], v[32:35]
	s_add_u32 s100, s10, 0x11610300
	s_addc_u32 s101, s11, 0
	s_mov_b32 m0, s13
	s_nop 0
	global_load_lds_dwordx4 v240, s[100:101]
	s_waitcnt lgkmcnt(0)
	v_mfma_f32_16x16x32_bf16 v[32:35], v[140:143], v[24:27], v[36:39]
	v_mfma_f32_16x16x32_bf16 v[36:39], v[136:139], v[24:27], v[44:47]
	v_mfma_f32_16x16x32_bf16 v[40:43], v[132:135], v[24:27], v[40:43]
	v_mfma_f32_16x16x32_bf16 v[44:47], v[128:131], v[24:27], v[66:69]
	v_mfma_f32_16x16x32_bf16 v[50:53], v[124:127], v[24:27], v[50:53]
	v_mfma_f32_16x16x32_bf16 v[66:69], v[120:123], v[24:27], v[72:75]
	s_nop 2
	ds_read_b128 v[72:75], v49 offset:33792
	ds_read_b128 v[120:123], v49 offset:35840
	ds_read_b128 v[124:127], v49 offset:37888
	ds_read_b128 v[128:131], v49 offset:39936
	v_mfma_f32_16x16x32_bf16 v[76:79], v[112:115], v[24:27], v[76:79]
	ds_read_b128 v[112:115], v49 offset:41984
	ds_read_b128 v[132:135], v49 offset:44032
	ds_read_b128 v[136:139], v49 offset:46080
	ds_read_b128 v[140:143], v49 offset:48128
	v_mfma_f32_16x16x32_bf16 v[104:107], v[104:107], v[24:27], v[108:111]
	s_add_u32 s100, s10, 0x11600380
	s_addc_u32 s101, s11, 0
	s_mov_b32 m0, s12
	s_nop 0
	global_load_lds_dwordx4 v240, s[100:101]
	s_waitcnt lgkmcnt(0)
	v_mfma_f32_16x16x32_bf16 v[72:75], v[72:75], v[24:27], v[80:83]
	v_mfma_f32_16x16x32_bf16 v[80:83], v[120:123], v[24:27], v[84:87]
	v_mfma_f32_16x16x32_bf16 v[84:87], v[124:127], v[24:27], v[88:91]
	v_mfma_f32_16x16x32_bf16 v[88:91], v[128:131], v[24:27], v[92:95]
	v_mfma_f32_16x16x32_bf16 v[92:95], v[112:115], v[24:27], v[96:99]
	v_mfma_f32_16x16x32_bf16 v[96:99], v[132:135], v[24:27], v[100:103]
	s_nop 2
	ds_read_b128 v[100:103], v49 offset:30720
	ds_read_b128 v[108:111], v49 offset:28672
	ds_read_b128 v[112:115], v49 offset:26624
	ds_read_b128 v[120:123], v49 offset:24576
	v_mfma_f32_16x16x32_bf16 v[116:119], v[136:139], v[24:27], v[116:119]
	ds_read_b128 v[124:127], v49 offset:22528
	ds_read_b128 v[128:131], v49 offset:20480
	ds_read_b128 v[132:135], v49 offset:18432
	ds_read_b128 v[136:139], v49 offset:16384
	v_mfma_f32_16x16x32_bf16 v[24:27], v[140:143], v[24:27], v[28:31]
	s_add_u32 s100, s10, 0x11610380
	s_addc_u32 s101, s11, 0
	s_mov_b32 m0, s14
	s_nop 0
	global_load_lds_dwordx4 v240, s[100:101]
	s_waitcnt lgkmcnt(0)
	v_mfma_f32_16x16x32_bf16 v[28:31], v[136:139], v[20:23], v[32:35]
	v_mfma_f32_16x16x32_bf16 v[32:35], v[132:135], v[20:23], v[36:39]
	v_mfma_f32_16x16x32_bf16 v[36:39], v[128:131], v[20:23], v[40:43]
	v_mfma_f32_16x16x32_bf16 v[40:43], v[124:127], v[20:23], v[44:47]
	v_mfma_f32_16x16x32_bf16 v[44:47], v[120:123], v[20:23], v[50:53]
	v_mfma_f32_16x16x32_bf16 v[50:53], v[112:115], v[20:23], v[66:69]
	s_nop 2
	ds_read_b128 v[66:69], v49 offset:49152
	ds_read_b128 v[112:115], v49 offset:51200
	ds_read_b128 v[120:123], v49 offset:53248
	ds_read_b128 v[124:127], v49 offset:55296
	v_mfma_f32_16x16x32_bf16 v[76:79], v[108:111], v[20:23], v[76:79]
	ds_read_b128 v[108:111], v49 offset:57344
	ds_read_b128 v[128:131], v49 offset:59392
	ds_read_b128 v[132:135], v49 offset:61440
	ds_read_b128 v[136:139], v49 offset:63488
	v_mfma_f32_16x16x32_bf16 v[100:103], v[100:103], v[20:23], v[104:107]
	s_add_u32 s100, s10, 0x11620300
	s_addc_u32 s101, s11, 0
	s_mov_b32 m0, s15
	s_nop 0
	global_load_lds_dwordx4 v240, s[100:101]
	s_waitcnt lgkmcnt(0)
	v_mfma_f32_16x16x32_bf16 v[66:69], v[66:69], v[20:23], v[72:75]
	v_mfma_f32_16x16x32_bf16 v[72:75], v[112:115], v[20:23], v[80:83]
	v_mfma_f32_16x16x32_bf16 v[80:83], v[120:123], v[20:23], v[84:87]
	v_mfma_f32_16x16x32_bf16 v[84:87], v[124:127], v[20:23], v[88:91]
	v_mfma_f32_16x16x32_bf16 v[88:91], v[108:111], v[20:23], v[92:95]
	v_mfma_f32_16x16x32_bf16 v[92:95], v[128:131], v[20:23], v[96:99]
	s_nop 2
	ds_read_b128 v[96:99], v49 offset:31744
	ds_read_b128 v[104:107], v49 offset:29696
	ds_read_b128 v[108:111], v49 offset:27648
	ds_read_b128 v[112:115], v49 offset:25600
	v_mfma_f32_16x16x32_bf16 v[116:119], v[132:135], v[20:23], v[116:119]
	ds_read_b128 v[120:123], v49 offset:23552
	ds_read_b128 v[124:127], v49 offset:21504
	ds_read_b128 v[128:131], v49 offset:19456
	ds_read_b128 v[132:135], v49 offset:17408
	v_mfma_f32_16x16x32_bf16 v[20:23], v[136:139], v[20:23], v[24:27]
	s_add_u32 s100, s10, 0x11630300
	s_addc_u32 s101, s11, 0
	s_mov_b32 m0, s16
	s_nop 0
	global_load_lds_dwordx4 v240, s[100:101]
	s_waitcnt lgkmcnt(0)
	v_mfma_f32_16x16x32_bf16 v[24:27], v[132:135], v[16:19], v[28:31]
	v_mfma_f32_16x16x32_bf16 v[28:31], v[128:131], v[16:19], v[32:35]
	v_mfma_f32_16x16x32_bf16 v[32:35], v[124:127], v[16:19], v[36:39]
	v_mfma_f32_16x16x32_bf16 v[36:39], v[120:123], v[16:19], v[40:43]
	v_mfma_f32_16x16x32_bf16 v[40:43], v[112:115], v[16:19], v[44:47]
	v_mfma_f32_16x16x32_bf16 v[50:53], v[108:111], v[16:19], v[50:53]
	s_nop 1
	ds_read_b128 v[44:47], v49 offset:50176
	ds_read_b128 v[108:111], v49 offset:52224
	ds_read_b128 v[112:115], v49 offset:54272
	ds_read_b128 v[120:123], v49 offset:56320
	v_mfma_f32_16x16x32_bf16 v[76:79], v[104:107], v[16:19], v[76:79]
	ds_read_b128 v[104:107], v49 offset:58368
	ds_read_b128 v[124:127], v49 offset:60416
	ds_read_b128 v[128:131], v49 offset:62464
	ds_read_b128 v[132:135], v49 offset:64512
	v_mfma_f32_16x16x32_bf16 v[96:99], v[96:99], v[16:19], v[100:103]
	s_add_u32 s100, s10, 0x11620380
	s_addc_u32 s101, s11, 0
	s_mov_b32 m0, s17
	s_nop 0
	global_load_lds_dwordx4 v240, s[100:101]
	s_waitcnt lgkmcnt(0)
	v_mfma_f32_16x16x32_bf16 v[66:69], v[44:47], v[16:19], v[66:69]
	v_mfma_f32_16x16x32_bf16 v[72:75], v[108:111], v[16:19], v[72:75]
	v_mfma_f32_16x16x32_bf16 v[80:83], v[112:115], v[16:19], v[80:83]
	v_mfma_f32_16x16x32_bf16 v[84:87], v[120:123], v[16:19], v[84:87]
	v_mfma_f32_16x16x32_bf16 v[88:91], v[104:107], v[16:19], v[88:91]
	v_mfma_f32_16x16x32_bf16 v[92:95], v[124:127], v[16:19], v[92:95]
	v_mfma_f32_16x16x32_bf16 v[100:103], v[128:131], v[16:19], v[116:119]
	v_mfma_f32_16x16x32_bf16 v[16:19], v[132:135], v[16:19], v[20:23]
	s_add_u32 s100, s10, 0x11630380
	s_addc_u32 s101, s11, 0
	s_mov_b32 m0, s18
	s_nop 0
	global_load_lds_dwordx4 v240, s[100:101]
	s_waitcnt vmcnt(0)
	s_waitcnt vmcnt(0)
	s_barrier
	v_mov_b32_e32 v49, v48
	ds_read_b128 v[20:23], v49
	ds_read_b128 v[104:107], v49 offset:2048
	s_waitcnt lgkmcnt(0)
	v_mfma_f32_16x16x32_bf16 v[20:23], v[20:23], v[12:15], v[24:27]
	s_nop 2
	ds_read_b128 v[24:27], v49 offset:4096
	v_mfma_f32_16x16x32_bf16 v[28:31], v[104:107], v[12:15], v[28:31]
	ds_read_b128 v[104:107], v49 offset:6144
	s_waitcnt lgkmcnt(0)
	v_mfma_f32_16x16x32_bf16 v[24:27], v[24:27], v[12:15], v[32:35]
	s_nop 2
	ds_read_b128 v[32:35], v49 offset:8192
	v_mfma_f32_16x16x32_bf16 v[36:39], v[104:107], v[12:15], v[36:39]
	ds_read_b128 v[104:107], v49 offset:10240
	s_waitcnt lgkmcnt(0)
	v_mfma_f32_16x16x32_bf16 v[32:35], v[32:35], v[12:15], v[40:43]
	s_nop 2
	ds_read_b128 v[40:43], v49 offset:12288
	ds_read_b128 v[108:111], v49 offset:14336
	v_mfma_f32_16x16x32_bf16 v[50:53], v[104:107], v[12:15], v[50:53]
	ds_read_b128 v[104:107], v49 offset:32768
	ds_read_b128 v[112:115], v49 offset:34816
	ds_read_b128 v[116:119], v49 offset:36864
	ds_read_b128 v[120:123], v49 offset:38912
	s_waitcnt lgkmcnt(0)
	v_mfma_f32_16x16x32_bf16 v[40:43], v[40:43], v[12:15], v[76:79]
	s_nop 2
	ds_read_b128 v[76:79], v49 offset:40960
	ds_read_b128 v[124:127], v49 offset:43008
	ds_read_b128 v[128:131], v49 offset:45056
	ds_read_b128 v[132:135], v49 offset:47104
	v_mfma_f32_16x16x32_bf16 v[96:99], v[108:111], v[12:15], v[96:99]
	s_add_u32 s100, s10, 0x11e00000
	s_addc_u32 s101, s11, 0
	s_mov_b32 m0, s22
	s_nop 0
	global_load_lds_dwordx4 v241, s[100:101]
	v_mfma_f32_16x16x32_bf16 v[66:69], v[104:107], v[12:15], v[66:69]
	v_mfma_f32_16x16x32_bf16 v[72:75], v[112:115], v[12:15], v[72:75]
	v_mfma_f32_16x16x32_bf16 v[80:83], v[116:119], v[12:15], v[80:83]
	v_mfma_f32_16x16x32_bf16 v[84:87], v[120:123], v[12:15], v[84:87]
	s_waitcnt lgkmcnt(0)
	v_mfma_f32_16x16x32_bf16 v[76:79], v[76:79], v[12:15], v[88:91]
	v_mfma_f32_16x16x32_bf16 v[88:91], v[124:127], v[12:15], v[92:95]
	s_nop 2
	ds_read_b128 v[92:95], v49 offset:15360
	ds_read_b128 v[104:107], v49 offset:13312
	ds_read_b128 v[108:111], v49 offset:11264
	ds_read_b128 v[112:115], v49 offset:9216
	v_mfma_f32_16x16x32_bf16 v[100:103], v[128:131], v[12:15], v[100:103]
	ds_read_b128 v[116:119], v49 offset:7168
	ds_read_b128 v[120:123], v49 offset:5120
	ds_read_b128 v[124:127], v49 offset:3072
	ds_read_b128 v[128:131], v49 offset:1024
	v_mfma_f32_16x16x32_bf16 v[12:15], v[132:135], v[12:15], v[16:19]
	s_add_u32 s100, s10, 0x11e08000
	s_addc_u32 s101, s11, 0
	s_mov_b32 m0, s21
	s_nop 0
	global_load_lds_dwordx4 v241, s[100:101]
	s_waitcnt lgkmcnt(0)
	v_mfma_f32_16x16x32_bf16 v[16:19], v[128:131], v[8:11], v[20:23]
	v_mfma_f32_16x16x32_bf16 v[20:23], v[124:127], v[8:11], v[28:31]
	v_mfma_f32_16x16x32_bf16 v[24:27], v[120:123], v[8:11], v[24:27]
	v_mfma_f32_16x16x32_bf16 v[28:31], v[116:119], v[8:11], v[36:39]
	v_mfma_f32_16x16x32_bf16 v[32:35], v[112:115], v[8:11], v[32:35]
	v_mfma_f32_16x16x32_bf16 v[36:39], v[108:111], v[8:11], v[50:53]
	s_nop 2
	ds_read_b128 v[50:53], v49 offset:33792
	ds_read_b128 v[108:111], v49 offset:35840
	ds_read_b128 v[112:115], v49 offset:37888
	ds_read_b128 v[116:119], v49 offset:39936
	v_mfma_f32_16x16x32_bf16 v[40:43], v[104:107], v[8:11], v[40:43]
	ds_read_b128 v[104:107], v49 offset:41984
	ds_read_b128 v[120:123], v49 offset:44032
	ds_read_b128 v[124:127], v49 offset:46080
	ds_read_b128 v[128:131], v49 offset:48128
	v_mfma_f32_16x16x32_bf16 v[92:95], v[92:95], v[8:11], v[96:99]
	s_add_u32 s100, s10, 0x11e00080
	s_addc_u32 s101, s11, 0
	s_mov_b32 m0, s20
	s_nop 0
	global_load_lds_dwordx4 v241, s[100:101]
	s_waitcnt lgkmcnt(0)
	v_mfma_f32_16x16x32_bf16 v[50:53], v[50:53], v[8:11], v[66:69]
	v_mfma_f32_16x16x32_bf16 v[66:69], v[108:111], v[8:11], v[72:75]
	v_mfma_f32_16x16x32_bf16 v[72:75], v[112:115], v[8:11], v[80:83]
	v_mfma_f32_16x16x32_bf16 v[80:83], v[116:119], v[8:11], v[84:87]
	v_mfma_f32_16x16x32_bf16 v[76:79], v[104:107], v[8:11], v[76:79]
	v_mfma_f32_16x16x32_bf16 v[84:87], v[120:123], v[8:11], v[88:91]
	s_nop 2
	ds_read_b128 v[88:91], v49 offset:30720
	ds_read_b128 v[96:99], v49 offset:28672
	ds_read_b128 v[104:107], v49 offset:26624
	ds_read_b128 v[108:111], v49 offset:24576
	v_mfma_f32_16x16x32_bf16 v[100:103], v[124:127], v[8:11], v[100:103]
	ds_read_b128 v[112:115], v49 offset:22528
	ds_read_b128 v[116:119], v49 offset:20480
	ds_read_b128 v[120:123], v49 offset:18432
	ds_read_b128 v[124:127], v49 offset:16384
	v_mfma_f32_16x16x32_bf16 v[8:11], v[128:131], v[8:11], v[12:15]
	s_add_u32 s100, s10, 0x11e08080
	s_addc_u32 s101, s11, 0
	s_mov_b32 m0, s23
	s_nop 0
	global_load_lds_dwordx4 v241, s[100:101]
	s_waitcnt lgkmcnt(0)
	v_mfma_f32_16x16x32_bf16 v[12:15], v[124:127], v[4:7], v[16:19]
	v_mfma_f32_16x16x32_bf16 v[16:19], v[120:123], v[4:7], v[20:23]
	v_mfma_f32_16x16x32_bf16 v[20:23], v[116:119], v[4:7], v[24:27]
	v_mfma_f32_16x16x32_bf16 v[24:27], v[112:115], v[4:7], v[28:31]
	v_mfma_f32_16x16x32_bf16 v[28:31], v[108:111], v[4:7], v[32:35]
	v_mfma_f32_16x16x32_bf16 v[32:35], v[104:107], v[4:7], v[36:39]
	s_nop 2
	ds_read_b128 v[36:39], v49 offset:49152
	ds_read_b128 v[104:107], v49 offset:51200
	ds_read_b128 v[108:111], v49 offset:53248
	ds_read_b128 v[112:115], v49 offset:55296
	v_mfma_f32_16x16x32_bf16 v[96:99], v[96:99], v[4:7], v[40:43]
	s_nop 2
	ds_read_b128 v[40:43], v49 offset:57344
	ds_read_b128 v[116:119], v49 offset:59392
	ds_read_b128 v[120:123], v49 offset:61440
	ds_read_b128 v[124:127], v49 offset:63488
	v_mfma_f32_16x16x32_bf16 v[88:91], v[88:91], v[4:7], v[92:95]
	s_add_u32 s100, s10, 0x11e10000
	s_addc_u32 s101, s11, 0
	s_mov_b32 m0, s24
	s_nop 0
	global_load_lds_dwordx4 v241, s[100:101]
	s_waitcnt lgkmcnt(0)
	v_mfma_f32_16x16x32_bf16 v[50:53], v[36:39], v[4:7], v[50:53]
	v_mfma_f32_16x16x32_bf16 v[66:69], v[104:107], v[4:7], v[66:69]
	v_mfma_f32_16x16x32_bf16 v[72:75], v[108:111], v[4:7], v[72:75]
	v_mfma_f32_16x16x32_bf16 v[80:83], v[112:115], v[4:7], v[80:83]
	v_mfma_f32_16x16x32_bf16 v[76:79], v[40:43], v[4:7], v[76:79]
	ds_read_b128 v[92:95], v49 offset:31744
	ds_read_b128 v[36:39], v49 offset:29696
	ds_read_b128 v[40:43], v49 offset:27648
	ds_read_b128 v[104:107], v49 offset:25600
	v_mfma_f32_16x16x32_bf16 v[84:87], v[116:119], v[4:7], v[84:87]
	v_mfma_f32_16x16x32_bf16 v[100:103], v[120:123], v[4:7], v[100:103]
	ds_read_b128 v[108:111], v49 offset:23552
	ds_read_b128 v[112:115], v49 offset:21504
	ds_read_b128 v[116:119], v49 offset:19456
	ds_read_b128 v[120:123], v49 offset:17408
	v_mfma_f32_16x16x32_bf16 v[124:127], v[124:127], v[4:7], v[8:11]
	s_add_u32 s100, s10, 0x11e18000
	s_addc_u32 s101, s11, 0
	s_mov_b32 m0, s25
	s_nop 0
	global_load_lds_dwordx4 v241, s[100:101]
	s_waitcnt lgkmcnt(0)
	v_mfma_f32_16x16x32_bf16 v[120:123], v[120:123], v[0:3], v[12:15]
	v_mfma_f32_16x16x32_bf16 v[116:119], v[116:119], v[0:3], v[16:19]
	ds_read_b128 v[4:7], v49 offset:50176
	ds_read_b128 v[8:11], v49 offset:52224
	ds_read_b128 v[12:15], v49 offset:54272
	ds_read_b128 v[16:19], v49 offset:56320
	v_mfma_f32_16x16x32_bf16 v[36:39], v[36:39], v[0:3], v[96:99]
	s_nop 2
	ds_read_b128 v[96:99], v49 offset:58368
	ds_read_b128 v[128:131], v49 offset:60416
	ds_read_b128 v[132:135], v49 offset:62464
	ds_read_b128 v[136:139], v49 offset:64512
	v_mfma_f32_16x16x32_bf16 v[112:115], v[112:115], v[0:3], v[20:23]
	v_mfma_f32_16x16x32_bf16 v[108:111], v[108:111], v[0:3], v[24:27]
	v_mfma_f32_16x16x32_bf16 v[104:107], v[104:107], v[0:3], v[28:31]
	v_mfma_f32_16x16x32_bf16 v[40:43], v[40:43], v[0:3], v[32:35]
	v_mfma_f32_16x16x32_bf16 v[32:35], v[92:95], v[0:3], v[88:91]
	s_add_u32 s100, s10, 0x11e10080
	s_addc_u32 s101, s11, 0
	s_mov_b32 m0, s26
	s_nop 0
	global_load_lds_dwordx4 v241, s[100:101]
	s_waitcnt lgkmcnt(0)
	v_mfma_f32_16x16x32_bf16 v[28:31], v[4:7], v[0:3], v[50:53]
	v_mfma_f32_16x16x32_bf16 v[24:27], v[8:11], v[0:3], v[66:69]
	v_mfma_f32_16x16x32_bf16 v[20:23], v[12:15], v[0:3], v[72:75]
	v_mfma_f32_16x16x32_bf16 v[16:19], v[16:19], v[0:3], v[80:83]
	v_mfma_f32_16x16x32_bf16 v[12:15], v[96:99], v[0:3], v[76:79]
	v_mfma_f32_16x16x32_bf16 v[8:11], v[128:131], v[0:3], v[84:87]
	v_mfma_f32_16x16x32_bf16 v[4:7], v[132:135], v[0:3], v[100:103]
	v_mfma_f32_16x16x32_bf16 v[0:3], v[136:139], v[0:3], v[124:127]
	s_add_u32 s100, s10, 0x11e18080
	s_addc_u32 s101, s11, 0
	s_mov_b32 m0, s27
	s_nop 0
	global_load_lds_dwordx4 v241, s[100:101]
	v_max_f32_e32 v49, v123, v123
	v_max_f32_e32 v50, v122, v122
	v_max_f32_e32 v49, v50, v49
	v_max_f32_e32 v50, v117, v117
	v_max_f32_e32 v51, v116, v116
	v_max_f32_e32 v50, v51, v50
	v_max_f32_e32 v51, v119, v119
	v_max_f32_e32 v52, v118, v118
	v_max3_f32 v49, v120, v121, v49
	v_max_f32_e32 v51, v52, v51
	v_max3_f32 v49, v49, v50, v51
	v_max_f32_e32 v50, v113, v113
	v_max_f32_e32 v51, v112, v112
	v_max_f32_e32 v50, v51, v50
	v_max_f32_e32 v51, v115, v115
	v_max_f32_e32 v52, v114, v114
	v_max_f32_e32 v51, v52, v51
	v_max3_f32 v49, v49, v50, v51
	v_max_f32_e32 v50, v109, v109
	v_max_f32_e32 v51, v108, v108
	v_max_f32_e32 v50, v51, v50
	v_max_f32_e32 v51, v111, v111
	v_max_f32_e32 v52, v110, v110
	v_max_f32_e32 v51, v52, v51
	v_max3_f32 v49, v49, v50, v51
	v_max_f32_e32 v50, v105, v105
	v_max_f32_e32 v51, v104, v104
	v_max_f32_e32 v50, v51, v50
	v_max_f32_e32 v51, v107, v107
	v_max_f32_e32 v52, v106, v106
	v_max_f32_e32 v51, v52, v51
	v_max3_f32 v49, v49, v50, v51
	v_max_f32_e32 v50, v41, v41
	v_max_f32_e32 v51, v40, v40
	v_max_f32_e32 v50, v51, v50
	v_max_f32_e32 v51, v43, v43
	v_max_f32_e32 v52, v42, v42
	v_max_f32_e32 v51, v52, v51
	v_max3_f32 v49, v49, v50, v51
	v_max_f32_e32 v50, v37, v37
	v_max_f32_e32 v51, v36, v36
	v_max_f32_e32 v50, v51, v50
	v_max_f32_e32 v51, v39, v39
	v_max_f32_e32 v52, v38, v38
	v_max_f32_e32 v51, v52, v51
	v_max3_f32 v49, v49, v50, v51
	v_max_f32_e32 v50, v33, v33
	v_max_f32_e32 v51, v32, v32
	v_max_f32_e32 v50, v51, v50
	v_max_f32_e32 v51, v35, v35
	v_max_f32_e32 v52, v34, v34
	v_max_f32_e32 v51, v52, v51
	v_max3_f32 v49, v49, v50, v51
	v_max_f32_e32 v50, v29, v29
	v_max_f32_e32 v51, v28, v28
	v_max_f32_e32 v50, v51, v50
	v_max_f32_e32 v51, v31, v31
	v_max_f32_e32 v52, v30, v30
	v_max_f32_e32 v51, v52, v51
	v_max3_f32 v49, v49, v50, v51
	v_max_f32_e32 v50, v25, v25
	v_max_f32_e32 v51, v24, v24
	v_max_f32_e32 v50, v51, v50
	v_max_f32_e32 v51, v27, v27
	v_max_f32_e32 v52, v26, v26
	v_max_f32_e32 v51, v52, v51
	v_max3_f32 v49, v49, v50, v51
	v_max_f32_e32 v50, v21, v21
	v_max_f32_e32 v51, v20, v20
	v_max_f32_e32 v50, v51, v50
	v_max_f32_e32 v51, v23, v23
	v_max_f32_e32 v52, v22, v22
	v_max_f32_e32 v51, v52, v51
	v_max3_f32 v49, v49, v50, v51
	v_max_f32_e32 v50, v17, v17
	v_max_f32_e32 v51, v16, v16
	v_max_f32_e32 v50, v51, v50
	v_max_f32_e32 v51, v19, v19
	v_max_f32_e32 v52, v18, v18
	v_max_f32_e32 v51, v52, v51
	v_max3_f32 v49, v49, v50, v51
	v_max_f32_e32 v50, v13, v13
	v_max_f32_e32 v51, v12, v12
	v_max_f32_e32 v50, v51, v50
	v_max_f32_e32 v51, v15, v15
	v_max_f32_e32 v52, v14, v14
	v_max_f32_e32 v51, v52, v51
	v_max3_f32 v49, v49, v50, v51
	v_max_f32_e32 v50, v9, v9
	v_max_f32_e32 v51, v8, v8
	v_max_f32_e32 v50, v51, v50
	v_max_f32_e32 v51, v11, v11
	v_max_f32_e32 v52, v10, v10
	v_max_f32_e32 v51, v52, v51
	v_max3_f32 v49, v49, v50, v51
	v_max_f32_e32 v50, v5, v5
	v_max_f32_e32 v51, v4, v4
	v_max_f32_e32 v50, v51, v50
	v_max_f32_e32 v51, v7, v7
	v_max_f32_e32 v52, v6, v6
	v_max_f32_e32 v51, v52, v51
	v_max3_f32 v49, v49, v50, v51
	v_max_f32_e32 v50, v1, v1
	v_max_f32_e32 v51, v0, v0
	v_max_f32_e32 v50, v51, v50
	v_max_f32_e32 v51, v3, v3
	v_max_f32_e32 v52, v2, v2
	v_max_f32_e32 v51, v52, v51
	v_max3_f32 v49, v49, v50, v51
	v_mbcnt_lo_u32_b32 v50, -1, 0
	v_mbcnt_hi_u32_b32 v50, -1, v50
	v_and_b32_e32 v52, 64, v50
	v_xor_b32_e32 v51, 16, v50
	v_add_u32_e32 v52, 64, v52
	v_cmp_lt_i32_e32 vcc, v51, v52
	s_nop 1
	v_cndmask_b32_e32 v51, v50, v51, vcc
	v_lshlrev_b32_e32 v51, 2, v51
	ds_bpermute_b32 v53, v51, v49
	s_waitcnt lgkmcnt(0)
	v_max_f32_e32 v53, v53, v53
	v_max_f32_e32 v49, v49, v53
	v_xor_b32_e32 v53, 32, v50
	v_cmp_lt_i32_e32 vcc, v53, v52
	s_nop 1
	v_cndmask_b32_e32 v50, v50, v53, vcc
	v_lshlrev_b32_e32 v50, 2, v50
	ds_bpermute_b32 v52, v50, v49
	s_waitcnt lgkmcnt(0)
	v_max_f32_e32 v52, v52, v52
	v_max_f32_e32 v49, v49, v52
	v_sub_f32_e32 v52, v120, v49
	v_exp_f32_e32 v52, v52
	v_sub_f32_e32 v53, v121, v49
	v_exp_f32_e32 v53, v53
	v_sub_f32_e32 v54, v122, v49
	v_exp_f32_e32 v54, v54
	v_sub_f32_e32 v55, v123, v49
	v_exp_f32_e32 v55, v55
	v_sub_f32_e32 v59, v116, v49
	v_add_f32_e32 v57, 0, v52
	v_exp_f32_e32 v59, v59
	v_sub_f32_e32 v62, v117, v49
	v_add_f32_e32 v57, v53, v57
	v_exp_f32_e32 v62, v62
	v_sub_f32_e32 v63, v118, v49
	v_add_f32_e32 v57, v54, v57
	v_exp_f32_e32 v63, v63
	v_sub_f32_e32 v64, v119, v49
	v_add_f32_e32 v57, v55, v57
	v_exp_f32_e32 v64, v64
	v_sub_f32_e32 v66, v112, v49
	v_add_f32_e32 v57, v59, v57
	v_exp_f32_e32 v66, v66
	v_sub_f32_e32 v67, v113, v49
	v_add_f32_e32 v57, v62, v57
	v_exp_f32_e32 v67, v67
	v_sub_f32_e32 v68, v114, v49
	v_add_f32_e32 v57, v63, v57
	v_exp_f32_e32 v68, v68
	v_sub_f32_e32 v69, v115, v49
	v_add_f32_e32 v57, v64, v57
	v_exp_f32_e32 v69, v69
	v_sub_f32_e32 v71, v108, v49
	v_add_f32_e32 v57, v66, v57
	v_exp_f32_e32 v71, v71
	v_sub_f32_e32 v72, v109, v49
	v_add_f32_e32 v57, v67, v57
	v_exp_f32_e32 v72, v72
	v_sub_f32_e32 v73, v110, v49
	v_add_f32_e32 v57, v68, v57
	v_exp_f32_e32 v73, v73
	v_sub_f32_e32 v74, v111, v49
	v_add_f32_e32 v57, v69, v57
	v_exp_f32_e32 v74, v74
	v_sub_f32_e32 v75, v104, v49
	v_add_f32_e32 v57, v71, v57
	v_exp_f32_e32 v75, v75
	v_sub_f32_e32 v76, v105, v49
	v_add_f32_e32 v57, v72, v57
	v_exp_f32_e32 v76, v76
	v_sub_f32_e32 v77, v106, v49
	v_add_f32_e32 v57, v73, v57
	v_exp_f32_e32 v77, v77
	v_sub_f32_e32 v78, v107, v49
	v_add_f32_e32 v57, v74, v57
	v_exp_f32_e32 v78, v78
	v_sub_f32_e32 v40, v40, v49
	v_add_f32_e32 v57, v75, v57
	v_exp_f32_e32 v40, v40
	v_sub_f32_e32 v41, v41, v49
	v_add_f32_e32 v57, v76, v57
	v_exp_f32_e32 v41, v41
	v_sub_f32_e32 v42, v42, v49
	v_add_f32_e32 v57, v77, v57
	v_exp_f32_e32 v42, v42
	v_sub_f32_e32 v43, v43, v49
	v_add_f32_e32 v57, v78, v57
	v_exp_f32_e32 v43, v43
	v_sub_f32_e32 v36, v36, v49
	v_add_f32_e32 v57, v40, v57
	v_exp_f32_e32 v36, v36
	v_sub_f32_e32 v37, v37, v49
	v_add_f32_e32 v57, v41, v57
	v_exp_f32_e32 v37, v37
	v_sub_f32_e32 v38, v38, v49
	v_add_f32_e32 v57, v42, v57
	v_exp_f32_e32 v38, v38
	v_sub_f32_e32 v39, v39, v49
	v_add_f32_e32 v57, v43, v57
	v_exp_f32_e32 v39, v39
	v_sub_f32_e32 v32, v32, v49
	v_add_f32_e32 v57, v36, v57
	v_exp_f32_e32 v32, v32
	v_sub_f32_e32 v33, v33, v49
	v_add_f32_e32 v57, v37, v57
	v_exp_f32_e32 v33, v33
	v_sub_f32_e32 v34, v34, v49
	v_add_f32_e32 v57, v38, v57
	v_exp_f32_e32 v34, v34
	v_sub_f32_e32 v35, v35, v49
	v_add_f32_e32 v57, v39, v57
	v_exp_f32_e32 v35, v35
	v_sub_f32_e32 v28, v28, v49
	v_add_f32_e32 v57, v32, v57
	v_exp_f32_e32 v79, v28
	v_sub_f32_e32 v28, v29, v49
	v_add_f32_e32 v57, v33, v57
	v_exp_f32_e32 v80, v28
	v_sub_f32_e32 v28, v30, v49
	v_add_f32_e32 v57, v34, v57
	v_exp_f32_e32 v81, v28
	v_sub_f32_e32 v28, v31, v49
	v_add_f32_e32 v57, v35, v57
	v_exp_f32_e32 v82, v28
	v_sub_f32_e32 v24, v24, v49
	v_add_f32_e32 v28, v79, v57
	v_exp_f32_e32 v57, v24
	v_sub_f32_e32 v24, v25, v49
	v_add_f32_e32 v28, v80, v28
	v_exp_f32_e32 v83, v24
	v_sub_f32_e32 v24, v26, v49
	v_add_f32_e32 v28, v81, v28
	v_exp_f32_e32 v84, v24
	v_sub_f32_e32 v24, v27, v49
	v_add_f32_e32 v28, v82, v28
	v_exp_f32_e32 v85, v24
	v_sub_f32_e32 v20, v20, v49
	v_add_f32_e32 v24, v57, v28
	v_exp_f32_e32 v86, v20
	v_sub_f32_e32 v20, v21, v49
	v_add_f32_e32 v24, v83, v24
	v_exp_f32_e32 v87, v20
	v_sub_f32_e32 v20, v22, v49
	v_add_f32_e32 v24, v84, v24
	v_exp_f32_e32 v88, v20
	v_sub_f32_e32 v20, v23, v49
	v_add_f32_e32 v24, v85, v24
	v_exp_f32_e32 v89, v20
	v_sub_f32_e32 v16, v16, v49
	v_add_f32_e32 v20, v86, v24
	v_exp_f32_e32 v90, v16
	v_sub_f32_e32 v16, v17, v49
	v_add_f32_e32 v20, v87, v20
	v_exp_f32_e32 v91, v16
	v_sub_f32_e32 v16, v18, v49
	v_add_f32_e32 v20, v88, v20
	v_exp_f32_e32 v92, v16
	v_sub_f32_e32 v16, v19, v49
	v_add_f32_e32 v20, v89, v20
	v_exp_f32_e32 v93, v16
	v_sub_f32_e32 v12, v12, v49
	v_add_f32_e32 v16, v90, v20
	v_exp_f32_e32 v94, v12
	v_sub_f32_e32 v12, v13, v49
	v_add_f32_e32 v16, v91, v16
	v_exp_f32_e32 v95, v12
	v_sub_f32_e32 v12, v14, v49
	v_add_f32_e32 v16, v92, v16
	v_exp_f32_e32 v96, v12
	v_sub_f32_e32 v12, v15, v49
	v_add_f32_e32 v16, v93, v16
	v_exp_f32_e32 v97, v12
	v_sub_f32_e32 v8, v8, v49
	v_add_f32_e32 v12, v94, v16
	v_exp_f32_e32 v98, v8
	v_sub_f32_e32 v8, v9, v49
	v_add_f32_e32 v12, v95, v12
	v_exp_f32_e32 v99, v8
	v_sub_f32_e32 v8, v10, v49
	v_add_f32_e32 v12, v96, v12
	v_exp_f32_e32 v100, v8
	v_sub_f32_e32 v8, v11, v49
	v_add_f32_e32 v12, v97, v12
	v_exp_f32_e32 v11, v8
	v_sub_f32_e32 v4, v4, v49
	v_add_f32_e32 v8, v98, v12
	v_exp_f32_e32 v101, v4
	v_sub_f32_e32 v4, v5, v49
	v_add_f32_e32 v8, v99, v8
	v_exp_f32_e32 v102, v4
	v_sub_f32_e32 v4, v6, v49
	v_add_f32_e32 v8, v100, v8
	v_exp_f32_e32 v103, v4
	v_sub_f32_e32 v4, v7, v49
	v_add_f32_e32 v8, v11, v8
	v_exp_f32_e32 v104, v4
	v_sub_f32_e32 v0, v0, v49
	v_add_f32_e32 v4, v101, v8
	v_exp_f32_e32 v105, v0
	v_sub_f32_e32 v0, v1, v49
	v_add_f32_e32 v4, v102, v4
	v_exp_f32_e32 v106, v0
	v_sub_f32_e32 v0, v2, v49
	v_add_f32_e32 v4, v103, v4
	v_exp_f32_e32 v107, v0
	v_sub_f32_e32 v0, v3, v49
	v_add_f32_e32 v4, v104, v4
	v_exp_f32_e32 v3, v0
	v_add_f32_e32 v0, v105, v4
	v_add_f32_e32 v0, v106, v0
	v_add_f32_e32 v0, v107, v0
	v_add_f32_e32 v0, v3, v0
	ds_bpermute_b32 v1, v51, v0
	v_cvt_pk_bf16_f32 v28, v52, v53
	v_cvt_pk_bf16_f32 v29, v54, v55
	v_cvt_pk_bf16_f32 v30, v59, v62
	v_cvt_pk_bf16_f32 v31, v63, v64
	s_waitcnt lgkmcnt(0)
	v_add_f32_e32 v0, v0, v1
	ds_bpermute_b32 v1, v50, v0
	v_cvt_pk_bf16_f32 v20, v66, v67
	v_cvt_pk_bf16_f32 v21, v68, v69
	v_cvt_pk_bf16_f32 v22, v71, v72
	v_cvt_pk_bf16_f32 v23, v73, v74
	s_waitcnt lgkmcnt(0)
	v_add_f32_e32 v49, v0, v1
	v_cvt_pk_bf16_f32 v24, v75, v76
	v_cvt_pk_bf16_f32 v25, v77, v78
	v_cvt_pk_bf16_f32 v26, v40, v41
	v_cvt_pk_bf16_f32 v27, v42, v43
	v_cvt_pk_bf16_f32 v16, v36, v37
	v_cvt_pk_bf16_f32 v17, v38, v39
	v_cvt_pk_bf16_f32 v18, v32, v33
	v_cvt_pk_bf16_f32 v19, v34, v35
	v_cvt_pk_bf16_f32 v12, v79, v80
	v_cvt_pk_bf16_f32 v13, v81, v82
	v_cvt_pk_bf16_f32 v14, v57, v83
	v_cvt_pk_bf16_f32 v15, v84, v85
	v_cvt_pk_bf16_f32 v4, v86, v87
	v_cvt_pk_bf16_f32 v5, v88, v89
	v_cvt_pk_bf16_f32 v6, v90, v91
	v_cvt_pk_bf16_f32 v7, v92, v93
	v_cvt_pk_bf16_f32 v8, v94, v95
	v_cvt_pk_bf16_f32 v9, v96, v97
	v_cvt_pk_bf16_f32 v10, v98, v99
	v_cvt_pk_bf16_f32 v11, v100, v11
	v_cvt_pk_bf16_f32 v0, v101, v102
	v_cvt_pk_bf16_f32 v1, v103, v104
	v_cvt_pk_bf16_f32 v2, v105, v106
	v_cvt_pk_bf16_f32 v3, v107, v3
	s_waitcnt vmcnt(0)
	s_waitcnt vmcnt(0)
	s_barrier
	v_mov_b32_e32 v64, v65
	v_div_scale_f32 v62, vcc, 1.0, v49, 1.0
	v_lshlrev_b32_e32 v54, 2, v70
	v_ashrrev_i32_e32 v55, 31, v54
	ds_read_b128 v[32:35], v64
	ds_read_b128 v[36:39], v64 offset:2048
	v_div_scale_f32 v57, s[0:1], v49, v49, 1.0
	v_rcp_f32_e32 v59, v57
	s_waitcnt lgkmcnt(0)
	v_mfma_f32_16x16x32_bf16 v[44:47], v[32:35], v[28:31], 0
	v_fma_f32 v40, -v57, v59, 1.0
	v_fmac_f32_e32 v59, v40, v59
	ds_read_b128 v[40:43], v64 offset:4096
	ds_read_b128 v[32:35], v64 offset:6144
	v_mul_f32_e32 v63, v62, v59
	v_fma_f32 v66, -v57, v63, v62
	v_fmac_f32_e32 v63, v66, v59
	v_mfma_f32_16x16x32_bf16 v[50:53], v[36:39], v[28:31], 0
	v_fma_f32 v36, -v57, v63, v62
	ds_read_b128 v[66:69], v64 offset:8192
	ds_read_b128 v[70:73], v64 offset:10240
	v_div_fmas_f32 v36, v36, v59, v63
	s_waitcnt lgkmcnt(0)
	v_mfma_f32_16x16x32_bf16 v[74:77], v[32:35], v[28:31], 0
	v_lshl_add_u64 v[34:35], v[54:55], 1, v[60:61]
	ds_read_b128 v[60:63], v64 offset:12288
	ds_read_b128 v[78:81], v64 offset:14336
	ds_read_b128 v[82:85], v64 offset:32768
	ds_read_b128 v[86:89], v64 offset:34816
	ds_read_b128 v[90:93], v64 offset:36864
	ds_read_b128 v[94:97], v64 offset:38912
	ds_read_b128 v[98:101], v64 offset:40960
	ds_read_b128 v[102:105], v64 offset:43008
	ds_read_b128 v[106:109], v64 offset:45056
	ds_read_b128 v[110:113], v64 offset:47104
	s_mov_b64 s[0:1], 0x1000000
	v_mfma_f32_16x16x32_bf16 v[38:41], v[40:43], v[28:31], 0
	v_div_fixup_f32 v36, v36, v49, 1.0
	v_lshl_add_u64 v[32:33], v[34:35], 0, s[0:1]
	v_mfma_f32_16x16x32_bf16 v[66:69], v[66:69], v[28:31], 0
	v_mfma_f32_16x16x32_bf16 v[70:73], v[70:73], v[28:31], 0
	s_waitcnt lgkmcnt(0)
	v_mfma_f32_16x16x32_bf16 v[60:63], v[60:63], v[28:31], 0
	v_mfma_f32_16x16x32_bf16 v[78:81], v[78:81], v[28:31], 0
	s_add_u32 s100, s10, 0x11e00100
	s_addc_u32 s101, s11, 0
	s_mov_b32 m0, s19
	s_nop 0
	global_load_lds_dwordx4 v241, s[100:101]
	ds_read_b128 v[114:117], v64 offset:30720
	ds_read_b128 v[118:121], v64 offset:28672
	ds_read_b128 v[122:125], v64 offset:26624
	ds_read_b128 v[126:129], v64 offset:24576
	ds_read_b128 v[130:133], v64 offset:22528
	ds_read_b128 v[134:137], v64 offset:20480
	ds_read_b128 v[138:141], v64 offset:18432
	ds_read_b128 v[142:145], v64 offset:16384
	v_mfma_f32_16x16x32_bf16 v[82:85], v[82:85], v[28:31], 0
	v_mfma_f32_16x16x32_bf16 v[86:89], v[86:89], v[28:31], 0
	v_mfma_f32_16x16x32_bf16 v[90:93], v[90:93], v[28:31], 0
	v_mfma_f32_16x16x32_bf16 v[94:97], v[94:97], v[28:31], 0
	v_mfma_f32_16x16x32_bf16 v[98:101], v[98:101], v[28:31], 0
	v_mfma_f32_16x16x32_bf16 v[102:105], v[102:105], v[28:31], 0
	v_mfma_f32_16x16x32_bf16 v[106:109], v[106:109], v[28:31], 0
	v_mfma_f32_16x16x32_bf16 v[110:113], v[110:113], v[28:31], 0
	s_add_u32 s100, s10, 0x11e08100
	s_addc_u32 s101, s11, 0
	s_mov_b32 m0, s13
	s_nop 0
	global_load_lds_dwordx4 v241, s[100:101]
	s_waitcnt lgkmcnt(0)
	v_mfma_f32_16x16x32_bf16 v[42:45], v[142:145], v[24:27], v[44:47]
	v_mfma_f32_16x16x32_bf16 v[50:53], v[138:141], v[24:27], v[50:53]
	v_mfma_f32_16x16x32_bf16 v[38:41], v[134:137], v[24:27], v[38:41]
	v_mfma_f32_16x16x32_bf16 v[74:77], v[130:133], v[24:27], v[74:77]
	v_mfma_f32_16x16x32_bf16 v[66:69], v[126:129], v[24:27], v[66:69]
	v_mfma_f32_16x16x32_bf16 v[70:73], v[122:125], v[24:27], v[70:73]
	ds_read_b128 v[122:125], v64 offset:49152
	ds_read_b128 v[126:129], v64 offset:51200
	ds_read_b128 v[130:133], v64 offset:53248
	ds_read_b128 v[134:137], v64 offset:55296
	v_mfma_f32_16x16x32_bf16 v[60:63], v[118:121], v[24:27], v[60:63]
	ds_read_b128 v[118:121], v64 offset:57344
	ds_read_b128 v[138:141], v64 offset:59392
	ds_read_b128 v[142:145], v64 offset:61440
	ds_read_b128 v[146:149], v64 offset:63488
	v_mfma_f32_16x16x32_bf16 v[78:81], v[114:117], v[24:27], v[78:81]
	s_add_u32 s100, s10, 0x11e00180
	s_addc_u32 s101, s11, 0
	s_mov_b32 m0, s12
	s_nop 0
	global_load_lds_dwordx4 v241, s[100:101]
	s_waitcnt lgkmcnt(0)
	v_mfma_f32_16x16x32_bf16 v[82:85], v[122:125], v[24:27], v[82:85]
	v_mfma_f32_16x16x32_bf16 v[86:89], v[126:129], v[24:27], v[86:89]
	v_mfma_f32_16x16x32_bf16 v[90:93], v[130:133], v[24:27], v[90:93]
	v_mfma_f32_16x16x32_bf16 v[94:97], v[134:137], v[24:27], v[94:97]
	v_mfma_f32_16x16x32_bf16 v[98:101], v[118:121], v[24:27], v[98:101]
	ds_read_b128 v[114:117], v64 offset:15360
	ds_read_b128 v[118:121], v64 offset:13312
	ds_read_b128 v[122:125], v64 offset:11264
	ds_read_b128 v[126:129], v64 offset:9216
	v_mfma_f32_16x16x32_bf16 v[102:105], v[138:141], v[24:27], v[102:105]
	v_mfma_f32_16x16x32_bf16 v[106:109], v[142:145], v[24:27], v[106:109]
	ds_read_b128 v[130:133], v64 offset:7168
	ds_read_b128 v[134:137], v64 offset:5120
	ds_read_b128 v[138:141], v64 offset:3072
	ds_read_b128 v[142:145], v64 offset:1024
	v_mfma_f32_16x16x32_bf16 v[110:113], v[146:149], v[24:27], v[110:113]
	s_add_u32 s100, s10, 0x11e08180
	s_addc_u32 s101, s11, 0
	s_mov_b32 m0, s14
	s_nop 0
	global_load_lds_dwordx4 v241, s[100:101]
	s_waitcnt lgkmcnt(0)
	v_mfma_f32_16x16x32_bf16 v[42:45], v[142:145], v[20:23], v[42:45]
	v_mfma_f32_16x16x32_bf16 v[50:53], v[138:141], v[20:23], v[50:53]
	v_mfma_f32_16x16x32_bf16 v[38:41], v[134:137], v[20:23], v[38:41]
	v_mfma_f32_16x16x32_bf16 v[74:77], v[130:133], v[20:23], v[74:77]
	v_mfma_f32_16x16x32_bf16 v[66:69], v[126:129], v[20:23], v[66:69]
	v_mfma_f32_16x16x32_bf16 v[70:73], v[122:125], v[20:23], v[70:73]
	ds_read_b128 v[122:125], v64 offset:33792
	ds_read_b128 v[126:129], v64 offset:35840
	ds_read_b128 v[130:133], v64 offset:37888
	ds_read_b128 v[134:137], v64 offset:39936
	v_mfma_f32_16x16x32_bf16 v[60:63], v[118:121], v[20:23], v[60:63]
	ds_read_b128 v[118:121], v64 offset:41984
	ds_read_b128 v[138:141], v64 offset:44032
	ds_read_b128 v[142:145], v64 offset:46080
	ds_read_b128 v[146:149], v64 offset:48128
	v_mfma_f32_16x16x32_bf16 v[78:81], v[114:117], v[20:23], v[78:81]
	s_add_u32 s100, s10, 0x11e10100
	s_addc_u32 s101, s11, 0
	s_mov_b32 m0, s15
	s_nop 0
	global_load_lds_dwordx4 v241, s[100:101]
	s_waitcnt lgkmcnt(0)
	v_mfma_f32_16x16x32_bf16 v[82:85], v[122:125], v[20:23], v[82:85]
	v_mfma_f32_16x16x32_bf16 v[86:89], v[126:129], v[20:23], v[86:89]
	v_mfma_f32_16x16x32_bf16 v[90:93], v[130:133], v[20:23], v[90:93]
	v_mfma_f32_16x16x32_bf16 v[94:97], v[134:137], v[20:23], v[94:97]
	v_mfma_f32_16x16x32_bf16 v[98:101], v[118:121], v[20:23], v[98:101]
	ds_read_b128 v[114:117], v64 offset:31744
	ds_read_b128 v[118:121], v64 offset:29696
	ds_read_b128 v[122:125], v64 offset:27648
	ds_read_b128 v[126:129], v64 offset:25600
	v_mfma_f32_16x16x32_bf16 v[102:105], v[138:141], v[20:23], v[102:105]
	v_mfma_f32_16x16x32_bf16 v[106:109], v[142:145], v[20:23], v[106:109]
	ds_read_b128 v[130:133], v64 offset:23552
	ds_read_b128 v[134:137], v64 offset:21504
	ds_read_b128 v[138:141], v64 offset:19456
	ds_read_b128 v[142:145], v64 offset:17408
	v_mfma_f32_16x16x32_bf16 v[110:113], v[146:149], v[20:23], v[110:113]
	s_add_u32 s100, s10, 0x11e18100
	s_addc_u32 s101, s11, 0
	s_mov_b32 m0, s16
	s_nop 0
	global_load_lds_dwordx4 v241, s[100:101]
	s_waitcnt lgkmcnt(0)
	v_mfma_f32_16x16x32_bf16 v[42:45], v[142:145], v[16:19], v[42:45]
	v_mfma_f32_16x16x32_bf16 v[50:53], v[138:141], v[16:19], v[50:53]
	v_mfma_f32_16x16x32_bf16 v[38:41], v[134:137], v[16:19], v[38:41]
	v_mfma_f32_16x16x32_bf16 v[74:77], v[130:133], v[16:19], v[74:77]
	v_mfma_f32_16x16x32_bf16 v[66:69], v[126:129], v[16:19], v[66:69]
	v_mfma_f32_16x16x32_bf16 v[70:73], v[122:125], v[16:19], v[70:73]
	ds_read_b128 v[122:125], v64 offset:50176
	ds_read_b128 v[126:129], v64 offset:52224
	ds_read_b128 v[130:133], v64 offset:54272
	ds_read_b128 v[134:137], v64 offset:56320
	v_mfma_f32_16x16x32_bf16 v[60:63], v[118:121], v[16:19], v[60:63]
	ds_read_b128 v[118:121], v64 offset:58368
	ds_read_b128 v[138:141], v64 offset:60416
	ds_read_b128 v[142:145], v64 offset:62464
	ds_read_b128 v[146:149], v64 offset:64512
	v_mfma_f32_16x16x32_bf16 v[78:81], v[114:117], v[16:19], v[78:81]
	s_add_u32 s100, s10, 0x11e10180
	s_addc_u32 s101, s11, 0
	s_mov_b32 m0, s17
	s_nop 0
	global_load_lds_dwordx4 v241, s[100:101]
	s_waitcnt lgkmcnt(0)
	v_mfma_f32_16x16x32_bf16 v[82:85], v[122:125], v[16:19], v[82:85]
	v_mfma_f32_16x16x32_bf16 v[86:89], v[126:129], v[16:19], v[86:89]
	v_mfma_f32_16x16x32_bf16 v[90:93], v[130:133], v[16:19], v[90:93]
	v_mfma_f32_16x16x32_bf16 v[94:97], v[134:137], v[16:19], v[94:97]
	v_mfma_f32_16x16x32_bf16 v[98:101], v[118:121], v[16:19], v[98:101]
	v_mfma_f32_16x16x32_bf16 v[102:105], v[138:141], v[16:19], v[102:105]
	v_mfma_f32_16x16x32_bf16 v[106:109], v[142:145], v[16:19], v[106:109]
	v_mfma_f32_16x16x32_bf16 v[110:113], v[146:149], v[16:19], v[110:113]
	s_add_u32 s100, s10, 0x11e18180
	s_addc_u32 s101, s11, 0
	s_mov_b32 m0, s18
	s_nop 0
	global_load_lds_dwordx4 v241, s[100:101]
	s_waitcnt vmcnt(0)
	s_waitcnt vmcnt(0)
	s_barrier
	v_mov_b32_e32 v37, v48
	ds_read_b128 v[114:117], v37
	ds_read_b128 v[118:121], v37 offset:2048
	s_waitcnt lgkmcnt(0)
	v_mfma_f32_16x16x32_bf16 v[42:45], v[114:117], v[12:15], v[42:45]
	ds_read_b128 v[114:117], v37 offset:4096
	v_mfma_f32_16x16x32_bf16 v[50:53], v[118:121], v[12:15], v[50:53]
	ds_read_b128 v[118:121], v37 offset:6144
	s_waitcnt lgkmcnt(0)
	v_mfma_f32_16x16x32_bf16 v[38:41], v[114:117], v[12:15], v[38:41]
	ds_read_b128 v[114:117], v37 offset:8192
	v_mfma_f32_16x16x32_bf16 v[74:77], v[118:121], v[12:15], v[74:77]
	ds_read_b128 v[118:121], v37 offset:10240
	s_waitcnt lgkmcnt(0)
	v_mfma_f32_16x16x32_bf16 v[66:69], v[114:117], v[12:15], v[66:69]
	ds_read_b128 v[114:117], v37 offset:12288
	ds_read_b128 v[122:125], v37 offset:14336
	v_mfma_f32_16x16x32_bf16 v[70:73], v[118:121], v[12:15], v[70:73]
	ds_read_b128 v[118:121], v37 offset:32768
	ds_read_b128 v[126:129], v37 offset:34816
	ds_read_b128 v[130:133], v37 offset:36864
	ds_read_b128 v[134:137], v37 offset:38912
	s_waitcnt lgkmcnt(0)
	v_mfma_f32_16x16x32_bf16 v[60:63], v[114:117], v[12:15], v[60:63]
	ds_read_b128 v[114:117], v37 offset:40960
	ds_read_b128 v[138:141], v37 offset:43008
	ds_read_b128 v[142:145], v37 offset:45056
	ds_read_b128 v[146:149], v37 offset:47104
	v_mfma_f32_16x16x32_bf16 v[78:81], v[122:125], v[12:15], v[78:81]
	s_add_u32 s100, s10, 0x11e20000
	s_addc_u32 s101, s11, 0
	s_mov_b32 m0, s22
	s_nop 0
	global_load_lds_dwordx4 v241, s[100:101]
	v_mfma_f32_16x16x32_bf16 v[82:85], v[118:121], v[12:15], v[82:85]
	v_mfma_f32_16x16x32_bf16 v[86:89], v[126:129], v[12:15], v[86:89]
	v_mfma_f32_16x16x32_bf16 v[90:93], v[130:133], v[12:15], v[90:93]
	v_mfma_f32_16x16x32_bf16 v[94:97], v[134:137], v[12:15], v[94:97]
	s_waitcnt lgkmcnt(0)
	v_mfma_f32_16x16x32_bf16 v[98:101], v[114:117], v[12:15], v[98:101]
	ds_read_b128 v[114:117], v37 offset:30720
	ds_read_b128 v[118:121], v37 offset:28672
	ds_read_b128 v[122:125], v37 offset:26624
	ds_read_b128 v[126:129], v37 offset:24576
	v_mfma_f32_16x16x32_bf16 v[102:105], v[138:141], v[12:15], v[102:105]
	v_mfma_f32_16x16x32_bf16 v[106:109], v[142:145], v[12:15], v[106:109]
	ds_read_b128 v[130:133], v37 offset:22528
	ds_read_b128 v[134:137], v37 offset:20480
	ds_read_b128 v[138:141], v37 offset:18432
	ds_read_b128 v[142:145], v37 offset:16384
	v_mfma_f32_16x16x32_bf16 v[110:113], v[146:149], v[12:15], v[110:113]
	s_add_u32 s100, s10, 0x11e28000
	s_addc_u32 s101, s11, 0
	s_mov_b32 m0, s21
	s_nop 0
	global_load_lds_dwordx4 v241, s[100:101]
	s_waitcnt lgkmcnt(0)
	v_mfma_f32_16x16x32_bf16 v[42:45], v[142:145], v[8:11], v[42:45]
	v_mfma_f32_16x16x32_bf16 v[50:53], v[138:141], v[8:11], v[50:53]
	v_mfma_f32_16x16x32_bf16 v[38:41], v[134:137], v[8:11], v[38:41]
	v_mfma_f32_16x16x32_bf16 v[74:77], v[130:133], v[8:11], v[74:77]
	v_mfma_f32_16x16x32_bf16 v[66:69], v[126:129], v[8:11], v[66:69]
	v_mfma_f32_16x16x32_bf16 v[70:73], v[122:125], v[8:11], v[70:73]
	ds_read_b128 v[122:125], v37 offset:49152
	ds_read_b128 v[126:129], v37 offset:51200
	ds_read_b128 v[130:133], v37 offset:53248
	ds_read_b128 v[134:137], v37 offset:55296
	v_mfma_f32_16x16x32_bf16 v[60:63], v[118:121], v[8:11], v[60:63]
	ds_read_b128 v[118:121], v37 offset:57344
	ds_read_b128 v[138:141], v37 offset:59392
	ds_read_b128 v[142:145], v37 offset:61440
	ds_read_b128 v[146:149], v37 offset:63488
	v_mfma_f32_16x16x32_bf16 v[78:81], v[114:117], v[8:11], v[78:81]
	s_add_u32 s100, s10, 0x11e20080
	s_addc_u32 s101, s11, 0
	s_mov_b32 m0, s20
	s_nop 0
	global_load_lds_dwordx4 v241, s[100:101]
	s_waitcnt lgkmcnt(0)
	v_mfma_f32_16x16x32_bf16 v[82:85], v[122:125], v[8:11], v[82:85]
	v_mfma_f32_16x16x32_bf16 v[86:89], v[126:129], v[8:11], v[86:89]
	v_mfma_f32_16x16x32_bf16 v[90:93], v[130:133], v[8:11], v[90:93]
	v_mfma_f32_16x16x32_bf16 v[94:97], v[134:137], v[8:11], v[94:97]
	v_mfma_f32_16x16x32_bf16 v[98:101], v[118:121], v[8:11], v[98:101]
	ds_read_b128 v[114:117], v37 offset:15360
	ds_read_b128 v[118:121], v37 offset:13312
	ds_read_b128 v[122:125], v37 offset:11264
	ds_read_b128 v[126:129], v37 offset:9216
	v_mfma_f32_16x16x32_bf16 v[102:105], v[138:141], v[8:11], v[102:105]
	v_mfma_f32_16x16x32_bf16 v[106:109], v[142:145], v[8:11], v[106:109]
	ds_read_b128 v[130:133], v37 offset:7168
	ds_read_b128 v[134:137], v37 offset:5120
	ds_read_b128 v[138:141], v37 offset:3072
	ds_read_b128 v[142:145], v37 offset:1024
	v_mfma_f32_16x16x32_bf16 v[110:113], v[146:149], v[8:11], v[110:113]
	s_add_u32 s100, s10, 0x11e28080
	s_addc_u32 s101, s11, 0
	s_mov_b32 m0, s23
	s_nop 0
	global_load_lds_dwordx4 v241, s[100:101]
	s_waitcnt lgkmcnt(0)
	v_mfma_f32_16x16x32_bf16 v[42:45], v[142:145], v[4:7], v[42:45]
	v_mfma_f32_16x16x32_bf16 v[50:53], v[138:141], v[4:7], v[50:53]
	v_mfma_f32_16x16x32_bf16 v[38:41], v[134:137], v[4:7], v[38:41]
	v_mfma_f32_16x16x32_bf16 v[74:77], v[130:133], v[4:7], v[74:77]
	v_mfma_f32_16x16x32_bf16 v[66:69], v[126:129], v[4:7], v[66:69]
	v_mfma_f32_16x16x32_bf16 v[70:73], v[122:125], v[4:7], v[70:73]
	ds_read_b128 v[122:125], v37 offset:33792
	ds_read_b128 v[126:129], v37 offset:35840
	ds_read_b128 v[130:133], v37 offset:37888
	ds_read_b128 v[134:137], v37 offset:39936
	v_mfma_f32_16x16x32_bf16 v[60:63], v[118:121], v[4:7], v[60:63]
	ds_read_b128 v[118:121], v37 offset:41984
	ds_read_b128 v[138:141], v37 offset:44032
	ds_read_b128 v[142:145], v37 offset:46080
	ds_read_b128 v[146:149], v37 offset:48128
	v_mfma_f32_16x16x32_bf16 v[78:81], v[114:117], v[4:7], v[78:81]
	s_add_u32 s100, s10, 0x11e30000
	s_addc_u32 s101, s11, 0
	s_mov_b32 m0, s24
	s_nop 0
	global_load_lds_dwordx4 v241, s[100:101]
	s_waitcnt lgkmcnt(0)
	v_mfma_f32_16x16x32_bf16 v[82:85], v[122:125], v[4:7], v[82:85]
	v_mfma_f32_16x16x32_bf16 v[86:89], v[126:129], v[4:7], v[86:89]
	v_mfma_f32_16x16x32_bf16 v[90:93], v[130:133], v[4:7], v[90:93]
	v_mfma_f32_16x16x32_bf16 v[94:97], v[134:137], v[4:7], v[94:97]
	v_mfma_f32_16x16x32_bf16 v[98:101], v[118:121], v[4:7], v[98:101]
	ds_read_b128 v[114:117], v37 offset:31744
	ds_read_b128 v[118:121], v37 offset:29696
	ds_read_b128 v[122:125], v37 offset:27648
	ds_read_b128 v[126:129], v37 offset:25600
	v_mfma_f32_16x16x32_bf16 v[102:105], v[138:141], v[4:7], v[102:105]
	v_mfma_f32_16x16x32_bf16 v[106:109], v[142:145], v[4:7], v[106:109]
	ds_read_b128 v[130:133], v37 offset:23552
	ds_read_b128 v[134:137], v37 offset:21504
	ds_read_b128 v[138:141], v37 offset:19456
	ds_read_b128 v[142:145], v37 offset:17408
	v_mfma_f32_16x16x32_bf16 v[110:113], v[146:149], v[4:7], v[110:113]
	s_add_u32 s100, s10, 0x11e38000
	s_addc_u32 s101, s11, 0
	s_mov_b32 m0, s25
	s_nop 0
	global_load_lds_dwordx4 v241, s[100:101]
	s_waitcnt lgkmcnt(0)
	v_mfma_f32_16x16x32_bf16 v[42:45], v[142:145], v[0:3], v[42:45]
	v_mfma_f32_16x16x32_bf16 v[50:53], v[138:141], v[0:3], v[50:53]
	v_mfma_f32_16x16x32_bf16 v[38:41], v[134:137], v[0:3], v[38:41]
	v_mfma_f32_16x16x32_bf16 v[74:77], v[130:133], v[0:3], v[74:77]
	v_mfma_f32_16x16x32_bf16 v[66:69], v[126:129], v[0:3], v[66:69]
	v_mfma_f32_16x16x32_bf16 v[70:73], v[122:125], v[0:3], v[70:73]
	ds_read_b128 v[122:125], v37 offset:50176
	ds_read_b128 v[126:129], v37 offset:52224
	ds_read_b128 v[130:133], v37 offset:54272
	ds_read_b128 v[134:137], v37 offset:56320
	v_mfma_f32_16x16x32_bf16 v[60:63], v[118:121], v[0:3], v[60:63]
	ds_read_b128 v[118:121], v37 offset:58368
	ds_read_b128 v[138:141], v37 offset:60416
	ds_read_b128 v[142:145], v37 offset:62464
	ds_read_b128 v[146:149], v37 offset:64512
	v_mfma_f32_16x16x32_bf16 v[78:81], v[114:117], v[0:3], v[78:81]
	s_add_u32 s100, s10, 0x11e30080
	s_addc_u32 s101, s11, 0
	s_mov_b32 m0, s26
	s_nop 0
	global_load_lds_dwordx4 v241, s[100:101]
	s_waitcnt lgkmcnt(0)
	v_mfma_f32_16x16x32_bf16 v[82:85], v[122:125], v[0:3], v[82:85]
	v_mfma_f32_16x16x32_bf16 v[86:89], v[126:129], v[0:3], v[86:89]
	v_mfma_f32_16x16x32_bf16 v[90:93], v[130:133], v[0:3], v[90:93]
	v_mfma_f32_16x16x32_bf16 v[94:97], v[134:137], v[0:3], v[94:97]
	v_mfma_f32_16x16x32_bf16 v[98:101], v[118:121], v[0:3], v[98:101]
	v_mfma_f32_16x16x32_bf16 v[102:105], v[138:141], v[0:3], v[102:105]
	v_mfma_f32_16x16x32_bf16 v[106:109], v[142:145], v[0:3], v[106:109]
	v_mfma_f32_16x16x32_bf16 v[110:113], v[146:149], v[0:3], v[110:113]
	s_add_u32 s100, s10, 0x11e38080
	s_addc_u32 s101, s11, 0
	s_mov_b32 m0, s27
	s_nop 0
	global_load_lds_dwordx4 v241, s[100:101]
	s_mov_b32 s0, 0x1000000
	v_add_co_u32_e32 v34, vcc, s0, v34
	v_mul_f32_e32 v37, v36, v42
	v_mul_f32_e32 v42, v36, v43
	v_mul_f32_e32 v43, v36, v45
	v_addc_co_u32_e32 v35, vcc, 0, v35, vcc
	v_cvt_pk_bf16_f32 v42, v37, v42
	v_mul_f32_e32 v37, v36, v44
	v_cvt_pk_bf16_f32 v43, v37, v43
	global_store_dwordx2 v[34:35], v[42:43], off
	v_mul_f32_e32 v34, v36, v50
	v_mul_f32_e32 v35, v36, v51
	v_cvt_pk_bf16_f32 v34, v34, v35
	v_mul_f32_e32 v35, v36, v52
	v_mul_f32_e32 v37, v36, v53
	v_cvt_pk_bf16_f32 v35, v35, v37
	global_store_dwordx2 v[32:33], v[34:35], off offset:32
	v_mul_f32_e32 v34, v36, v38
	v_mul_f32_e32 v35, v36, v39
	v_cvt_pk_bf16_f32 v34, v34, v35
	v_mul_f32_e32 v35, v36, v40
	v_mul_f32_e32 v37, v36, v41
	v_cvt_pk_bf16_f32 v35, v35, v37
	global_store_dwordx2 v[32:33], v[34:35], off offset:64
	v_mul_f32_e32 v34, v36, v74
	v_mul_f32_e32 v35, v36, v75
	v_cvt_pk_bf16_f32 v34, v34, v35
	v_mul_f32_e32 v35, v36, v76
	v_mul_f32_e32 v37, v36, v77
	v_cvt_pk_bf16_f32 v35, v35, v37
	global_store_dwordx2 v[32:33], v[34:35], off offset:96
	v_mul_f32_e32 v34, v36, v66
	v_mul_f32_e32 v35, v36, v67
	v_cvt_pk_bf16_f32 v34, v34, v35
	v_mul_f32_e32 v35, v36, v68
	v_mul_f32_e32 v37, v36, v69
	v_cvt_pk_bf16_f32 v35, v35, v37
	global_store_dwordx2 v[32:33], v[34:35], off offset:128
	v_mul_f32_e32 v34, v36, v70
	v_mul_f32_e32 v35, v36, v71
	v_cvt_pk_bf16_f32 v34, v34, v35
	v_mul_f32_e32 v35, v36, v72
	v_mul_f32_e32 v37, v36, v73
	v_cvt_pk_bf16_f32 v35, v35, v37
	global_store_dwordx2 v[32:33], v[34:35], off offset:160
	v_mul_f32_e32 v34, v36, v60
	v_mul_f32_e32 v35, v36, v61
	v_cvt_pk_bf16_f32 v34, v34, v35
	v_mul_f32_e32 v35, v36, v62
	v_mul_f32_e32 v37, v36, v63
	v_cvt_pk_bf16_f32 v35, v35, v37
	global_store_dwordx2 v[32:33], v[34:35], off offset:192
	v_mul_f32_e32 v34, v36, v78
	v_mul_f32_e32 v35, v36, v79
	v_cvt_pk_bf16_f32 v34, v34, v35
	v_mul_f32_e32 v35, v36, v80
	v_mul_f32_e32 v37, v36, v81
	v_cvt_pk_bf16_f32 v35, v35, v37
	global_store_dwordx2 v[32:33], v[34:35], off offset:224
	v_mul_f32_e32 v34, v36, v82
	v_mul_f32_e32 v35, v36, v83
	v_cvt_pk_bf16_f32 v34, v34, v35
	v_mul_f32_e32 v35, v36, v84
	v_mul_f32_e32 v37, v36, v85
	v_cvt_pk_bf16_f32 v35, v35, v37
	global_store_dwordx2 v[32:33], v[34:35], off offset:256
	v_mul_f32_e32 v34, v36, v86
	v_mul_f32_e32 v35, v36, v87
	v_cvt_pk_bf16_f32 v34, v34, v35
	v_mul_f32_e32 v35, v36, v88
	v_mul_f32_e32 v37, v36, v89
	v_cvt_pk_bf16_f32 v35, v35, v37
	global_store_dwordx2 v[32:33], v[34:35], off offset:288
	v_mul_f32_e32 v34, v36, v90
	v_mul_f32_e32 v35, v36, v91
	v_cvt_pk_bf16_f32 v34, v34, v35
	v_mul_f32_e32 v35, v36, v92
	v_mul_f32_e32 v37, v36, v93
	v_cvt_pk_bf16_f32 v35, v35, v37
	global_store_dwordx2 v[32:33], v[34:35], off offset:320
	v_mul_f32_e32 v34, v36, v94
	v_mul_f32_e32 v35, v36, v95
	v_cvt_pk_bf16_f32 v34, v34, v35
	v_mul_f32_e32 v35, v36, v96
	v_mul_f32_e32 v37, v36, v97
	v_cvt_pk_bf16_f32 v35, v35, v37
	global_store_dwordx2 v[32:33], v[34:35], off offset:352
	v_mul_f32_e32 v34, v36, v98
	v_mul_f32_e32 v35, v36, v99
	v_cvt_pk_bf16_f32 v34, v34, v35
	v_mul_f32_e32 v35, v36, v100
	v_mul_f32_e32 v37, v36, v101
	v_cvt_pk_bf16_f32 v35, v35, v37
	global_store_dwordx2 v[32:33], v[34:35], off offset:384
	v_mul_f32_e32 v34, v36, v102
	v_mul_f32_e32 v35, v36, v103
	v_cvt_pk_bf16_f32 v34, v34, v35
	v_mul_f32_e32 v35, v36, v104
	v_mul_f32_e32 v37, v36, v105
	v_cvt_pk_bf16_f32 v35, v35, v37
	global_store_dwordx2 v[32:33], v[34:35], off offset:416
	v_mul_f32_e32 v34, v36, v106
	v_mul_f32_e32 v35, v36, v107
	v_cvt_pk_bf16_f32 v34, v34, v35
	v_mul_f32_e32 v35, v36, v108
	v_mul_f32_e32 v37, v36, v109
	v_cvt_pk_bf16_f32 v35, v35, v37
	global_store_dwordx2 v[32:33], v[34:35], off offset:448
	v_mul_f32_e32 v34, v36, v110
	v_mul_f32_e32 v35, v36, v111
	v_cvt_pk_bf16_f32 v34, v34, v35
	v_mul_f32_e32 v35, v36, v112
	v_mul_f32_e32 v37, v36, v113
	v_cvt_pk_bf16_f32 v35, v35, v37
	global_store_dwordx2 v[32:33], v[34:35], off offset:480
	s_waitcnt vmcnt(0)
	s_waitcnt vmcnt(0)
	s_barrier
	ds_read_b128 v[38:41], v65
	ds_read_b128 v[42:45], v65 offset:2048
	ds_read_b128 v[50:53], v65 offset:4096
	ds_read_b128 v[54:57], v65 offset:6144
	ds_read_b128 v[58:61], v65 offset:8192
	ds_read_b128 v[66:69], v65 offset:10240
	ds_read_b128 v[70:73], v65 offset:12288
	ds_read_b128 v[74:77], v65 offset:14336
	ds_read_b128 v[78:81], v65 offset:32768
	ds_read_b128 v[82:85], v65 offset:34816
	ds_read_b128 v[86:89], v65 offset:36864
	ds_read_b128 v[90:93], v65 offset:38912
	ds_read_b128 v[94:97], v65 offset:40960
	ds_read_b128 v[98:101], v65 offset:43008
	ds_read_b128 v[102:105], v65 offset:45056
	ds_read_b128 v[106:109], v65 offset:47104
	s_waitcnt lgkmcnt(0)
	v_mfma_f32_16x16x32_bf16 v[38:41], v[38:41], v[28:31], 0
	v_mfma_f32_16x16x32_bf16 v[42:45], v[42:45], v[28:31], 0
	v_mfma_f32_16x16x32_bf16 v[50:53], v[50:53], v[28:31], 0
	v_mfma_f32_16x16x32_bf16 v[54:57], v[54:57], v[28:31], 0
	v_mfma_f32_16x16x32_bf16 v[58:61], v[58:61], v[28:31], 0
	v_mfma_f32_16x16x32_bf16 v[66:69], v[66:69], v[28:31], 0
	v_mfma_f32_16x16x32_bf16 v[70:73], v[70:73], v[28:31], 0
	v_mfma_f32_16x16x32_bf16 v[74:77], v[74:77], v[28:31], 0
	s_add_u32 s100, s10, 0x11e20100
	s_addc_u32 s101, s11, 0
	s_mov_b32 m0, s19
	s_nop 0
	global_load_lds_dwordx4 v241, s[100:101]
	ds_read_b128 v[110:113], v65 offset:30720
	ds_read_b128 v[114:117], v65 offset:28672
	ds_read_b128 v[118:121], v65 offset:26624
	ds_read_b128 v[122:125], v65 offset:24576
	ds_read_b128 v[126:129], v65 offset:22528
	ds_read_b128 v[130:133], v65 offset:20480
	ds_read_b128 v[134:137], v65 offset:18432
	ds_read_b128 v[138:141], v65 offset:16384
	v_mfma_f32_16x16x32_bf16 v[78:81], v[78:81], v[28:31], 0
	v_mfma_f32_16x16x32_bf16 v[82:85], v[82:85], v[28:31], 0
	v_mfma_f32_16x16x32_bf16 v[86:89], v[86:89], v[28:31], 0
	v_mfma_f32_16x16x32_bf16 v[90:93], v[90:93], v[28:31], 0
	v_mfma_f32_16x16x32_bf16 v[94:97], v[94:97], v[28:31], 0
	v_mfma_f32_16x16x32_bf16 v[98:101], v[98:101], v[28:31], 0
	v_mfma_f32_16x16x32_bf16 v[102:105], v[102:105], v[28:31], 0
	v_mfma_f32_16x16x32_bf16 v[28:31], v[106:109], v[28:31], 0
	s_add_u32 s100, s10, 0x11e28100
	s_addc_u32 s101, s11, 0
	s_mov_b32 m0, s13
	s_nop 0
	global_load_lds_dwordx4 v241, s[100:101]
	s_waitcnt lgkmcnt(0)
	v_mfma_f32_16x16x32_bf16 v[38:41], v[138:141], v[24:27], v[38:41]
	v_mfma_f32_16x16x32_bf16 v[42:45], v[134:137], v[24:27], v[42:45]
	v_mfma_f32_16x16x32_bf16 v[50:53], v[130:133], v[24:27], v[50:53]
	v_mfma_f32_16x16x32_bf16 v[54:57], v[126:129], v[24:27], v[54:57]
	v_mfma_f32_16x16x32_bf16 v[58:61], v[122:125], v[24:27], v[58:61]
	v_mfma_f32_16x16x32_bf16 v[66:69], v[118:121], v[24:27], v[66:69]
	ds_read_b128 v[106:109], v65 offset:49152
	ds_read_b128 v[118:121], v65 offset:51200
	ds_read_b128 v[122:125], v65 offset:53248
	ds_read_b128 v[126:129], v65 offset:55296
	v_mfma_f32_16x16x32_bf16 v[70:73], v[114:117], v[24:27], v[70:73]
	ds_read_b128 v[114:117], v65 offset:57344
	ds_read_b128 v[130:133], v65 offset:59392
	ds_read_b128 v[134:137], v65 offset:61440
	ds_read_b128 v[138:141], v65 offset:63488
	v_mfma_f32_16x16x32_bf16 v[74:77], v[110:113], v[24:27], v[74:77]
	s_add_u32 s100, s10, 0x11e20180
	s_addc_u32 s101, s11, 0
	s_mov_b32 m0, s12
	s_nop 0
	global_load_lds_dwordx4 v241, s[100:101]
	s_waitcnt lgkmcnt(0)
	v_mfma_f32_16x16x32_bf16 v[78:81], v[106:109], v[24:27], v[78:81]
	v_mfma_f32_16x16x32_bf16 v[82:85], v[118:121], v[24:27], v[82:85]
	v_mfma_f32_16x16x32_bf16 v[86:89], v[122:125], v[24:27], v[86:89]
	v_mfma_f32_16x16x32_bf16 v[90:93], v[126:129], v[24:27], v[90:93]
	v_mfma_f32_16x16x32_bf16 v[94:97], v[114:117], v[24:27], v[94:97]
	ds_read_b128 v[106:109], v65 offset:15360
	ds_read_b128 v[110:113], v65 offset:13312
	ds_read_b128 v[114:117], v65 offset:11264
	ds_read_b128 v[118:121], v65 offset:9216
	v_mfma_f32_16x16x32_bf16 v[98:101], v[130:133], v[24:27], v[98:101]
	v_mfma_f32_16x16x32_bf16 v[102:105], v[134:137], v[24:27], v[102:105]
	ds_read_b128 v[122:125], v65 offset:7168
	ds_read_b128 v[126:129], v65 offset:5120
	ds_read_b128 v[130:133], v65 offset:3072
	ds_read_b128 v[134:137], v65 offset:1024
	v_mfma_f32_16x16x32_bf16 v[24:27], v[138:141], v[24:27], v[28:31]
	s_add_u32 s100, s10, 0x11e28180
	s_addc_u32 s101, s11, 0
	s_mov_b32 m0, s14
	s_nop 0
	global_load_lds_dwordx4 v241, s[100:101]
	s_waitcnt lgkmcnt(0)
	v_mfma_f32_16x16x32_bf16 v[28:31], v[134:137], v[20:23], v[38:41]
	v_mfma_f32_16x16x32_bf16 v[38:41], v[130:133], v[20:23], v[42:45]
	v_mfma_f32_16x16x32_bf16 v[42:45], v[126:129], v[20:23], v[50:53]
	v_mfma_f32_16x16x32_bf16 v[50:53], v[122:125], v[20:23], v[54:57]
	v_mfma_f32_16x16x32_bf16 v[54:57], v[118:121], v[20:23], v[58:61]
	v_mfma_f32_16x16x32_bf16 v[58:61], v[114:117], v[20:23], v[66:69]
	s_nop 2
	ds_read_b128 v[66:69], v65 offset:33792
	ds_read_b128 v[114:117], v65 offset:35840
	ds_read_b128 v[118:121], v65 offset:37888
	ds_read_b128 v[122:125], v65 offset:39936
	v_mfma_f32_16x16x32_bf16 v[70:73], v[110:113], v[20:23], v[70:73]
	ds_read_b128 v[110:113], v65 offset:41984
	ds_read_b128 v[126:129], v65 offset:44032
	ds_read_b128 v[130:133], v65 offset:46080
	ds_read_b128 v[134:137], v65 offset:48128
	v_mfma_f32_16x16x32_bf16 v[74:77], v[106:109], v[20:23], v[74:77]
	s_add_u32 s100, s10, 0x11e30100
	s_addc_u32 s101, s11, 0
	s_mov_b32 m0, s15
	s_nop 0
	global_load_lds_dwordx4 v241, s[100:101]
	s_waitcnt lgkmcnt(0)
	v_mfma_f32_16x16x32_bf16 v[66:69], v[66:69], v[20:23], v[78:81]
	v_mfma_f32_16x16x32_bf16 v[78:81], v[114:117], v[20:23], v[82:85]
	v_mfma_f32_16x16x32_bf16 v[82:85], v[118:121], v[20:23], v[86:89]
	v_mfma_f32_16x16x32_bf16 v[86:89], v[122:125], v[20:23], v[90:93]
	v_mfma_f32_16x16x32_bf16 v[90:93], v[110:113], v[20:23], v[94:97]
	v_mfma_f32_16x16x32_bf16 v[94:97], v[126:129], v[20:23], v[98:101]
	s_nop 2
	ds_read_b128 v[98:101], v65 offset:31744
	ds_read_b128 v[106:109], v65 offset:29696
	ds_read_b128 v[110:113], v65 offset:27648
	ds_read_b128 v[114:117], v65 offset:25600
	v_mfma_f32_16x16x32_bf16 v[102:105], v[130:133], v[20:23], v[102:105]
	ds_read_b128 v[118:121], v65 offset:23552
	ds_read_b128 v[122:125], v65 offset:21504
	ds_read_b128 v[126:129], v65 offset:19456
	ds_read_b128 v[130:133], v65 offset:17408
	v_mfma_f32_16x16x32_bf16 v[20:23], v[134:137], v[20:23], v[24:27]
	s_add_u32 s100, s10, 0x11e38100
	s_addc_u32 s101, s11, 0
	s_mov_b32 m0, s16
	s_nop 0
	global_load_lds_dwordx4 v241, s[100:101]
	s_waitcnt lgkmcnt(0)
	v_mfma_f32_16x16x32_bf16 v[24:27], v[130:133], v[16:19], v[28:31]
	v_mfma_f32_16x16x32_bf16 v[28:31], v[126:129], v[16:19], v[38:41]
	v_mfma_f32_16x16x32_bf16 v[38:41], v[122:125], v[16:19], v[42:45]
	v_mfma_f32_16x16x32_bf16 v[42:45], v[118:121], v[16:19], v[50:53]
	v_mfma_f32_16x16x32_bf16 v[50:53], v[114:117], v[16:19], v[54:57]
	v_mfma_f32_16x16x32_bf16 v[54:57], v[110:113], v[16:19], v[58:61]
	s_nop 2
	ds_read_b128 v[58:61], v65 offset:50176
	ds_read_b128 v[110:113], v65 offset:52224
	ds_read_b128 v[114:117], v65 offset:54272
	ds_read_b128 v[118:121], v65 offset:56320
	v_mfma_f32_16x16x32_bf16 v[70:73], v[106:109], v[16:19], v[70:73]
	ds_read_b128 v[106:109], v65 offset:58368
	ds_read_b128 v[122:125], v65 offset:60416
	ds_read_b128 v[126:129], v65 offset:62464
	ds_read_b128 v[62:65], v65 offset:64512
	v_mfma_f32_16x16x32_bf16 v[74:77], v[98:101], v[16:19], v[74:77]
	s_add_u32 s100, s10, 0x11e30180
	s_addc_u32 s101, s11, 0
	s_mov_b32 m0, s17
	s_nop 0
	global_load_lds_dwordx4 v241, s[100:101]
	s_waitcnt lgkmcnt(0)
	v_mfma_f32_16x16x32_bf16 v[58:61], v[58:61], v[16:19], v[66:69]
	v_mfma_f32_16x16x32_bf16 v[66:69], v[110:113], v[16:19], v[78:81]
	v_mfma_f32_16x16x32_bf16 v[78:81], v[114:117], v[16:19], v[82:85]
	v_mfma_f32_16x16x32_bf16 v[82:85], v[118:121], v[16:19], v[86:89]
	v_mfma_f32_16x16x32_bf16 v[86:89], v[106:109], v[16:19], v[90:93]
	v_mfma_f32_16x16x32_bf16 v[90:93], v[122:125], v[16:19], v[94:97]
	v_mfma_f32_16x16x32_bf16 v[94:97], v[126:129], v[16:19], v[102:105]
	v_mfma_f32_16x16x32_bf16 v[16:19], v[62:65], v[16:19], v[20:23]
	s_add_u32 s100, s10, 0x11e38180
	s_addc_u32 s101, s11, 0
	s_mov_b32 m0, s18
	s_nop 0
	global_load_lds_dwordx4 v241, s[100:101]
	s_waitcnt vmcnt(0)
	s_waitcnt vmcnt(0)
	s_barrier
	s_nop 0
	ds_read_b128 v[20:23], v48
	ds_read_b128 v[62:65], v48 offset:2048
	s_waitcnt lgkmcnt(1)
	v_mfma_f32_16x16x32_bf16 v[20:23], v[20:23], v[12:15], v[24:27]
	s_nop 2
	ds_read_b128 v[24:27], v48 offset:4096
	s_waitcnt lgkmcnt(1)
	v_mfma_f32_16x16x32_bf16 v[28:31], v[62:65], v[12:15], v[28:31]
	ds_read_b128 v[62:65], v48 offset:6144
	s_waitcnt lgkmcnt(1)
	v_mfma_f32_16x16x32_bf16 v[24:27], v[24:27], v[12:15], v[38:41]
	s_nop 2
	ds_read_b128 v[38:41], v48 offset:8192
	s_waitcnt lgkmcnt(1)
	v_mfma_f32_16x16x32_bf16 v[42:45], v[62:65], v[12:15], v[42:45]
	ds_read_b128 v[62:65], v48 offset:10240
	s_waitcnt lgkmcnt(1)
	v_mfma_f32_16x16x32_bf16 v[38:41], v[38:41], v[12:15], v[50:53]
	s_nop 2
	ds_read_b128 v[50:53], v48 offset:12288
	ds_read_b128 v[98:101], v48 offset:14336
	s_waitcnt lgkmcnt(2)
	v_mfma_f32_16x16x32_bf16 v[54:57], v[62:65], v[12:15], v[54:57]
	ds_read_b128 v[62:65], v48 offset:32768
	ds_read_b128 v[102:105], v48 offset:34816
	ds_read_b128 v[106:109], v48 offset:36864
	ds_read_b128 v[110:113], v48 offset:38912
	s_waitcnt lgkmcnt(5)
	v_mfma_f32_16x16x32_bf16 v[50:53], v[50:53], v[12:15], v[70:73]
	s_nop 2
	ds_read_b128 v[70:73], v48 offset:40960
	ds_read_b128 v[114:117], v48 offset:43008
	ds_read_b128 v[118:121], v48 offset:45056
	ds_read_b128 v[122:125], v48 offset:47104
	s_waitcnt lgkmcnt(8)
	v_mfma_f32_16x16x32_bf16 v[74:77], v[98:101], v[12:15], v[74:77]
	s_waitcnt lgkmcnt(7)
	v_mfma_f32_16x16x32_bf16 v[58:61], v[62:65], v[12:15], v[58:61]
	s_waitcnt lgkmcnt(6)
	v_mfma_f32_16x16x32_bf16 v[62:65], v[102:105], v[12:15], v[66:69]
	s_waitcnt lgkmcnt(5)
	v_mfma_f32_16x16x32_bf16 v[66:69], v[106:109], v[12:15], v[78:81]
	s_waitcnt lgkmcnt(4)
	v_mfma_f32_16x16x32_bf16 v[78:81], v[110:113], v[12:15], v[82:85]
	s_waitcnt lgkmcnt(3)
	v_mfma_f32_16x16x32_bf16 v[70:73], v[70:73], v[12:15], v[86:89]
	s_waitcnt lgkmcnt(2)
	v_mfma_f32_16x16x32_bf16 v[82:85], v[114:117], v[12:15], v[90:93]
	s_nop 0
	ds_read_b128 v[86:89], v48 offset:30720
	s_nop 0
	ds_read_b128 v[90:93], v48 offset:28672
	ds_read_b128 v[98:101], v48 offset:26624
	ds_read_b128 v[102:105], v48 offset:24576
	s_waitcnt lgkmcnt(5)
	v_mfma_f32_16x16x32_bf16 v[94:97], v[118:121], v[12:15], v[94:97]
	ds_read_b128 v[106:109], v48 offset:22528
	ds_read_b128 v[110:113], v48 offset:20480
	ds_read_b128 v[114:117], v48 offset:18432
	ds_read_b128 v[118:121], v48 offset:16384
	s_waitcnt lgkmcnt(8)
	v_mfma_f32_16x16x32_bf16 v[12:15], v[122:125], v[12:15], v[16:19]
	s_waitcnt lgkmcnt(0)
	v_mfma_f32_16x16x32_bf16 v[16:19], v[118:121], v[8:11], v[20:23]
	v_mfma_f32_16x16x32_bf16 v[20:23], v[114:117], v[8:11], v[28:31]
	v_mfma_f32_16x16x32_bf16 v[24:27], v[110:113], v[8:11], v[24:27]
	v_mfma_f32_16x16x32_bf16 v[28:31], v[106:109], v[8:11], v[42:45]
	v_mfma_f32_16x16x32_bf16 v[38:41], v[102:105], v[8:11], v[38:41]
	v_mfma_f32_16x16x32_bf16 v[42:45], v[98:101], v[8:11], v[54:57]
	s_nop 2
	ds_read_b128 v[54:57], v48 offset:49152
	ds_read_b128 v[98:101], v48 offset:51200
	ds_read_b128 v[102:105], v48 offset:53248
	ds_read_b128 v[106:109], v48 offset:55296
	v_mfma_f32_16x16x32_bf16 v[50:53], v[90:93], v[8:11], v[50:53]
	ds_read_b128 v[90:93], v48 offset:57344
	ds_read_b128 v[110:113], v48 offset:59392
	ds_read_b128 v[114:117], v48 offset:61440
	ds_read_b128 v[118:121], v48 offset:63488
	v_mfma_f32_16x16x32_bf16 v[74:77], v[86:89], v[8:11], v[74:77]
	s_waitcnt lgkmcnt(7)
	v_mfma_f32_16x16x32_bf16 v[54:57], v[54:57], v[8:11], v[58:61]
	s_waitcnt lgkmcnt(6)
	v_mfma_f32_16x16x32_bf16 v[58:61], v[98:101], v[8:11], v[62:65]
	s_waitcnt lgkmcnt(5)
	v_mfma_f32_16x16x32_bf16 v[62:65], v[102:105], v[8:11], v[66:69]
	s_waitcnt lgkmcnt(4)
	v_mfma_f32_16x16x32_bf16 v[66:69], v[106:109], v[8:11], v[78:81]
	s_waitcnt lgkmcnt(3)
	v_mfma_f32_16x16x32_bf16 v[70:73], v[90:93], v[8:11], v[70:73]
	s_waitcnt lgkmcnt(2)
	v_mfma_f32_16x16x32_bf16 v[78:81], v[110:113], v[8:11], v[82:85]
	s_nop 2
	ds_read_b128 v[82:85], v48 offset:15360
	ds_read_b128 v[86:89], v48 offset:13312
	ds_read_b128 v[90:93], v48 offset:11264
	ds_read_b128 v[98:101], v48 offset:9216
	s_waitcnt lgkmcnt(5)
	v_mfma_f32_16x16x32_bf16 v[94:97], v[114:117], v[8:11], v[94:97]
	ds_read_b128 v[102:105], v48 offset:7168
	ds_read_b128 v[106:109], v48 offset:5120
	ds_read_b128 v[110:113], v48 offset:3072
	ds_read_b128 v[114:117], v48 offset:1024
	s_waitcnt lgkmcnt(8)
	v_mfma_f32_16x16x32_bf16 v[8:11], v[118:121], v[8:11], v[12:15]
	s_waitcnt lgkmcnt(0)
	v_mfma_f32_16x16x32_bf16 v[12:15], v[114:117], v[4:7], v[16:19]
	v_mfma_f32_16x16x32_bf16 v[16:19], v[110:113], v[4:7], v[20:23]
	v_mfma_f32_16x16x32_bf16 v[20:23], v[106:109], v[4:7], v[24:27]
	v_mfma_f32_16x16x32_bf16 v[24:27], v[102:105], v[4:7], v[28:31]
	v_mfma_f32_16x16x32_bf16 v[28:31], v[98:101], v[4:7], v[38:41]
	v_mfma_f32_16x16x32_bf16 v[38:41], v[90:93], v[4:7], v[42:45]
	s_nop 2
	ds_read_b128 v[42:45], v48 offset:33792
	ds_read_b128 v[90:93], v48 offset:35840
	ds_read_b128 v[98:101], v48 offset:37888
	ds_read_b128 v[102:105], v48 offset:39936
	v_mfma_f32_16x16x32_bf16 v[50:53], v[86:89], v[4:7], v[50:53]
	ds_read_b128 v[86:89], v48 offset:41984
	ds_read_b128 v[106:109], v48 offset:44032
	ds_read_b128 v[110:113], v48 offset:46080
	ds_read_b128 v[114:117], v48 offset:48128
	v_mfma_f32_16x16x32_bf16 v[74:77], v[82:85], v[4:7], v[74:77]
	s_waitcnt lgkmcnt(7)
	v_mfma_f32_16x16x32_bf16 v[42:45], v[42:45], v[4:7], v[54:57]
	s_waitcnt lgkmcnt(6)
	v_mfma_f32_16x16x32_bf16 v[54:57], v[90:93], v[4:7], v[58:61]
	s_waitcnt lgkmcnt(5)
	v_mfma_f32_16x16x32_bf16 v[58:61], v[98:101], v[4:7], v[62:65]
	s_waitcnt lgkmcnt(4)
	v_mfma_f32_16x16x32_bf16 v[62:65], v[102:105], v[4:7], v[66:69]
	s_waitcnt lgkmcnt(3)
	v_mfma_f32_16x16x32_bf16 v[66:69], v[86:89], v[4:7], v[70:73]
	s_waitcnt lgkmcnt(2)
	v_mfma_f32_16x16x32_bf16 v[70:73], v[106:109], v[4:7], v[78:81]
	s_nop 2
	ds_read_b128 v[78:81], v48 offset:31744
	ds_read_b128 v[82:85], v48 offset:29696
	ds_read_b128 v[86:89], v48 offset:27648
	ds_read_b128 v[90:93], v48 offset:25600
	s_waitcnt lgkmcnt(5)
	v_mfma_f32_16x16x32_bf16 v[94:97], v[110:113], v[4:7], v[94:97]
	ds_read_b128 v[98:101], v48 offset:23552
	ds_read_b128 v[102:105], v48 offset:21504
	ds_read_b128 v[106:109], v48 offset:19456
	ds_read_b128 v[110:113], v48 offset:17408
	s_waitcnt lgkmcnt(8)
	v_mfma_f32_16x16x32_bf16 v[4:7], v[114:117], v[4:7], v[8:11]
	s_waitcnt lgkmcnt(0)
	v_mfma_f32_16x16x32_bf16 v[8:11], v[110:113], v[0:3], v[12:15]
	v_mfma_f32_16x16x32_bf16 v[12:15], v[106:109], v[0:3], v[16:19]
	v_mfma_f32_16x16x32_bf16 v[16:19], v[102:105], v[0:3], v[20:23]
	v_mfma_f32_16x16x32_bf16 v[20:23], v[98:101], v[0:3], v[24:27]
	v_mfma_f32_16x16x32_bf16 v[24:27], v[90:93], v[0:3], v[28:31]
	v_mfma_f32_16x16x32_bf16 v[28:31], v[86:89], v[0:3], v[38:41]
	s_nop 2
	ds_read_b128 v[38:41], v48 offset:50176
	ds_read_b128 v[86:89], v48 offset:52224
	ds_read_b128 v[90:93], v48 offset:54272
	ds_read_b128 v[98:101], v48 offset:56320
	v_mfma_f32_16x16x32_bf16 v[50:53], v[82:85], v[0:3], v[50:53]
	ds_read_b128 v[82:85], v48 offset:58368
	ds_read_b128 v[102:105], v48 offset:60416
	ds_read_b128 v[106:109], v48 offset:62464
	ds_read_b128 v[46:49], v48 offset:64512
	v_mfma_f32_16x16x32_bf16 v[74:77], v[78:81], v[0:3], v[74:77]
	s_waitcnt lgkmcnt(7)
	v_mfma_f32_16x16x32_bf16 v[38:41], v[38:41], v[0:3], v[42:45]
	s_waitcnt lgkmcnt(6)
	v_mfma_f32_16x16x32_bf16 v[42:45], v[86:89], v[0:3], v[54:57]
	s_waitcnt lgkmcnt(5)
	v_mfma_f32_16x16x32_bf16 v[54:57], v[90:93], v[0:3], v[58:61]
	s_waitcnt lgkmcnt(4)
	v_mfma_f32_16x16x32_bf16 v[58:61], v[98:101], v[0:3], v[62:65]
	s_waitcnt lgkmcnt(3)
	v_mfma_f32_16x16x32_bf16 v[62:65], v[82:85], v[0:3], v[66:69]
	s_waitcnt lgkmcnt(2)
	v_mfma_f32_16x16x32_bf16 v[66:69], v[102:105], v[0:3], v[70:73]
	s_waitcnt lgkmcnt(1)
	v_mfma_f32_16x16x32_bf16 v[70:73], v[106:109], v[0:3], v[94:97]
	s_waitcnt lgkmcnt(0)
	v_mfma_f32_16x16x32_bf16 v[0:3], v[46:49], v[0:3], v[4:7]
	s_nop 2
	v_mul_f32_e32 v4, v36, v8
	v_mul_f32_e32 v5, v36, v9
	v_cvt_pk_bf16_f32 v4, v4, v5
	v_mul_f32_e32 v5, v36, v10
	v_mul_f32_e32 v6, v36, v11
	v_cvt_pk_bf16_f32 v5, v5, v6
	global_store_dwordx2 v[32:33], v[4:5], off offset:512
	v_mul_f32_e32 v4, v36, v12
	v_mul_f32_e32 v5, v36, v13
	v_cvt_pk_bf16_f32 v4, v4, v5
	v_mul_f32_e32 v5, v36, v14
	v_mul_f32_e32 v6, v36, v15
	v_cvt_pk_bf16_f32 v5, v5, v6
	global_store_dwordx2 v[32:33], v[4:5], off offset:544
	v_mul_f32_e32 v4, v36, v16
	v_mul_f32_e32 v5, v36, v17
	v_cvt_pk_bf16_f32 v4, v4, v5
	v_mul_f32_e32 v5, v36, v18
	v_mul_f32_e32 v6, v36, v19
	v_cvt_pk_bf16_f32 v5, v5, v6
	global_store_dwordx2 v[32:33], v[4:5], off offset:576
	v_mul_f32_e32 v4, v36, v20
	v_mul_f32_e32 v5, v36, v21
	v_cvt_pk_bf16_f32 v4, v4, v5
	v_mul_f32_e32 v5, v36, v22
	v_mul_f32_e32 v6, v36, v23
	v_cvt_pk_bf16_f32 v5, v5, v6
	global_store_dwordx2 v[32:33], v[4:5], off offset:608
	v_mul_f32_e32 v4, v36, v24
	v_mul_f32_e32 v5, v36, v25
	v_cvt_pk_bf16_f32 v4, v4, v5
	v_mul_f32_e32 v5, v36, v26
	v_mul_f32_e32 v6, v36, v27
	v_cvt_pk_bf16_f32 v5, v5, v6
	global_store_dwordx2 v[32:33], v[4:5], off offset:640
	v_mul_f32_e32 v4, v36, v28
	v_mul_f32_e32 v5, v36, v29
	v_cvt_pk_bf16_f32 v4, v4, v5
	v_mul_f32_e32 v5, v36, v30
	v_mul_f32_e32 v6, v36, v31
	v_cvt_pk_bf16_f32 v5, v5, v6
	global_store_dwordx2 v[32:33], v[4:5], off offset:672
	v_mul_f32_e32 v4, v36, v50
	v_mul_f32_e32 v5, v36, v51
	v_cvt_pk_bf16_f32 v4, v4, v5
	v_mul_f32_e32 v5, v36, v52
	v_mul_f32_e32 v6, v36, v53
	v_cvt_pk_bf16_f32 v5, v5, v6
	global_store_dwordx2 v[32:33], v[4:5], off offset:704
	v_mul_f32_e32 v4, v36, v74
	v_mul_f32_e32 v5, v36, v75
	v_cvt_pk_bf16_f32 v4, v4, v5
	v_mul_f32_e32 v5, v36, v76
	v_mul_f32_e32 v6, v36, v77
	v_cvt_pk_bf16_f32 v5, v5, v6
	global_store_dwordx2 v[32:33], v[4:5], off offset:736
	v_mul_f32_e32 v4, v36, v38
	v_mul_f32_e32 v5, v36, v39
	v_cvt_pk_bf16_f32 v4, v4, v5
	v_mul_f32_e32 v5, v36, v40
	v_mul_f32_e32 v6, v36, v41
	v_cvt_pk_bf16_f32 v5, v5, v6
	global_store_dwordx2 v[32:33], v[4:5], off offset:768
	v_mul_f32_e32 v4, v36, v42
	v_mul_f32_e32 v5, v36, v43
	v_cvt_pk_bf16_f32 v4, v4, v5
	v_mul_f32_e32 v5, v36, v44
	v_mul_f32_e32 v6, v36, v45
	v_cvt_pk_bf16_f32 v5, v5, v6
	global_store_dwordx2 v[32:33], v[4:5], off offset:800
	v_mul_f32_e32 v4, v36, v54
	v_mul_f32_e32 v5, v36, v55
	v_cvt_pk_bf16_f32 v4, v4, v5
	v_mul_f32_e32 v5, v36, v56
	v_mul_f32_e32 v6, v36, v57
	v_cvt_pk_bf16_f32 v5, v5, v6
	global_store_dwordx2 v[32:33], v[4:5], off offset:832
	v_mul_f32_e32 v4, v36, v58
	v_mul_f32_e32 v5, v36, v59
	v_cvt_pk_bf16_f32 v4, v4, v5
	v_mul_f32_e32 v5, v36, v60
	v_mul_f32_e32 v6, v36, v61
	v_cvt_pk_bf16_f32 v5, v5, v6
	global_store_dwordx2 v[32:33], v[4:5], off offset:864
	v_mul_f32_e32 v4, v36, v62
	v_mul_f32_e32 v5, v36, v63
	v_cvt_pk_bf16_f32 v4, v4, v5
	v_mul_f32_e32 v5, v36, v64
	v_mul_f32_e32 v6, v36, v65
	v_cvt_pk_bf16_f32 v5, v5, v6
	global_store_dwordx2 v[32:33], v[4:5], off offset:896
	v_mul_f32_e32 v4, v36, v66
	v_mul_f32_e32 v5, v36, v67
	v_cvt_pk_bf16_f32 v4, v4, v5
	v_mul_f32_e32 v5, v36, v68
	v_mul_f32_e32 v6, v36, v69
	v_cvt_pk_bf16_f32 v5, v5, v6
	global_store_dwordx2 v[32:33], v[4:5], off offset:928
	v_mul_f32_e32 v4, v36, v70
	v_mul_f32_e32 v5, v36, v71
	v_cvt_pk_bf16_f32 v4, v4, v5
	v_mul_f32_e32 v5, v36, v72
	v_mul_f32_e32 v0, v36, v0
	v_mul_f32_e32 v1, v36, v1
	v_mul_f32_e32 v6, v36, v73
	v_cvt_pk_bf16_f32 v5, v5, v6
	global_store_dwordx2 v[32:33], v[4:5], off offset:960
	v_cvt_pk_bf16_f32 v0, v0, v1
	v_mul_f32_e32 v1, v36, v2
	v_mul_f32_e32 v2, v36, v3
	v_cvt_pk_bf16_f32 v1, v1, v2
	global_store_dwordx2 v[32:33], v[0:1], off offset:992
	s_waitcnt vmcnt(0)
	s_barrier
